# v072 + GEMM loops: back edge rotated (loop-carried scalar updates, exit test and next iteration's head address math moved behind the last MFMA group, ahead of the closing barrier)
# baseline (speedup 1.0000x reference)
; #define PG8_STAGE(bufoff, gbase, voff) do { _Pragma("unroll") for (int _i = 0; _i < 2; ++_i) \
;         __builtin_amdgcn_global_load_lds((const gunsigned*)((const gchar*)(gbase) + (voff)[_i]), (LAS unsigned*)(lds + (bufoff) + ldsw + _i * 8192), 16, 0, 0); } while (0)
; #define PG8_LDA(dst, b, h) do { _Pragma("unroll") for (int m = 0; m < 4; ++m) _Pragma("unroll") for (int k = 0; k < 2; ++k) dst[m][k] = *(const LAS bf16x8*)(lds + PG8_SA(b, h) + aoff + m * 2048 + k * 1024); } while (0)
; #define PG8_LDB(dst, b, h) do { _Pragma("unroll") for (int n = 0; n < 2; ++n) _Pragma("unroll") for (int k = 0; k < 2; ++k) dst[n][k] = *(const LAS bf16x8*)(lds + PG8_SB(b, h) + boff + n * 2048 + k * 1024); } while (0)
; #define PG8_WAIT_V(n) asm volatile("s_waitcnt vmcnt(" #n ")" ::: "memory")
; template <class Epi, class Sched>
; __device__ __forceinline__ void gemm_phase(LAS unsigned char* lds, const int tid, const Gemm g, const Sched& S, const Epi& E) {
;     ...
;         for (int t = 0; t < nt; t += 2) {
;             const bool last = (t == nt - 2);
;             const gchar* a1 = cA + (size_t)(t + 1) * kstep;
;             const gchar* a2 = last ? nA : cA + (size_t)(t + 2) * kstep; const gchar* b2 = last ? nB : cB + (size_t)(t + 2) * kstep;
;             const gchar* a3 = a2 + kstep; const gchar* b3 = b2 + kstep;
;             PG8_LDB(B0, 0, 0); PG8_LDB(B1, 0, 1); PG8_SCHED; PG8_LDA(At, 0, 0); PG8_STAGE(PG8_SA(1, 1), a1 + hstep, voffA);
;             PG8_WAIT_V(8); PG8_WAIT_L(0); PG8_BAR; PG8_MMA(0, 0, At, B0); PG8_MMA(0, 1, At, B1); PG8_BAR; PG8_SCHED;
;             PG8_LDA(At, 0, 1); PG8_STAGE(PG8_SB(0, 0), b2, voffB); PG8_STAGE(PG8_SB(0, 1), b2 + hstep, voffB); PG8_STAGE(PG8_SA(0, 0), a2, voffA);
;             PG8_WAIT_V(8); PG8_WAIT_L(0); PG8_BAR; PG8_MMA(1, 0, At, B0); PG8_MMA(1, 1, At, B1); PG8_BAR; PG8_SCHED;
;             PG8_LDB(B0, 1, 0); PG8_LDB(B1, 1, 1); PG8_SCHED; PG8_LDA(At, 1, 0); PG8_STAGE(PG8_SA(0, 1), a2 + hstep, voffA);
;             PG8_WAIT_V(8); PG8_WAIT_L(0); PG8_BAR; PG8_MMA(0, 0, At, B0); PG8_MMA(0, 1, At, B1); PG8_BAR; PG8_SCHED;
;             PG8_LDA(At, 1, 1); PG8_STAGE(PG8_SB(1, 0), b3, voffB); PG8_STAGE(PG8_SB(1, 1), b3 + hstep, voffB); PG8_STAGE(PG8_SA(1, 0), a3, voffA);
;             PG8_WAIT_V(8); PG8_WAIT_L(0); PG8_BAR; PG8_MMA(1, 0, At, B0); PG8_MMA(1, 1, At, B1); PG8_BAR; PG8_SCHED;
;         }
.Lrot_319:
	ds_read_b128 v[130:133], v142
	ds_read_b128 v[134:137], v142 offset:1024
	ds_read_b128 v[138:141], v142 offset:2048
	ds_read_b128 v[142:145], v142 offset:3072
	ds_read_b128 v[146:149], v168
	ds_read_b128 v[150:153], v168 offset:1024
	ds_read_b128 v[164:167], v168 offset:2048
	ds_read_b128 v[168:171], v168 offset:3072
	s_add_i32 m0, s46, 0xc000
	ds_read_b128 v[192:195], v190
	ds_read_b128 v[204:207], v190 offset:1024
	ds_read_b128 v[208:211], v190 offset:2048
	ds_read_b128 v[212:215], v190 offset:3072
	ds_read_b128 v[216:219], v190 offset:4096
	ds_read_b128 v[220:223], v190 offset:5120
	ds_read_b128 v[224:227], v190 offset:6144
	ds_read_b128 v[242:245], v190 offset:7168
	global_load_lds_dwordx4 v162, s[10:11]
	s_add_i32 m0, s46, 0xe000
	s_nop 0
	global_load_lds_dwordx4 v160, s[10:11]
	s_waitcnt vmcnt(8)
	s_waitcnt lgkmcnt(0)
	s_barrier
	s_setprio 1
	s_waitcnt lgkmcnt(0)
	v_mfma_f32_16x16x32_bf16 v[126:129], v[130:133], v[192:195], v[126:129]
	v_mfma_f32_16x16x32_bf16 v[122:125], v[138:141], v[192:195], v[122:125]
	v_mfma_f32_16x16x32_bf16 v[110:113], v[130:133], v[208:211], v[110:113]
	v_mfma_f32_16x16x32_bf16 v[106:109], v[138:141], v[208:211], v[106:109]
	v_mfma_f32_16x16x32_bf16 v[94:97], v[130:133], v[216:219], v[94:97]
	v_mfma_f32_16x16x32_bf16 v[90:93], v[138:141], v[216:219], v[90:93]
	v_mfma_f32_16x16x32_bf16 v[78:81], v[130:133], v[224:227], v[78:81]
	v_mfma_f32_16x16x32_bf16 v[74:77], v[138:141], v[224:227], v[74:77]
	v_mfma_f32_16x16x32_bf16 v[126:129], v[134:137], v[204:207], v[126:129]
	v_mfma_f32_16x16x32_bf16 v[122:125], v[142:145], v[204:207], v[122:125]
	v_mfma_f32_16x16x32_bf16 v[110:113], v[134:137], v[212:215], v[110:113]
	v_mfma_f32_16x16x32_bf16 v[106:109], v[142:145], v[212:215], v[106:109]
	v_mfma_f32_16x16x32_bf16 v[94:97], v[134:137], v[220:223], v[94:97]
	v_mfma_f32_16x16x32_bf16 v[90:93], v[142:145], v[220:223], v[90:93]
	v_mfma_f32_16x16x32_bf16 v[78:81], v[134:137], v[242:245], v[78:81]
	v_mfma_f32_16x16x32_bf16 v[74:77], v[142:145], v[242:245], v[74:77]
	s_setprio 0
	s_setprio 1
	v_mfma_f32_16x16x32_bf16 v[118:121], v[146:149], v[192:195], v[118:121]
	v_mfma_f32_16x16x32_bf16 v[114:117], v[164:167], v[192:195], v[114:117]
	v_mfma_f32_16x16x32_bf16 v[102:105], v[146:149], v[208:211], v[102:105]
	v_mfma_f32_16x16x32_bf16 v[98:101], v[164:167], v[208:211], v[98:101]
	v_mfma_f32_16x16x32_bf16 v[86:89], v[146:149], v[216:219], v[86:89]
	v_mfma_f32_16x16x32_bf16 v[82:85], v[164:167], v[216:219], v[82:85]
	v_mfma_f32_16x16x32_bf16 v[70:73], v[146:149], v[224:227], v[70:73]
	v_mfma_f32_16x16x32_bf16 v[66:69], v[164:167], v[224:227], v[66:69]
	v_mfma_f32_16x16x32_bf16 v[118:121], v[150:153], v[204:207], v[118:121]
	v_mfma_f32_16x16x32_bf16 v[114:117], v[168:171], v[204:207], v[114:117]
	v_mfma_f32_16x16x32_bf16 v[102:105], v[150:153], v[212:215], v[102:105]
	v_mfma_f32_16x16x32_bf16 v[98:101], v[168:171], v[212:215], v[98:101]
	v_mfma_f32_16x16x32_bf16 v[86:89], v[150:153], v[220:223], v[86:89]
	v_mfma_f32_16x16x32_bf16 v[82:85], v[168:171], v[220:223], v[82:85]
	v_mfma_f32_16x16x32_bf16 v[70:73], v[150:153], v[242:245], v[70:73]
	v_mfma_f32_16x16x32_bf16 v[66:69], v[168:171], v[242:245], v[66:69]
	s_setprio 0
	s_barrier
	s_add_i32 s10, s39, s43
	s_mov_b32 m0, s10
	ds_read_b128 v[192:195], v190 offset:16384
	ds_read_b128 v[204:207], v190 offset:17408
	ds_read_b128 v[208:211], v190 offset:18432
	ds_read_b128 v[212:215], v190 offset:19456
	ds_read_b128 v[216:219], v190 offset:20480
	ds_read_b128 v[220:223], v190 offset:21504
	ds_read_b128 v[224:227], v190 offset:22528
	ds_read_b128 v[242:245], v190 offset:23552
	global_load_lds_dwordx4 v0, s[72:73]
	s_add_i32 m0, s10, 0x2000
	s_add_u32 s10, s72, 0xb0000
	s_addc_u32 s11, s73, 0
	s_add_i32 s30, s30, s43
	global_load_lds_dwordx4 v158, s[72:73]
	s_mov_b32 m0, s30
	s_nop 0
	global_load_lds_dwordx4 v0, s[10:11]
	s_add_i32 m0, s30, 0x2000
	s_nop 0
	global_load_lds_dwordx4 v158, s[10:11]
	s_mov_b32 m0, s46
	s_nop 0
	global_load_lds_dwordx4 v154, s[74:75]
	s_mov_b32 m0, s47
	s_nop 0
	global_load_lds_dwordx4 v156, s[74:75]
	s_waitcnt vmcnt(8)
	s_waitcnt lgkmcnt(0)
	s_barrier
	s_setprio 1
	s_waitcnt lgkmcnt(0)
	v_mfma_f32_16x16x32_bf16 v[62:65], v[130:133], v[192:195], v[62:65]
	v_mfma_f32_16x16x32_bf16 v[58:61], v[138:141], v[192:195], v[58:61]
	v_mfma_f32_16x16x32_bf16 v[46:49], v[130:133], v[208:211], v[46:49]
	v_mfma_f32_16x16x32_bf16 v[42:45], v[138:141], v[208:211], v[42:45]
	v_mfma_f32_16x16x32_bf16 v[30:33], v[130:133], v[216:219], v[30:33]
	v_mfma_f32_16x16x32_bf16 v[26:29], v[138:141], v[216:219], v[26:29]
	v_mfma_f32_16x16x32_bf16 v[14:17], v[130:133], v[224:227], v[14:17]
	v_mfma_f32_16x16x32_bf16 v[10:13], v[138:141], v[224:227], v[10:13]
	v_mfma_f32_16x16x32_bf16 v[62:65], v[134:137], v[204:207], v[62:65]
	v_mfma_f32_16x16x32_bf16 v[58:61], v[142:145], v[204:207], v[58:61]
	v_mfma_f32_16x16x32_bf16 v[46:49], v[134:137], v[212:215], v[46:49]
	v_mfma_f32_16x16x32_bf16 v[42:45], v[142:145], v[212:215], v[42:45]
	v_mfma_f32_16x16x32_bf16 v[30:33], v[134:137], v[220:223], v[30:33]
	v_mfma_f32_16x16x32_bf16 v[26:29], v[142:145], v[220:223], v[26:29]
	v_mfma_f32_16x16x32_bf16 v[14:17], v[134:137], v[242:245], v[14:17]
	v_mfma_f32_16x16x32_bf16 v[10:13], v[142:145], v[242:245], v[10:13]
	s_setprio 0
	s_setprio 1
	v_mfma_f32_16x16x32_bf16 v[54:57], v[146:149], v[192:195], v[54:57]
	v_mfma_f32_16x16x32_bf16 v[50:53], v[164:167], v[192:195], v[50:53]
	v_mfma_f32_16x16x32_bf16 v[38:41], v[146:149], v[208:211], v[38:41]
	v_mfma_f32_16x16x32_bf16 v[34:37], v[164:167], v[208:211], v[34:37]
	v_mfma_f32_16x16x32_bf16 v[22:25], v[146:149], v[216:219], v[22:25]
	v_mfma_f32_16x16x32_bf16 v[18:21], v[164:167], v[216:219], v[18:21]
	v_mfma_f32_16x16x32_bf16 v[6:9], v[146:149], v[224:227], v[6:9]
	v_mfma_f32_16x16x32_bf16 v[2:5], v[164:167], v[224:227], v[2:5]
	v_mfma_f32_16x16x32_bf16 v[54:57], v[150:153], v[204:207], v[54:57]
	v_mfma_f32_16x16x32_bf16 v[50:53], v[168:171], v[204:207], v[50:53]
	v_mfma_f32_16x16x32_bf16 v[38:41], v[150:153], v[212:215], v[38:41]
	v_mfma_f32_16x16x32_bf16 v[34:37], v[168:171], v[212:215], v[34:37]
	v_mfma_f32_16x16x32_bf16 v[22:25], v[150:153], v[220:223], v[22:25]
	v_mfma_f32_16x16x32_bf16 v[18:21], v[168:171], v[220:223], v[18:21]
	v_mfma_f32_16x16x32_bf16 v[6:9], v[150:153], v[242:245], v[6:9]
	v_mfma_f32_16x16x32_bf16 v[2:5], v[168:171], v[242:245], v[2:5]
	s_setprio 0
	s_barrier
; #define PG8_STAGE(bufoff, gbase, voff) do { _Pragma("unroll") for (int _i = 0; _i < 2; ++_i) \
;         __builtin_amdgcn_global_load_lds((const gunsigned*)((const gchar*)(gbase) + (voff)[_i]), (LAS unsigned*)(lds + (bufoff) + ldsw + _i * 8192), 16, 0, 0); } while (0)
; #define PG8_LDA(dst, b, h) do { _Pragma("unroll") for (int m = 0; m < 4; ++m) _Pragma("unroll") for (int k = 0; k < 2; ++k) dst[m][k] = *(const LAS bf16x8*)(lds + PG8_SA(b, h) + aoff + m * 2048 + k * 1024); } while (0)
; #define PG8_LDB(dst, b, h) do { _Pragma("unroll") for (int n = 0; n < 2; ++n) _Pragma("unroll") for (int k = 0; k < 2; ++k) dst[n][k] = *(const LAS bf16x8*)(lds + PG8_SB(b, h) + boff + n * 2048 + k * 1024); } while (0)
; #define PG8_WAIT_V(n) asm volatile("s_waitcnt vmcnt(" #n ")" ::: "memory")
; template <class Epi, class Sched>
; __device__ __forceinline__ void gemm_phase(LAS unsigned char* lds, const int tid, const Gemm g, const Sched& S, const Epi& E) {
;     ...
;         for (int t = 0; t < nt; t += 2) {
;             const bool last = (t == nt - 2);
;             const gchar* a1 = cA + (size_t)(t + 1) * kstep;
;             const gchar* a2 = last ? nA : cA + (size_t)(t + 2) * kstep; const gchar* b2 = last ? nB : cB + (size_t)(t + 2) * kstep;
;             const gchar* a3 = a2 + kstep; const gchar* b3 = b2 + kstep;
;             PG8_LDB(B0, 0, 0); PG8_LDB(B1, 0, 1); PG8_SCHED; PG8_LDA(At, 0, 0); PG8_STAGE(PG8_SA(1, 1), a1 + hstep, voffA);
;             PG8_WAIT_V(8); PG8_WAIT_L(0); PG8_BAR; PG8_MMA(0, 0, At, B0); PG8_MMA(0, 1, At, B1); PG8_BAR; PG8_SCHED;
;             PG8_LDA(At, 0, 1); PG8_STAGE(PG8_SB(0, 0), b2, voffB); PG8_STAGE(PG8_SB(0, 1), b2 + hstep, voffB); PG8_STAGE(PG8_SA(0, 0), a2, voffA);
;             PG8_WAIT_V(8); PG8_WAIT_L(0); PG8_BAR; PG8_MMA(1, 0, At, B0); PG8_MMA(1, 1, At, B1); PG8_BAR; PG8_SCHED;
;             PG8_LDB(B0, 1, 0); PG8_LDB(B1, 1, 1); PG8_SCHED; PG8_LDA(At, 1, 0); PG8_STAGE(PG8_SA(0, 1), a2 + hstep, voffA);
;             PG8_WAIT_V(8); PG8_WAIT_L(0); PG8_BAR; PG8_MMA(0, 0, At, B0); PG8_MMA(0, 1, At, B1); PG8_BAR; PG8_SCHED;
;             PG8_LDA(At, 1, 1); PG8_STAGE(PG8_SB(1, 0), b3, voffB); PG8_STAGE(PG8_SB(1, 1), b3 + hstep, voffB); PG8_STAGE(PG8_SA(1, 0), a3, voffA);
;             PG8_WAIT_V(8); PG8_WAIT_L(0); PG8_BAR; PG8_MMA(1, 0, At, B0); PG8_MMA(1, 1, At, B1); PG8_BAR; PG8_SCHED;
;         }
	s_add_i32 s30, 0, 0x18000
	s_add_i32 s39, 0, 0x1c000
	v_add_u32_e32 v142, s30, v174
	v_add_u32_e32 v168, s39, v174
	ds_read_b128 v[130:133], v142
	ds_read_b128 v[134:137], v142 offset:1024
	ds_read_b128 v[138:141], v142 offset:2048
	ds_read_b128 v[142:145], v142 offset:3072
	ds_read_b128 v[146:149], v168
	ds_read_b128 v[150:153], v168 offset:1024
	ds_read_b128 v[164:167], v168 offset:2048
	ds_read_b128 v[168:171], v168 offset:3072
	s_add_u32 s10, s74, 0xb0000
	s_addc_u32 s11, s75, 0
	s_mov_b32 m0, s48
	ds_read_b128 v[192:195], v190 offset:32768
	ds_read_b128 v[204:207], v190 offset:33792
	ds_read_b128 v[208:211], v190 offset:34816
	ds_read_b128 v[212:215], v190 offset:35840
	ds_read_b128 v[216:219], v190 offset:36864
	ds_read_b128 v[220:223], v190 offset:37888
	ds_read_b128 v[224:227], v190 offset:38912
	ds_read_b128 v[242:245], v190 offset:39936
	global_load_lds_dwordx4 v154, s[10:11]
	s_mov_b32 m0, s49
	s_nop 0
	global_load_lds_dwordx4 v156, s[10:11]
	s_waitcnt vmcnt(8)
	s_waitcnt lgkmcnt(0)
	s_barrier
	s_setprio 1
	s_waitcnt lgkmcnt(0)
	v_mfma_f32_16x16x32_bf16 v[126:129], v[130:133], v[192:195], v[126:129]
	v_mfma_f32_16x16x32_bf16 v[122:125], v[138:141], v[192:195], v[122:125]
	v_mfma_f32_16x16x32_bf16 v[110:113], v[130:133], v[208:211], v[110:113]
	v_mfma_f32_16x16x32_bf16 v[106:109], v[138:141], v[208:211], v[106:109]
	v_mfma_f32_16x16x32_bf16 v[94:97], v[130:133], v[216:219], v[94:97]
	v_mfma_f32_16x16x32_bf16 v[90:93], v[138:141], v[216:219], v[90:93]
	v_mfma_f32_16x16x32_bf16 v[78:81], v[130:133], v[224:227], v[78:81]
	v_mfma_f32_16x16x32_bf16 v[74:77], v[138:141], v[224:227], v[74:77]
	v_mfma_f32_16x16x32_bf16 v[126:129], v[134:137], v[204:207], v[126:129]
	v_mfma_f32_16x16x32_bf16 v[122:125], v[142:145], v[204:207], v[122:125]
	v_mfma_f32_16x16x32_bf16 v[110:113], v[134:137], v[212:215], v[110:113]
	v_mfma_f32_16x16x32_bf16 v[106:109], v[142:145], v[212:215], v[106:109]
	v_mfma_f32_16x16x32_bf16 v[94:97], v[134:137], v[220:223], v[94:97]
	v_mfma_f32_16x16x32_bf16 v[90:93], v[142:145], v[220:223], v[90:93]
	v_mfma_f32_16x16x32_bf16 v[78:81], v[134:137], v[242:245], v[78:81]
	v_mfma_f32_16x16x32_bf16 v[74:77], v[142:145], v[242:245], v[74:77]
	s_setprio 0
	s_setprio 1
	v_mfma_f32_16x16x32_bf16 v[118:121], v[146:149], v[192:195], v[118:121]
	v_mfma_f32_16x16x32_bf16 v[114:117], v[164:167], v[192:195], v[114:117]
	v_mfma_f32_16x16x32_bf16 v[102:105], v[146:149], v[208:211], v[102:105]
	v_mfma_f32_16x16x32_bf16 v[98:101], v[164:167], v[208:211], v[98:101]
	v_mfma_f32_16x16x32_bf16 v[86:89], v[146:149], v[216:219], v[86:89]
	v_mfma_f32_16x16x32_bf16 v[82:85], v[164:167], v[216:219], v[82:85]
	v_mfma_f32_16x16x32_bf16 v[70:73], v[146:149], v[224:227], v[70:73]
	v_mfma_f32_16x16x32_bf16 v[66:69], v[164:167], v[224:227], v[66:69]
	v_mfma_f32_16x16x32_bf16 v[118:121], v[150:153], v[204:207], v[118:121]
	v_mfma_f32_16x16x32_bf16 v[114:117], v[168:171], v[204:207], v[114:117]
	v_mfma_f32_16x16x32_bf16 v[102:105], v[150:153], v[212:215], v[102:105]
	v_mfma_f32_16x16x32_bf16 v[98:101], v[168:171], v[212:215], v[98:101]
	v_mfma_f32_16x16x32_bf16 v[86:89], v[150:153], v[220:223], v[86:89]
	v_mfma_f32_16x16x32_bf16 v[82:85], v[168:171], v[220:223], v[82:85]
	v_mfma_f32_16x16x32_bf16 v[70:73], v[150:153], v[242:245], v[70:73]
	v_mfma_f32_16x16x32_bf16 v[66:69], v[168:171], v[242:245], v[66:69]
	s_setprio 0
	s_barrier
	s_add_i32 s10, s30, s43
	s_mov_b32 m0, s10
	ds_read_b128 v[192:195], v190 offset:49152
	ds_read_b128 v[204:207], v190 offset:50176
	ds_read_b128 v[208:211], v190 offset:51200
	ds_read_b128 v[212:215], v190 offset:52224
	ds_read_b128 v[216:219], v190 offset:53248
	ds_read_b128 v[220:223], v190 offset:54272
	ds_read_b128 v[224:227], v190 offset:55296
	ds_read_b128 v[242:245], v190 offset:56320
	global_load_lds_dwordx4 v201, s[72:73]
	s_add_i32 m0, s10, 0x2000
	s_add_u32 s10, s72, 0xb0080
	s_addc_u32 s11, s73, 0
	s_add_i32 s30, s39, s43
	global_load_lds_dwordx4 v247, s[72:73]
	s_mov_b32 m0, s30
	s_nop 0
	global_load_lds_dwordx4 v0, s[10:11]
	s_add_i32 m0, s30, 0x2000
	s_nop 0
	global_load_lds_dwordx4 v158, s[10:11]
	s_mov_b32 m0, s53
	s_nop 0
	global_load_lds_dwordx4 v249, s[74:75]
	s_mov_b32 m0, s54
	s_nop 0
	global_load_lds_dwordx4 v251, s[74:75]
	s_waitcnt vmcnt(8)
	s_waitcnt lgkmcnt(0)
	s_barrier
	s_setprio 1
	s_waitcnt lgkmcnt(0)
	v_mfma_f32_16x16x32_bf16 v[62:65], v[130:133], v[192:195], v[62:65]
	v_mfma_f32_16x16x32_bf16 v[58:61], v[138:141], v[192:195], v[58:61]
	v_mfma_f32_16x16x32_bf16 v[46:49], v[130:133], v[208:211], v[46:49]
	v_mfma_f32_16x16x32_bf16 v[42:45], v[138:141], v[208:211], v[42:45]
	v_mfma_f32_16x16x32_bf16 v[30:33], v[130:133], v[216:219], v[30:33]
	v_mfma_f32_16x16x32_bf16 v[26:29], v[138:141], v[216:219], v[26:29]
	v_mfma_f32_16x16x32_bf16 v[14:17], v[130:133], v[224:227], v[14:17]
	v_mfma_f32_16x16x32_bf16 v[10:13], v[138:141], v[224:227], v[10:13]
	v_mfma_f32_16x16x32_bf16 v[62:65], v[134:137], v[204:207], v[62:65]
	v_mfma_f32_16x16x32_bf16 v[58:61], v[142:145], v[204:207], v[58:61]
	v_mfma_f32_16x16x32_bf16 v[46:49], v[134:137], v[212:215], v[46:49]
	v_mfma_f32_16x16x32_bf16 v[42:45], v[142:145], v[212:215], v[42:45]
	v_mfma_f32_16x16x32_bf16 v[30:33], v[134:137], v[220:223], v[30:33]
	v_mfma_f32_16x16x32_bf16 v[26:29], v[142:145], v[220:223], v[26:29]
	v_mfma_f32_16x16x32_bf16 v[14:17], v[134:137], v[242:245], v[14:17]
	v_mfma_f32_16x16x32_bf16 v[10:13], v[142:145], v[242:245], v[10:13]
	s_setprio 0
	s_setprio 1
	v_mfma_f32_16x16x32_bf16 v[54:57], v[146:149], v[192:195], v[54:57]
	v_mfma_f32_16x16x32_bf16 v[50:53], v[164:167], v[192:195], v[50:53]
	v_mfma_f32_16x16x32_bf16 v[38:41], v[146:149], v[208:211], v[38:41]
	v_mfma_f32_16x16x32_bf16 v[34:37], v[164:167], v[208:211], v[34:37]
	v_mfma_f32_16x16x32_bf16 v[22:25], v[146:149], v[216:219], v[22:25]
	v_mfma_f32_16x16x32_bf16 v[18:21], v[164:167], v[216:219], v[18:21]
	v_mfma_f32_16x16x32_bf16 v[6:9], v[146:149], v[224:227], v[6:9]
	v_mfma_f32_16x16x32_bf16 v[2:5], v[164:167], v[224:227], v[2:5]
	v_mfma_f32_16x16x32_bf16 v[54:57], v[150:153], v[204:207], v[54:57]
	v_mfma_f32_16x16x32_bf16 v[50:53], v[168:171], v[204:207], v[50:53]
	v_mfma_f32_16x16x32_bf16 v[38:41], v[150:153], v[212:215], v[38:41]
	v_mfma_f32_16x16x32_bf16 v[34:37], v[168:171], v[212:215], v[34:37]
	v_mfma_f32_16x16x32_bf16 v[22:25], v[150:153], v[220:223], v[22:25]
	v_mfma_f32_16x16x32_bf16 v[18:21], v[168:171], v[220:223], v[18:21]
	v_mfma_f32_16x16x32_bf16 v[6:9], v[150:153], v[242:245], v[6:9]
	v_mfma_f32_16x16x32_bf16 v[2:5], v[168:171], v[242:245], v[2:5]
	s_add_i32 s29, s29, 2
	s_add_u32 s31, s31, 0x100
	s_addc_u32 s93, s93, 0
	s_cmp_gt_u32 s29, 41
	s_mov_b64 s[10:11], vcc
	s_cbranch_scc1 .Lrot_exit_319
	s_add_u32 vcc_lo, s10, 0x100
	s_addc_u32 vcc_hi, s11, 0
	s_add_i32 s39, 0, 0x10000
	s_cmp_eq_u32 s29, 40
	s_cselect_b32 s75, s21, vcc_hi
	s_cselect_b32 s74, s20, vcc_lo
	s_cselect_b32 s73, s1, s93
	s_cselect_b32 s72, s0, s31
	s_add_i32 s30, 0, 0x14000
	v_add_u32_e32 v142, s39, v174
	v_add_u32_e32 v168, s30, v174
	s_setprio 0
	s_barrier
	s_branch .Lrot_319
; #define PG8_MMA(ai, bj, At, Bt) do { __builtin_amdgcn_s_setprio(1); _Pragma("unroll") for (int m = 0; m < 4; ++m) _Pragma("unroll") for (int n = 0; n < 2; ++n) _Pragma("unroll") for (int k = 0; k < 2; ++k) \
;         acc[ai][bj][m][n] = __builtin_amdgcn_mfma_f32_16x16x32_bf16(Bt[n][k], At[m][k], acc[ai][bj][m][n], 0, 0, 0); __builtin_amdgcn_s_setprio(0); } while (0)
; #define PG8_WAIT_V(n) asm volatile("s_waitcnt vmcnt(" #n ")" ::: "memory")
; #define PG8_WAIT_L(n) asm volatile("s_waitcnt lgkmcnt(" #n ")" ::: "memory")
; #define PG8_BAR __builtin_amdgcn_s_barrier()
; #define PG8_SCHED __builtin_amdgcn_sched_barrier(0)
; template <class Epi, class Sched>
; __device__ __forceinline__ void gemm_phase(LAS unsigned char* lds, const int tid, const Gemm g, const Sched& S, const Epi& E) {
;     ...
;             PG8_WAIT_V(8); PG8_WAIT_L(0); PG8_BAR; PG8_MMA(1, 0, At, B0); PG8_MMA(1, 1, At, B1); PG8_BAR; PG8_SCHED;
;         }
;         if (wr == 0) PG8_BAR;
;         E(acc, cur, wr, wc, fr, fq, lds, tid);
.Lrot_exit_319:
	s_setprio 0
	s_barrier
	s_and_b64 vcc, exec, s[16:17]
	s_cbranch_vccz .LBB0_322
	s_barrier

; #define PG8_STAGE(bufoff, gbase, voff) do { _Pragma("unroll") for (int _i = 0; _i < 2; ++_i) \
;         __builtin_amdgcn_global_load_lds((const gunsigned*)((const gchar*)(gbase) + (voff)[_i]), (LAS unsigned*)(lds + (bufoff) + ldsw + _i * 8192), 16, 0, 0); } while (0)
; #define PG8_LDA(dst, b, h) do { _Pragma("unroll") for (int m = 0; m < 4; ++m) _Pragma("unroll") for (int k = 0; k < 2; ++k) dst[m][k] = *(const LAS bf16x8*)(lds + PG8_SA(b, h) + aoff + m * 2048 + k * 1024); } while (0)
; #define PG8_LDB(dst, b, h) do { _Pragma("unroll") for (int n = 0; n < 2; ++n) _Pragma("unroll") for (int k = 0; k < 2; ++k) dst[n][k] = *(const LAS bf16x8*)(lds + PG8_SB(b, h) + boff + n * 2048 + k * 1024); } while (0)
; #define PG8_WAIT_V(n) asm volatile("s_waitcnt vmcnt(" #n ")" ::: "memory")
; template <class Epi, class Sched>
; __device__ __forceinline__ void gemm_phase(LAS unsigned char* lds, const int tid, const Gemm g, const Sched& S, const Epi& E) {
;     ...
;         for (int t = 0; t < nt; t += 2) {
;             const bool last = (t == nt - 2);
;             const gchar* a1 = cA + (size_t)(t + 1) * kstep;
;             const gchar* a2 = last ? nA : cA + (size_t)(t + 2) * kstep; const gchar* b2 = last ? nB : cB + (size_t)(t + 2) * kstep;
;             const gchar* a3 = a2 + kstep; const gchar* b3 = b2 + kstep;
;             PG8_LDB(B0, 0, 0); PG8_LDB(B1, 0, 1); PG8_SCHED; PG8_LDA(At, 0, 0); PG8_STAGE(PG8_SA(1, 1), a1 + hstep, voffA);
;             PG8_WAIT_V(8); PG8_WAIT_L(0); PG8_BAR; PG8_MMA(0, 0, At, B0); PG8_MMA(0, 1, At, B1); PG8_BAR; PG8_SCHED;
;             PG8_LDA(At, 0, 1); PG8_STAGE(PG8_SB(0, 0), b2, voffB); PG8_STAGE(PG8_SB(0, 1), b2 + hstep, voffB); PG8_STAGE(PG8_SA(0, 0), a2, voffA);
;             PG8_WAIT_V(8); PG8_WAIT_L(0); PG8_BAR; PG8_MMA(1, 0, At, B0); PG8_MMA(1, 1, At, B1); PG8_BAR; PG8_SCHED;
;             PG8_LDB(B0, 1, 0); PG8_LDB(B1, 1, 1); PG8_SCHED; PG8_LDA(At, 1, 0); PG8_STAGE(PG8_SA(0, 1), a2 + hstep, voffA);
;             PG8_WAIT_V(8); PG8_WAIT_L(0); PG8_BAR; PG8_MMA(0, 0, At, B0); PG8_MMA(0, 1, At, B1); PG8_BAR; PG8_SCHED;
;             PG8_LDA(At, 1, 1); PG8_STAGE(PG8_SB(1, 0), b3, voffB); PG8_STAGE(PG8_SB(1, 1), b3 + hstep, voffB); PG8_STAGE(PG8_SA(1, 0), a3, voffA);
;             PG8_WAIT_V(8); PG8_WAIT_L(0); PG8_BAR; PG8_MMA(1, 0, At, B0); PG8_MMA(1, 1, At, B1); PG8_BAR; PG8_SCHED;
;         }
.Lrot_369:
	ds_read_b128 v[146:149], v140
	ds_read_b128 v[156:159], v140 offset:1024
	ds_read_b128 v[160:163], v140 offset:2048
	ds_read_b128 v[164:167], v140 offset:3072
	v_add_u32_e32 v140, s30, v145
	ds_read_b128 v[168:171], v140
	ds_read_b128 v[172:175], v140 offset:1024
	ds_read_b128 v[176:179], v140 offset:2048
	ds_read_b128 v[180:183], v140 offset:3072
	s_add_i32 m0, s73, 0xc000
	ds_read_b128 v[184:187], v155
	ds_read_b128 v[188:191], v155 offset:1024
	ds_read_b128 v[192:195], v155 offset:2048
	ds_read_b128 v[204:207], v155 offset:3072
	ds_read_b128 v[208:211], v155 offset:4096
	ds_read_b128 v[212:215], v155 offset:5120
	ds_read_b128 v[216:219], v155 offset:6144
	ds_read_b128 v[220:223], v155 offset:7168
	global_load_lds_dwordx4 v138, s[16:17]
	s_add_i32 m0, s73, 0xe000
	s_nop 0
	global_load_lds_dwordx4 v136, s[16:17]
	s_waitcnt vmcnt(8)
	s_waitcnt lgkmcnt(0)
	s_barrier
	s_setprio 1
	s_waitcnt lgkmcnt(0)
	v_mfma_f32_16x16x32_bf16 v[126:129], v[146:149], v[184:187], v[126:129]
	v_mfma_f32_16x16x32_bf16 v[118:121], v[160:163], v[184:187], v[118:121]
	v_mfma_f32_16x16x32_bf16 v[110:113], v[146:149], v[192:195], v[110:113]
	v_mfma_f32_16x16x32_bf16 v[102:105], v[160:163], v[192:195], v[102:105]
	v_mfma_f32_16x16x32_bf16 v[94:97], v[146:149], v[208:211], v[94:97]
	v_mfma_f32_16x16x32_bf16 v[86:89], v[160:163], v[208:211], v[86:89]
	v_mfma_f32_16x16x32_bf16 v[78:81], v[146:149], v[216:219], v[78:81]
	v_mfma_f32_16x16x32_bf16 v[70:73], v[160:163], v[216:219], v[70:73]
	v_mfma_f32_16x16x32_bf16 v[126:129], v[156:159], v[188:191], v[126:129]
	v_mfma_f32_16x16x32_bf16 v[118:121], v[164:167], v[188:191], v[118:121]
	v_mfma_f32_16x16x32_bf16 v[110:113], v[156:159], v[204:207], v[110:113]
	v_mfma_f32_16x16x32_bf16 v[102:105], v[164:167], v[204:207], v[102:105]
	v_mfma_f32_16x16x32_bf16 v[94:97], v[156:159], v[212:215], v[94:97]
	v_mfma_f32_16x16x32_bf16 v[86:89], v[164:167], v[212:215], v[86:89]
	v_mfma_f32_16x16x32_bf16 v[78:81], v[156:159], v[220:223], v[78:81]
	v_mfma_f32_16x16x32_bf16 v[70:73], v[164:167], v[220:223], v[70:73]
	s_setprio 0
	s_setprio 1
	v_mfma_f32_16x16x32_bf16 v[122:125], v[168:171], v[184:187], v[122:125]
	v_mfma_f32_16x16x32_bf16 v[114:117], v[176:179], v[184:187], v[114:117]
	v_mfma_f32_16x16x32_bf16 v[106:109], v[168:171], v[192:195], v[106:109]
	v_mfma_f32_16x16x32_bf16 v[98:101], v[176:179], v[192:195], v[98:101]
	v_mfma_f32_16x16x32_bf16 v[90:93], v[168:171], v[208:211], v[90:93]
	v_mfma_f32_16x16x32_bf16 v[82:85], v[176:179], v[208:211], v[82:85]
	v_mfma_f32_16x16x32_bf16 v[74:77], v[168:171], v[216:219], v[74:77]
	v_mfma_f32_16x16x32_bf16 v[66:69], v[176:179], v[216:219], v[66:69]
	v_mfma_f32_16x16x32_bf16 v[122:125], v[172:175], v[188:191], v[122:125]
	v_mfma_f32_16x16x32_bf16 v[114:117], v[180:183], v[188:191], v[114:117]
	v_mfma_f32_16x16x32_bf16 v[106:109], v[172:175], v[204:207], v[106:109]
	v_mfma_f32_16x16x32_bf16 v[98:101], v[180:183], v[204:207], v[98:101]
	v_mfma_f32_16x16x32_bf16 v[90:93], v[172:175], v[212:215], v[90:93]
	v_mfma_f32_16x16x32_bf16 v[82:85], v[180:183], v[212:215], v[82:85]
	v_mfma_f32_16x16x32_bf16 v[74:77], v[172:175], v[220:223], v[74:77]
	v_mfma_f32_16x16x32_bf16 v[66:69], v[180:183], v[220:223], v[66:69]
	s_setprio 0
	s_barrier
	s_add_i32 s29, s29, s43
	s_mov_b32 m0, s29
	ds_read_b128 v[184:187], v155 offset:16384
	ds_read_b128 v[188:191], v155 offset:17408
	ds_read_b128 v[192:195], v155 offset:18432
	ds_read_b128 v[204:207], v155 offset:19456
	ds_read_b128 v[208:211], v155 offset:20480
	ds_read_b128 v[212:215], v155 offset:21504
	ds_read_b128 v[216:219], v155 offset:22528
	ds_read_b128 v[220:223], v155 offset:23552
	global_load_lds_dwordx4 v0, s[20:21]
	s_add_i32 m0, s29, 0x2000
	s_add_u32 s46, s20, 0x40000
	s_addc_u32 s47, s21, 0
	s_add_i32 s29, s30, s43
	global_load_lds_dwordx4 v130, s[20:21]
	s_mov_b32 m0, s29
	s_nop 0
	global_load_lds_dwordx4 v0, s[46:47]
	s_add_i32 m0, s29, 0x2000
	s_nop 0
	global_load_lds_dwordx4 v130, s[46:47]
	s_mov_b32 m0, s73
	s_nop 0
	global_load_lds_dwordx4 v134, s[56:57]
	s_mov_b32 m0, s74
	s_nop 0
	global_load_lds_dwordx4 v132, s[56:57]
	s_waitcnt vmcnt(8)
	s_waitcnt lgkmcnt(0)
	s_barrier
	s_setprio 1
	s_waitcnt lgkmcnt(0)
	v_mfma_f32_16x16x32_bf16 v[62:65], v[146:149], v[184:187], v[62:65]
	v_mfma_f32_16x16x32_bf16 v[54:57], v[160:163], v[184:187], v[54:57]
	v_mfma_f32_16x16x32_bf16 v[46:49], v[146:149], v[192:195], v[46:49]
	v_mfma_f32_16x16x32_bf16 v[38:41], v[160:163], v[192:195], v[38:41]
	v_mfma_f32_16x16x32_bf16 v[30:33], v[146:149], v[208:211], v[30:33]
	v_mfma_f32_16x16x32_bf16 v[22:25], v[160:163], v[208:211], v[22:25]
	v_mfma_f32_16x16x32_bf16 v[14:17], v[146:149], v[216:219], v[14:17]
	v_mfma_f32_16x16x32_bf16 v[6:9], v[160:163], v[216:219], v[6:9]
	v_mfma_f32_16x16x32_bf16 v[62:65], v[156:159], v[188:191], v[62:65]
	v_mfma_f32_16x16x32_bf16 v[54:57], v[164:167], v[188:191], v[54:57]
	v_mfma_f32_16x16x32_bf16 v[46:49], v[156:159], v[204:207], v[46:49]
	v_mfma_f32_16x16x32_bf16 v[38:41], v[164:167], v[204:207], v[38:41]
	v_mfma_f32_16x16x32_bf16 v[30:33], v[156:159], v[212:215], v[30:33]
	v_mfma_f32_16x16x32_bf16 v[22:25], v[164:167], v[212:215], v[22:25]
	v_mfma_f32_16x16x32_bf16 v[14:17], v[156:159], v[220:223], v[14:17]
	v_mfma_f32_16x16x32_bf16 v[6:9], v[164:167], v[220:223], v[6:9]
	s_setprio 0
	s_setprio 1
	v_mfma_f32_16x16x32_bf16 v[58:61], v[168:171], v[184:187], v[58:61]
	v_mfma_f32_16x16x32_bf16 v[50:53], v[176:179], v[184:187], v[50:53]
	v_mfma_f32_16x16x32_bf16 v[42:45], v[168:171], v[192:195], v[42:45]
	v_mfma_f32_16x16x32_bf16 v[34:37], v[176:179], v[192:195], v[34:37]
	v_mfma_f32_16x16x32_bf16 v[26:29], v[168:171], v[208:211], v[26:29]
	v_mfma_f32_16x16x32_bf16 v[18:21], v[176:179], v[208:211], v[18:21]
	v_mfma_f32_16x16x32_bf16 v[10:13], v[168:171], v[216:219], v[10:13]
	v_mfma_f32_16x16x32_bf16 v[2:5], v[176:179], v[216:219], v[2:5]
	v_mfma_f32_16x16x32_bf16 v[58:61], v[172:175], v[188:191], v[58:61]
	v_mfma_f32_16x16x32_bf16 v[50:53], v[180:183], v[188:191], v[50:53]
	v_mfma_f32_16x16x32_bf16 v[42:45], v[172:175], v[204:207], v[42:45]
	v_mfma_f32_16x16x32_bf16 v[34:37], v[180:183], v[204:207], v[34:37]
	v_mfma_f32_16x16x32_bf16 v[26:29], v[172:175], v[212:215], v[26:29]
	v_mfma_f32_16x16x32_bf16 v[18:21], v[180:183], v[212:215], v[18:21]
	v_mfma_f32_16x16x32_bf16 v[10:13], v[172:175], v[220:223], v[10:13]
	v_mfma_f32_16x16x32_bf16 v[2:5], v[180:183], v[220:223], v[2:5]
	s_setprio 0
	s_barrier
; #define PG8_STAGE(bufoff, gbase, voff) do { _Pragma("unroll") for (int _i = 0; _i < 2; ++_i) \
;         __builtin_amdgcn_global_load_lds((const gunsigned*)((const gchar*)(gbase) + (voff)[_i]), (LAS unsigned*)(lds + (bufoff) + ldsw + _i * 8192), 16, 0, 0); } while (0)
; #define PG8_LDA(dst, b, h) do { _Pragma("unroll") for (int m = 0; m < 4; ++m) _Pragma("unroll") for (int k = 0; k < 2; ++k) dst[m][k] = *(const LAS bf16x8*)(lds + PG8_SA(b, h) + aoff + m * 2048 + k * 1024); } while (0)
; #define PG8_LDB(dst, b, h) do { _Pragma("unroll") for (int n = 0; n < 2; ++n) _Pragma("unroll") for (int k = 0; k < 2; ++k) dst[n][k] = *(const LAS bf16x8*)(lds + PG8_SB(b, h) + boff + n * 2048 + k * 1024); } while (0)
; #define PG8_WAIT_V(n) asm volatile("s_waitcnt vmcnt(" #n ")" ::: "memory")
; template <class Epi, class Sched>
; __device__ __forceinline__ void gemm_phase(LAS unsigned char* lds, const int tid, const Gemm g, const Sched& S, const Epi& E) {
;     ...
;         for (int t = 0; t < nt; t += 2) {
;             const bool last = (t == nt - 2);
;             const gchar* a1 = cA + (size_t)(t + 1) * kstep;
;             const gchar* a2 = last ? nA : cA + (size_t)(t + 2) * kstep; const gchar* b2 = last ? nB : cB + (size_t)(t + 2) * kstep;
;             const gchar* a3 = a2 + kstep; const gchar* b3 = b2 + kstep;
;             PG8_LDB(B0, 0, 0); PG8_LDB(B1, 0, 1); PG8_SCHED; PG8_LDA(At, 0, 0); PG8_STAGE(PG8_SA(1, 1), a1 + hstep, voffA);
;             PG8_WAIT_V(8); PG8_WAIT_L(0); PG8_BAR; PG8_MMA(0, 0, At, B0); PG8_MMA(0, 1, At, B1); PG8_BAR; PG8_SCHED;
;             PG8_LDA(At, 0, 1); PG8_STAGE(PG8_SB(0, 0), b2, voffB); PG8_STAGE(PG8_SB(0, 1), b2 + hstep, voffB); PG8_STAGE(PG8_SA(0, 0), a2, voffA);
;             PG8_WAIT_V(8); PG8_WAIT_L(0); PG8_BAR; PG8_MMA(1, 0, At, B0); PG8_MMA(1, 1, At, B1); PG8_BAR; PG8_SCHED;
;             PG8_LDB(B0, 1, 0); PG8_LDB(B1, 1, 1); PG8_SCHED; PG8_LDA(At, 1, 0); PG8_STAGE(PG8_SA(0, 1), a2 + hstep, voffA);
;             PG8_WAIT_V(8); PG8_WAIT_L(0); PG8_BAR; PG8_MMA(0, 0, At, B0); PG8_MMA(0, 1, At, B1); PG8_BAR; PG8_SCHED;
;             PG8_LDA(At, 1, 1); PG8_STAGE(PG8_SB(1, 0), b3, voffB); PG8_STAGE(PG8_SB(1, 1), b3 + hstep, voffB); PG8_STAGE(PG8_SA(1, 0), a3, voffA);
;             PG8_WAIT_V(8); PG8_WAIT_L(0); PG8_BAR; PG8_MMA(1, 0, At, B0); PG8_MMA(1, 1, At, B1); PG8_BAR; PG8_SCHED;
;         }
	s_add_i32 s29, 0, 0x18000
	v_add_u32_e32 v142, s29, v145
	s_add_i32 s30, 0, 0x1c000
	ds_read_b128 v[146:149], v142
	ds_read_b128 v[156:159], v142 offset:1024
	ds_read_b128 v[160:163], v142 offset:2048
	ds_read_b128 v[164:167], v142 offset:3072
	v_add_u32_e32 v142, s30, v145
	ds_read_b128 v[168:171], v142
	ds_read_b128 v[172:175], v142 offset:1024
	ds_read_b128 v[176:179], v142 offset:2048
	ds_read_b128 v[180:183], v142 offset:3072
	s_add_u32 s46, s56, 0x40000
	s_addc_u32 s47, s57, 0
	s_mov_b32 m0, s75
	ds_read_b128 v[184:187], v155 offset:32768
	ds_read_b128 v[188:191], v155 offset:33792
	ds_read_b128 v[192:195], v155 offset:34816
	ds_read_b128 v[204:207], v155 offset:35840
	ds_read_b128 v[208:211], v155 offset:36864
	ds_read_b128 v[212:215], v155 offset:37888
	ds_read_b128 v[216:219], v155 offset:38912
	ds_read_b128 v[220:223], v155 offset:39936
	global_load_lds_dwordx4 v134, s[46:47]
	s_mov_b32 m0, s92
	s_nop 0
	global_load_lds_dwordx4 v132, s[46:47]
	s_waitcnt vmcnt(8)
	s_waitcnt lgkmcnt(0)
	s_barrier
	s_setprio 1
	s_waitcnt lgkmcnt(0)
	v_mfma_f32_16x16x32_bf16 v[126:129], v[146:149], v[184:187], v[126:129]
	v_mfma_f32_16x16x32_bf16 v[118:121], v[160:163], v[184:187], v[118:121]
	v_mfma_f32_16x16x32_bf16 v[110:113], v[146:149], v[192:195], v[110:113]
	v_mfma_f32_16x16x32_bf16 v[102:105], v[160:163], v[192:195], v[102:105]
	v_mfma_f32_16x16x32_bf16 v[94:97], v[146:149], v[208:211], v[94:97]
	v_mfma_f32_16x16x32_bf16 v[86:89], v[160:163], v[208:211], v[86:89]
	v_mfma_f32_16x16x32_bf16 v[78:81], v[146:149], v[216:219], v[78:81]
	v_mfma_f32_16x16x32_bf16 v[70:73], v[160:163], v[216:219], v[70:73]
	v_mfma_f32_16x16x32_bf16 v[126:129], v[156:159], v[188:191], v[126:129]
	v_mfma_f32_16x16x32_bf16 v[118:121], v[164:167], v[188:191], v[118:121]
	v_mfma_f32_16x16x32_bf16 v[110:113], v[156:159], v[204:207], v[110:113]
	v_mfma_f32_16x16x32_bf16 v[102:105], v[164:167], v[204:207], v[102:105]
	v_mfma_f32_16x16x32_bf16 v[94:97], v[156:159], v[212:215], v[94:97]
	v_mfma_f32_16x16x32_bf16 v[86:89], v[164:167], v[212:215], v[86:89]
	v_mfma_f32_16x16x32_bf16 v[78:81], v[156:159], v[220:223], v[78:81]
	v_mfma_f32_16x16x32_bf16 v[70:73], v[164:167], v[220:223], v[70:73]
	s_setprio 0
	s_setprio 1
	v_mfma_f32_16x16x32_bf16 v[122:125], v[168:171], v[184:187], v[122:125]
	v_mfma_f32_16x16x32_bf16 v[114:117], v[176:179], v[184:187], v[114:117]
	v_mfma_f32_16x16x32_bf16 v[106:109], v[168:171], v[192:195], v[106:109]
	v_mfma_f32_16x16x32_bf16 v[98:101], v[176:179], v[192:195], v[98:101]
	v_mfma_f32_16x16x32_bf16 v[90:93], v[168:171], v[208:211], v[90:93]
	v_mfma_f32_16x16x32_bf16 v[82:85], v[176:179], v[208:211], v[82:85]
	v_mfma_f32_16x16x32_bf16 v[74:77], v[168:171], v[216:219], v[74:77]
	v_mfma_f32_16x16x32_bf16 v[66:69], v[176:179], v[216:219], v[66:69]
	v_mfma_f32_16x16x32_bf16 v[122:125], v[172:175], v[188:191], v[122:125]
	v_mfma_f32_16x16x32_bf16 v[114:117], v[180:183], v[188:191], v[114:117]
	v_mfma_f32_16x16x32_bf16 v[106:109], v[172:175], v[204:207], v[106:109]
	v_mfma_f32_16x16x32_bf16 v[98:101], v[180:183], v[204:207], v[98:101]
	v_mfma_f32_16x16x32_bf16 v[90:93], v[172:175], v[212:215], v[90:93]
	v_mfma_f32_16x16x32_bf16 v[82:85], v[180:183], v[212:215], v[82:85]
	v_mfma_f32_16x16x32_bf16 v[74:77], v[172:175], v[220:223], v[74:77]
	v_mfma_f32_16x16x32_bf16 v[66:69], v[180:183], v[220:223], v[66:69]
	s_setprio 0
	s_barrier
	s_add_i32 s29, s29, s43
	s_mov_b32 m0, s29
	ds_read_b128 v[184:187], v155 offset:49152
	ds_read_b128 v[188:191], v155 offset:50176
	ds_read_b128 v[192:195], v155 offset:51200
	ds_read_b128 v[204:207], v155 offset:52224
	ds_read_b128 v[208:211], v155 offset:53248
	ds_read_b128 v[212:215], v155 offset:54272
	ds_read_b128 v[216:219], v155 offset:55296
	ds_read_b128 v[220:223], v155 offset:56320
	global_load_lds_dwordx4 v141, s[20:21]
	s_add_i32 m0, s29, 0x2000
	s_add_i32 s29, s30, s43
	global_load_lds_dwordx4 v153, s[20:21]
	s_add_u32 s20, s20, 0x40080
	s_addc_u32 s21, s21, 0
	s_mov_b32 m0, s29
	s_nop 0
	global_load_lds_dwordx4 v0, s[20:21]
	s_add_i32 m0, s29, 0x2000
	s_nop 0
	global_load_lds_dwordx4 v130, s[20:21]
	s_mov_b32 m0, s93
	s_nop 0
	global_load_lds_dwordx4 v201, s[56:57]
	s_mov_b32 m0, s44
	s_nop 0
	global_load_lds_dwordx4 v225, s[56:57]
	s_waitcnt vmcnt(8)
	s_waitcnt lgkmcnt(0)
	s_barrier
	s_setprio 1
	s_waitcnt lgkmcnt(0)
	v_mfma_f32_16x16x32_bf16 v[62:65], v[146:149], v[184:187], v[62:65]
	v_mfma_f32_16x16x32_bf16 v[54:57], v[160:163], v[184:187], v[54:57]
	v_mfma_f32_16x16x32_bf16 v[46:49], v[146:149], v[192:195], v[46:49]
	v_mfma_f32_16x16x32_bf16 v[38:41], v[160:163], v[192:195], v[38:41]
	v_mfma_f32_16x16x32_bf16 v[30:33], v[146:149], v[208:211], v[30:33]
	v_mfma_f32_16x16x32_bf16 v[22:25], v[160:163], v[208:211], v[22:25]
	v_mfma_f32_16x16x32_bf16 v[14:17], v[146:149], v[216:219], v[14:17]
	v_mfma_f32_16x16x32_bf16 v[6:9], v[160:163], v[216:219], v[6:9]
	v_mfma_f32_16x16x32_bf16 v[62:65], v[156:159], v[188:191], v[62:65]
	v_mfma_f32_16x16x32_bf16 v[54:57], v[164:167], v[188:191], v[54:57]
	v_mfma_f32_16x16x32_bf16 v[46:49], v[156:159], v[204:207], v[46:49]
	v_mfma_f32_16x16x32_bf16 v[38:41], v[164:167], v[204:207], v[38:41]
	v_mfma_f32_16x16x32_bf16 v[30:33], v[156:159], v[212:215], v[30:33]
	v_mfma_f32_16x16x32_bf16 v[22:25], v[164:167], v[212:215], v[22:25]
	v_mfma_f32_16x16x32_bf16 v[14:17], v[156:159], v[220:223], v[14:17]
	v_mfma_f32_16x16x32_bf16 v[6:9], v[164:167], v[220:223], v[6:9]
	s_setprio 0
	s_setprio 1
	v_mfma_f32_16x16x32_bf16 v[58:61], v[168:171], v[184:187], v[58:61]
	v_mfma_f32_16x16x32_bf16 v[50:53], v[176:179], v[184:187], v[50:53]
	v_mfma_f32_16x16x32_bf16 v[42:45], v[168:171], v[192:195], v[42:45]
	v_mfma_f32_16x16x32_bf16 v[34:37], v[176:179], v[192:195], v[34:37]
	v_mfma_f32_16x16x32_bf16 v[26:29], v[168:171], v[208:211], v[26:29]
	v_mfma_f32_16x16x32_bf16 v[18:21], v[176:179], v[208:211], v[18:21]
	v_mfma_f32_16x16x32_bf16 v[10:13], v[168:171], v[216:219], v[10:13]
	v_mfma_f32_16x16x32_bf16 v[2:5], v[176:179], v[216:219], v[2:5]
	v_mfma_f32_16x16x32_bf16 v[58:61], v[172:175], v[188:191], v[58:61]
	v_mfma_f32_16x16x32_bf16 v[50:53], v[180:183], v[188:191], v[50:53]
	v_mfma_f32_16x16x32_bf16 v[42:45], v[172:175], v[204:207], v[42:45]
	v_mfma_f32_16x16x32_bf16 v[34:37], v[180:183], v[204:207], v[34:37]
	v_mfma_f32_16x16x32_bf16 v[26:29], v[172:175], v[212:215], v[26:29]
	v_mfma_f32_16x16x32_bf16 v[18:21], v[180:183], v[212:215], v[18:21]
	v_mfma_f32_16x16x32_bf16 v[10:13], v[172:175], v[220:223], v[10:13]
	v_mfma_f32_16x16x32_bf16 v[2:5], v[180:183], v[220:223], v[2:5]
	s_add_i32 s31, s31, 2
	s_add_u32 s23, s23, 0x100
	s_addc_u32 s24, s24, 0
	s_add_u32 s16, s16, 0x100
	s_addc_u32 s17, s17, 0
	s_cmp_gt_u32 s31, 13
	s_cbranch_scc1 .Lrot_exit_369
	s_add_u32 s20, s16, 0xfffc0080
	s_addc_u32 s21, s17, -1
	s_add_i32 s29, 0, 0x10000
	s_cmp_eq_u32 s31, 12
	s_cselect_b32 s57, s11, s21
	s_cselect_b32 s56, s12, s20
	v_add_u32_e32 v140, s29, v145
	s_cselect_b32 s21, s9, s24
	s_cselect_b32 s20, s15, s23
	s_add_i32 s30, 0, 0x14000
	s_setprio 0
	s_barrier
	s_branch .Lrot_369
; #define PG8_MMA(ai, bj, At, Bt) do { __builtin_amdgcn_s_setprio(1); _Pragma("unroll") for (int m = 0; m < 4; ++m) _Pragma("unroll") for (int n = 0; n < 2; ++n) _Pragma("unroll") for (int k = 0; k < 2; ++k) \
;         acc[ai][bj][m][n] = __builtin_amdgcn_mfma_f32_16x16x32_bf16(Bt[n][k], At[m][k], acc[ai][bj][m][n], 0, 0, 0); __builtin_amdgcn_s_setprio(0); } while (0)
; #define PG8_WAIT_V(n) asm volatile("s_waitcnt vmcnt(" #n ")" ::: "memory")
; #define PG8_WAIT_L(n) asm volatile("s_waitcnt lgkmcnt(" #n ")" ::: "memory")
; #define PG8_BAR __builtin_amdgcn_s_barrier()
; #define PG8_SCHED __builtin_amdgcn_sched_barrier(0)
; template <class Epi, class Sched>
; __device__ __forceinline__ void gemm_phase(LAS unsigned char* lds, const int tid, const Gemm g, const Sched& S, const Epi& E) {
;     ...
;             PG8_WAIT_V(8); PG8_WAIT_L(0); PG8_BAR; PG8_MMA(1, 0, At, B0); PG8_MMA(1, 1, At, B1); PG8_BAR; PG8_SCHED;
;         }
;         if (wr == 0) PG8_BAR;
;         E(acc, cur, wr, wc, fr, fq, lds, tid);
.Lrot_exit_369:
	s_setprio 0
	s_barrier
	s_and_b64 vcc, exec, s[6:7]
	s_cbranch_vccz .LBB0_372
	s_barrier

; #define PG8_STAGE(bufoff, gbase, voff) do { _Pragma("unroll") for (int _i = 0; _i < 2; ++_i) \
;         __builtin_amdgcn_global_load_lds((const gunsigned*)((const gchar*)(gbase) + (voff)[_i]), (LAS unsigned*)(lds + (bufoff) + ldsw + _i * 8192), 16, 0, 0); } while (0)
; #define PG8_LDA(dst, b, h) do { _Pragma("unroll") for (int m = 0; m < 4; ++m) _Pragma("unroll") for (int k = 0; k < 2; ++k) dst[m][k] = *(const LAS bf16x8*)(lds + PG8_SA(b, h) + aoff + m * 2048 + k * 1024); } while (0)
; #define PG8_LDB(dst, b, h) do { _Pragma("unroll") for (int n = 0; n < 2; ++n) _Pragma("unroll") for (int k = 0; k < 2; ++k) dst[n][k] = *(const LAS bf16x8*)(lds + PG8_SB(b, h) + boff + n * 2048 + k * 1024); } while (0)
; #define PG8_WAIT_V(n) asm volatile("s_waitcnt vmcnt(" #n ")" ::: "memory")
; template <class Epi, class Sched>
; __device__ __forceinline__ void gemm_phase(LAS unsigned char* lds, const int tid, const Gemm g, const Sched& S, const Epi& E) {
;     ...
;         for (int t = 0; t < nt; t += 2) {
;             const bool last = (t == nt - 2);
;             const gchar* a1 = cA + (size_t)(t + 1) * kstep;
;             const gchar* a2 = last ? nA : cA + (size_t)(t + 2) * kstep; const gchar* b2 = last ? nB : cB + (size_t)(t + 2) * kstep;
;             const gchar* a3 = a2 + kstep; const gchar* b3 = b2 + kstep;
;             PG8_LDB(B0, 0, 0); PG8_LDB(B1, 0, 1); PG8_SCHED; PG8_LDA(At, 0, 0); PG8_STAGE(PG8_SA(1, 1), a1 + hstep, voffA);
;             PG8_WAIT_V(8); PG8_WAIT_L(0); PG8_BAR; PG8_MMA(0, 0, At, B0); PG8_MMA(0, 1, At, B1); PG8_BAR; PG8_SCHED;
;             PG8_LDA(At, 0, 1); PG8_STAGE(PG8_SB(0, 0), b2, voffB); PG8_STAGE(PG8_SB(0, 1), b2 + hstep, voffB); PG8_STAGE(PG8_SA(0, 0), a2, voffA);
;             PG8_WAIT_V(8); PG8_WAIT_L(0); PG8_BAR; PG8_MMA(1, 0, At, B0); PG8_MMA(1, 1, At, B1); PG8_BAR; PG8_SCHED;
;             PG8_LDB(B0, 1, 0); PG8_LDB(B1, 1, 1); PG8_SCHED; PG8_LDA(At, 1, 0); PG8_STAGE(PG8_SA(0, 1), a2 + hstep, voffA);
;             PG8_WAIT_V(8); PG8_WAIT_L(0); PG8_BAR; PG8_MMA(0, 0, At, B0); PG8_MMA(0, 1, At, B1); PG8_BAR; PG8_SCHED;
;             PG8_LDA(At, 1, 1); PG8_STAGE(PG8_SB(1, 0), b3, voffB); PG8_STAGE(PG8_SB(1, 1), b3 + hstep, voffB); PG8_STAGE(PG8_SA(1, 0), a3, voffA);
;             PG8_WAIT_V(8); PG8_WAIT_L(0); PG8_BAR; PG8_MMA(1, 0, At, B0); PG8_MMA(1, 1, At, B1); PG8_BAR; PG8_SCHED;
;         }
.Lrot_397:
	ds_read_b128 v[130:133], v142
	ds_read_b128 v[134:137], v142 offset:1024
	ds_read_b128 v[138:141], v142 offset:2048
	ds_read_b128 v[142:145], v142 offset:3072
	ds_read_b128 v[146:149], v168
	ds_read_b128 v[150:153], v168 offset:1024
	ds_read_b128 v[164:167], v168 offset:2048
	ds_read_b128 v[168:171], v168 offset:3072
	s_add_i32 m0, s43, 0xc000
	ds_read_b128 v[172:175], v181
	ds_read_b128 v[182:185], v181 offset:1024
	ds_read_b128 v[186:189], v181 offset:2048
	ds_read_b128 v[190:193], v181 offset:3072
	ds_read_b128 v[204:207], v181 offset:4096
	ds_read_b128 v[208:211], v181 offset:5120
	ds_read_b128 v[212:215], v181 offset:6144
	ds_read_b128 v[216:219], v181 offset:7168
	global_load_lds_dwordx4 v162, s[92:93]
	s_add_i32 m0, s43, 0xe000
	s_nop 0
	global_load_lds_dwordx4 v160, s[92:93]
	s_waitcnt vmcnt(8)
	s_waitcnt lgkmcnt(0)
	s_barrier
	s_setprio 1
	s_waitcnt lgkmcnt(0)
	v_mfma_f32_16x16x32_bf16 v[126:129], v[130:133], v[172:175], v[126:129]
	v_mfma_f32_16x16x32_bf16 v[122:125], v[138:141], v[172:175], v[122:125]
	v_mfma_f32_16x16x32_bf16 v[110:113], v[130:133], v[186:189], v[110:113]
	v_mfma_f32_16x16x32_bf16 v[106:109], v[138:141], v[186:189], v[106:109]
	v_mfma_f32_16x16x32_bf16 v[94:97], v[130:133], v[204:207], v[94:97]
	v_mfma_f32_16x16x32_bf16 v[90:93], v[138:141], v[204:207], v[90:93]
	v_mfma_f32_16x16x32_bf16 v[78:81], v[130:133], v[212:215], v[78:81]
	v_mfma_f32_16x16x32_bf16 v[74:77], v[138:141], v[212:215], v[74:77]
	v_mfma_f32_16x16x32_bf16 v[126:129], v[134:137], v[182:185], v[126:129]
	v_mfma_f32_16x16x32_bf16 v[122:125], v[142:145], v[182:185], v[122:125]
	v_mfma_f32_16x16x32_bf16 v[110:113], v[134:137], v[190:193], v[110:113]
	v_mfma_f32_16x16x32_bf16 v[106:109], v[142:145], v[190:193], v[106:109]
	v_mfma_f32_16x16x32_bf16 v[94:97], v[134:137], v[208:211], v[94:97]
	v_mfma_f32_16x16x32_bf16 v[90:93], v[142:145], v[208:211], v[90:93]
	v_mfma_f32_16x16x32_bf16 v[78:81], v[134:137], v[216:219], v[78:81]
	v_mfma_f32_16x16x32_bf16 v[74:77], v[142:145], v[216:219], v[74:77]
	s_setprio 0
	s_setprio 1
	v_mfma_f32_16x16x32_bf16 v[118:121], v[146:149], v[172:175], v[118:121]
	v_mfma_f32_16x16x32_bf16 v[114:117], v[164:167], v[172:175], v[114:117]
	v_mfma_f32_16x16x32_bf16 v[102:105], v[146:149], v[186:189], v[102:105]
	v_mfma_f32_16x16x32_bf16 v[98:101], v[164:167], v[186:189], v[98:101]
	v_mfma_f32_16x16x32_bf16 v[86:89], v[146:149], v[204:207], v[86:89]
	v_mfma_f32_16x16x32_bf16 v[82:85], v[164:167], v[204:207], v[82:85]
	v_mfma_f32_16x16x32_bf16 v[70:73], v[146:149], v[212:215], v[70:73]
	v_mfma_f32_16x16x32_bf16 v[66:69], v[164:167], v[212:215], v[66:69]
	v_mfma_f32_16x16x32_bf16 v[118:121], v[150:153], v[182:185], v[118:121]
	v_mfma_f32_16x16x32_bf16 v[114:117], v[168:171], v[182:185], v[114:117]
	v_mfma_f32_16x16x32_bf16 v[102:105], v[150:153], v[190:193], v[102:105]
	v_mfma_f32_16x16x32_bf16 v[98:101], v[168:171], v[190:193], v[98:101]
	v_mfma_f32_16x16x32_bf16 v[86:89], v[150:153], v[208:211], v[86:89]
	v_mfma_f32_16x16x32_bf16 v[82:85], v[168:171], v[208:211], v[82:85]
	v_mfma_f32_16x16x32_bf16 v[70:73], v[150:153], v[216:219], v[70:73]
	v_mfma_f32_16x16x32_bf16 v[66:69], v[168:171], v[216:219], v[66:69]
	s_setprio 0
	s_barrier
	s_add_i32 s29, s29, s15
	s_mov_b32 m0, s29
	ds_read_b128 v[172:175], v181 offset:16384
	ds_read_b128 v[182:185], v181 offset:17408
	ds_read_b128 v[186:189], v181 offset:18432
	ds_read_b128 v[190:193], v181 offset:19456
	ds_read_b128 v[204:207], v181 offset:20480
	ds_read_b128 v[208:211], v181 offset:21504
	ds_read_b128 v[212:215], v181 offset:22528
	ds_read_b128 v[216:219], v181 offset:23552
	global_load_lds_dwordx4 v0, s[20:21]
	s_add_i32 m0, s29, 0x2000
	s_add_u32 s54, s20, 0x40000
	s_addc_u32 s55, s21, 0
	s_add_i32 s29, s30, s15
	global_load_lds_dwordx4 v158, s[20:21]
	s_mov_b32 m0, s29
	s_nop 0
	global_load_lds_dwordx4 v0, s[54:55]
	s_add_i32 m0, s29, 0x2000
	s_nop 0
	global_load_lds_dwordx4 v158, s[54:55]
	s_mov_b32 m0, s43
	s_nop 0
	global_load_lds_dwordx4 v154, s[72:73]
	s_mov_b32 m0, s44
	s_nop 0
	global_load_lds_dwordx4 v156, s[72:73]
	s_waitcnt vmcnt(8)
	s_waitcnt lgkmcnt(0)
	s_barrier
	s_setprio 1
	s_waitcnt lgkmcnt(0)
	v_mfma_f32_16x16x32_bf16 v[62:65], v[130:133], v[172:175], v[62:65]
	v_mfma_f32_16x16x32_bf16 v[58:61], v[138:141], v[172:175], v[58:61]
	v_mfma_f32_16x16x32_bf16 v[46:49], v[130:133], v[186:189], v[46:49]
	v_mfma_f32_16x16x32_bf16 v[42:45], v[138:141], v[186:189], v[42:45]
	v_mfma_f32_16x16x32_bf16 v[30:33], v[130:133], v[204:207], v[30:33]
	v_mfma_f32_16x16x32_bf16 v[26:29], v[138:141], v[204:207], v[26:29]
	v_mfma_f32_16x16x32_bf16 v[14:17], v[130:133], v[212:215], v[14:17]
	v_mfma_f32_16x16x32_bf16 v[10:13], v[138:141], v[212:215], v[10:13]
	v_mfma_f32_16x16x32_bf16 v[62:65], v[134:137], v[182:185], v[62:65]
	v_mfma_f32_16x16x32_bf16 v[58:61], v[142:145], v[182:185], v[58:61]
	v_mfma_f32_16x16x32_bf16 v[46:49], v[134:137], v[190:193], v[46:49]
	v_mfma_f32_16x16x32_bf16 v[42:45], v[142:145], v[190:193], v[42:45]
	v_mfma_f32_16x16x32_bf16 v[30:33], v[134:137], v[208:211], v[30:33]
	v_mfma_f32_16x16x32_bf16 v[26:29], v[142:145], v[208:211], v[26:29]
	v_mfma_f32_16x16x32_bf16 v[14:17], v[134:137], v[216:219], v[14:17]
	v_mfma_f32_16x16x32_bf16 v[10:13], v[142:145], v[216:219], v[10:13]
	s_setprio 0
	s_setprio 1
	v_mfma_f32_16x16x32_bf16 v[54:57], v[146:149], v[172:175], v[54:57]
	v_mfma_f32_16x16x32_bf16 v[50:53], v[164:167], v[172:175], v[50:53]
	v_mfma_f32_16x16x32_bf16 v[38:41], v[146:149], v[186:189], v[38:41]
	v_mfma_f32_16x16x32_bf16 v[34:37], v[164:167], v[186:189], v[34:37]
	v_mfma_f32_16x16x32_bf16 v[22:25], v[146:149], v[204:207], v[22:25]
	v_mfma_f32_16x16x32_bf16 v[18:21], v[164:167], v[204:207], v[18:21]
	v_mfma_f32_16x16x32_bf16 v[6:9], v[146:149], v[212:215], v[6:9]
	v_mfma_f32_16x16x32_bf16 v[2:5], v[164:167], v[212:215], v[2:5]
	v_mfma_f32_16x16x32_bf16 v[54:57], v[150:153], v[182:185], v[54:57]
	v_mfma_f32_16x16x32_bf16 v[50:53], v[168:171], v[182:185], v[50:53]
	v_mfma_f32_16x16x32_bf16 v[38:41], v[150:153], v[190:193], v[38:41]
	v_mfma_f32_16x16x32_bf16 v[34:37], v[168:171], v[190:193], v[34:37]
	v_mfma_f32_16x16x32_bf16 v[22:25], v[150:153], v[208:211], v[22:25]
	v_mfma_f32_16x16x32_bf16 v[18:21], v[168:171], v[208:211], v[18:21]
	v_mfma_f32_16x16x32_bf16 v[6:9], v[150:153], v[216:219], v[6:9]
	v_mfma_f32_16x16x32_bf16 v[2:5], v[168:171], v[216:219], v[2:5]
	s_setprio 0
	s_barrier
; #define PG8_STAGE(bufoff, gbase, voff) do { _Pragma("unroll") for (int _i = 0; _i < 2; ++_i) \
;         __builtin_amdgcn_global_load_lds((const gunsigned*)((const gchar*)(gbase) + (voff)[_i]), (LAS unsigned*)(lds + (bufoff) + ldsw + _i * 8192), 16, 0, 0); } while (0)
; #define PG8_LDA(dst, b, h) do { _Pragma("unroll") for (int m = 0; m < 4; ++m) _Pragma("unroll") for (int k = 0; k < 2; ++k) dst[m][k] = *(const LAS bf16x8*)(lds + PG8_SA(b, h) + aoff + m * 2048 + k * 1024); } while (0)
; #define PG8_LDB(dst, b, h) do { _Pragma("unroll") for (int n = 0; n < 2; ++n) _Pragma("unroll") for (int k = 0; k < 2; ++k) dst[n][k] = *(const LAS bf16x8*)(lds + PG8_SB(b, h) + boff + n * 2048 + k * 1024); } while (0)
; #define PG8_WAIT_V(n) asm volatile("s_waitcnt vmcnt(" #n ")" ::: "memory")
; template <class Epi, class Sched>
; __device__ __forceinline__ void gemm_phase(LAS unsigned char* lds, const int tid, const Gemm g, const Sched& S, const Epi& E) {
;     ...
;         for (int t = 0; t < nt; t += 2) {
;             const bool last = (t == nt - 2);
;             const gchar* a1 = cA + (size_t)(t + 1) * kstep;
;             const gchar* a2 = last ? nA : cA + (size_t)(t + 2) * kstep; const gchar* b2 = last ? nB : cB + (size_t)(t + 2) * kstep;
;             const gchar* a3 = a2 + kstep; const gchar* b3 = b2 + kstep;
;             PG8_LDB(B0, 0, 0); PG8_LDB(B1, 0, 1); PG8_SCHED; PG8_LDA(At, 0, 0); PG8_STAGE(PG8_SA(1, 1), a1 + hstep, voffA);
;             PG8_WAIT_V(8); PG8_WAIT_L(0); PG8_BAR; PG8_MMA(0, 0, At, B0); PG8_MMA(0, 1, At, B1); PG8_BAR; PG8_SCHED;
;             PG8_LDA(At, 0, 1); PG8_STAGE(PG8_SB(0, 0), b2, voffB); PG8_STAGE(PG8_SB(0, 1), b2 + hstep, voffB); PG8_STAGE(PG8_SA(0, 0), a2, voffA);
;             PG8_WAIT_V(8); PG8_WAIT_L(0); PG8_BAR; PG8_MMA(1, 0, At, B0); PG8_MMA(1, 1, At, B1); PG8_BAR; PG8_SCHED;
;             PG8_LDB(B0, 1, 0); PG8_LDB(B1, 1, 1); PG8_SCHED; PG8_LDA(At, 1, 0); PG8_STAGE(PG8_SA(0, 1), a2 + hstep, voffA);
;             PG8_WAIT_V(8); PG8_WAIT_L(0); PG8_BAR; PG8_MMA(0, 0, At, B0); PG8_MMA(0, 1, At, B1); PG8_BAR; PG8_SCHED;
;             PG8_LDA(At, 1, 1); PG8_STAGE(PG8_SB(1, 0), b3, voffB); PG8_STAGE(PG8_SB(1, 1), b3 + hstep, voffB); PG8_STAGE(PG8_SA(1, 0), a3, voffA);
;             PG8_WAIT_V(8); PG8_WAIT_L(0); PG8_BAR; PG8_MMA(1, 0, At, B0); PG8_MMA(1, 1, At, B1); PG8_BAR; PG8_SCHED;
;         }
	s_add_i32 s29, 0, 0x18000
	s_add_i32 s30, 0, 0x1c000
	v_add_u32_e32 v142, s29, v177
	v_add_u32_e32 v168, s30, v177
	ds_read_b128 v[130:133], v142
	ds_read_b128 v[134:137], v142 offset:1024
	ds_read_b128 v[138:141], v142 offset:2048
	ds_read_b128 v[142:145], v142 offset:3072
	ds_read_b128 v[146:149], v168
	ds_read_b128 v[150:153], v168 offset:1024
	ds_read_b128 v[164:167], v168 offset:2048
	ds_read_b128 v[168:171], v168 offset:3072
	s_add_u32 s54, s72, 0x40000
	s_addc_u32 s55, s73, 0
	s_mov_b32 m0, s45
	ds_read_b128 v[172:175], v181 offset:32768
	ds_read_b128 v[182:185], v181 offset:33792
	ds_read_b128 v[186:189], v181 offset:34816
	ds_read_b128 v[190:193], v181 offset:35840
	ds_read_b128 v[204:207], v181 offset:36864
	ds_read_b128 v[208:211], v181 offset:37888
	ds_read_b128 v[212:215], v181 offset:38912
	ds_read_b128 v[216:219], v181 offset:39936
	global_load_lds_dwordx4 v154, s[54:55]
	s_mov_b32 m0, s46
	s_nop 0
	global_load_lds_dwordx4 v156, s[54:55]
	s_waitcnt vmcnt(8)
	s_waitcnt lgkmcnt(0)
	s_barrier
	s_setprio 1
	s_waitcnt lgkmcnt(0)
	v_mfma_f32_16x16x32_bf16 v[126:129], v[130:133], v[172:175], v[126:129]
	v_mfma_f32_16x16x32_bf16 v[122:125], v[138:141], v[172:175], v[122:125]
	v_mfma_f32_16x16x32_bf16 v[110:113], v[130:133], v[186:189], v[110:113]
	v_mfma_f32_16x16x32_bf16 v[106:109], v[138:141], v[186:189], v[106:109]
	v_mfma_f32_16x16x32_bf16 v[94:97], v[130:133], v[204:207], v[94:97]
	v_mfma_f32_16x16x32_bf16 v[90:93], v[138:141], v[204:207], v[90:93]
	v_mfma_f32_16x16x32_bf16 v[78:81], v[130:133], v[212:215], v[78:81]
	v_mfma_f32_16x16x32_bf16 v[74:77], v[138:141], v[212:215], v[74:77]
	v_mfma_f32_16x16x32_bf16 v[126:129], v[134:137], v[182:185], v[126:129]
	v_mfma_f32_16x16x32_bf16 v[122:125], v[142:145], v[182:185], v[122:125]
	v_mfma_f32_16x16x32_bf16 v[110:113], v[134:137], v[190:193], v[110:113]
	v_mfma_f32_16x16x32_bf16 v[106:109], v[142:145], v[190:193], v[106:109]
	v_mfma_f32_16x16x32_bf16 v[94:97], v[134:137], v[208:211], v[94:97]
	v_mfma_f32_16x16x32_bf16 v[90:93], v[142:145], v[208:211], v[90:93]
	v_mfma_f32_16x16x32_bf16 v[78:81], v[134:137], v[216:219], v[78:81]
	v_mfma_f32_16x16x32_bf16 v[74:77], v[142:145], v[216:219], v[74:77]
	s_setprio 0
	s_setprio 1
	v_mfma_f32_16x16x32_bf16 v[118:121], v[146:149], v[172:175], v[118:121]
	v_mfma_f32_16x16x32_bf16 v[114:117], v[164:167], v[172:175], v[114:117]
	v_mfma_f32_16x16x32_bf16 v[102:105], v[146:149], v[186:189], v[102:105]
	v_mfma_f32_16x16x32_bf16 v[98:101], v[164:167], v[186:189], v[98:101]
	v_mfma_f32_16x16x32_bf16 v[86:89], v[146:149], v[204:207], v[86:89]
	v_mfma_f32_16x16x32_bf16 v[82:85], v[164:167], v[204:207], v[82:85]
	v_mfma_f32_16x16x32_bf16 v[70:73], v[146:149], v[212:215], v[70:73]
	v_mfma_f32_16x16x32_bf16 v[66:69], v[164:167], v[212:215], v[66:69]
	v_mfma_f32_16x16x32_bf16 v[118:121], v[150:153], v[182:185], v[118:121]
	v_mfma_f32_16x16x32_bf16 v[114:117], v[168:171], v[182:185], v[114:117]
	v_mfma_f32_16x16x32_bf16 v[102:105], v[150:153], v[190:193], v[102:105]
	v_mfma_f32_16x16x32_bf16 v[98:101], v[168:171], v[190:193], v[98:101]
	v_mfma_f32_16x16x32_bf16 v[86:89], v[150:153], v[208:211], v[86:89]
	v_mfma_f32_16x16x32_bf16 v[82:85], v[168:171], v[208:211], v[82:85]
	v_mfma_f32_16x16x32_bf16 v[70:73], v[150:153], v[216:219], v[70:73]
	v_mfma_f32_16x16x32_bf16 v[66:69], v[168:171], v[216:219], v[66:69]
	s_setprio 0
	s_barrier
; #define PG8_STAGE(bufoff, gbase, voff) do { _Pragma("unroll") for (int _i = 0; _i < 2; ++_i) \
;         __builtin_amdgcn_global_load_lds((const gunsigned*)((const gchar*)(gbase) + (voff)[_i]), (LAS unsigned*)(lds + (bufoff) + ldsw + _i * 8192), 16, 0, 0); } while (0)
; #define PG8_LDA(dst, b, h) do { _Pragma("unroll") for (int m = 0; m < 4; ++m) _Pragma("unroll") for (int k = 0; k < 2; ++k) dst[m][k] = *(const LAS bf16x8*)(lds + PG8_SA(b, h) + aoff + m * 2048 + k * 1024); } while (0)
; #define PG8_LDB(dst, b, h) do { _Pragma("unroll") for (int n = 0; n < 2; ++n) _Pragma("unroll") for (int k = 0; k < 2; ++k) dst[n][k] = *(const LAS bf16x8*)(lds + PG8_SB(b, h) + boff + n * 2048 + k * 1024); } while (0)
; template <class Epi, class Sched>
; __device__ __forceinline__ void gemm_phase(LAS unsigned char* lds, const int tid, const Gemm g, const Sched& S, const Epi& E) {
;     ...
;         for (int t = 0; t < nt; t += 2) {
;             const bool last = (t == nt - 2);
;             const gchar* a1 = cA + (size_t)(t + 1) * kstep;
;             const gchar* a2 = last ? nA : cA + (size_t)(t + 2) * kstep; const gchar* b2 = last ? nB : cB + (size_t)(t + 2) * kstep;
;             const gchar* a3 = a2 + kstep; const gchar* b3 = b2 + kstep;
;             PG8_LDB(B0, 0, 0); PG8_LDB(B1, 0, 1); PG8_SCHED; PG8_LDA(At, 0, 0); PG8_STAGE(PG8_SA(1, 1), a1 + hstep, voffA);
;             PG8_WAIT_V(8); PG8_WAIT_L(0); PG8_BAR; PG8_MMA(0, 0, At, B0); PG8_MMA(0, 1, At, B1); PG8_BAR; PG8_SCHED;
;             PG8_LDA(At, 0, 1); PG8_STAGE(PG8_SB(0, 0), b2, voffB); PG8_STAGE(PG8_SB(0, 1), b2 + hstep, voffB); PG8_STAGE(PG8_SA(0, 0), a2, voffA);
;             PG8_WAIT_V(8); PG8_WAIT_L(0); PG8_BAR; PG8_MMA(1, 0, At, B0); PG8_MMA(1, 1, At, B1); PG8_BAR; PG8_SCHED;
;             PG8_LDB(B0, 1, 0); PG8_LDB(B1, 1, 1); PG8_SCHED; PG8_LDA(At, 1, 0); PG8_STAGE(PG8_SA(0, 1), a2 + hstep, voffA);
;             PG8_WAIT_V(8); PG8_WAIT_L(0); PG8_BAR; PG8_MMA(0, 0, At, B0); PG8_MMA(0, 1, At, B1); PG8_BAR; PG8_SCHED;
;             PG8_LDA(At, 1, 1); PG8_STAGE(PG8_SB(1, 0), b3, voffB); PG8_STAGE(PG8_SB(1, 1), b3 + hstep, voffB); PG8_STAGE(PG8_SA(1, 0), a3, voffA);
;             PG8_WAIT_V(8); PG8_WAIT_L(0); PG8_BAR; PG8_MMA(1, 0, At, B0); PG8_MMA(1, 1, At, B1); PG8_BAR; PG8_SCHED;
;         }
;         if (wr == 0) PG8_BAR;
;         E(acc, cur, wr, wc, fr, fq, lds, tid);
	s_add_i32 s29, s29, s15
	s_mov_b32 m0, s29
	ds_read_b128 v[172:175], v181 offset:49152
	ds_read_b128 v[182:185], v181 offset:50176
	ds_read_b128 v[186:189], v181 offset:51200
	ds_read_b128 v[190:193], v181 offset:52224
	ds_read_b128 v[204:207], v181 offset:53248
	ds_read_b128 v[208:211], v181 offset:54272
	ds_read_b128 v[212:215], v181 offset:55296
	ds_read_b128 v[216:219], v181 offset:56320
	global_load_lds_dwordx4 v195, s[20:21]
	s_add_i32 m0, s29, 0x2000
	s_add_i32 s29, s30, s15
	global_load_lds_dwordx4 v201, s[20:21]
	s_add_u32 s20, s20, 0x40080
	s_addc_u32 s21, s21, 0
	s_mov_b32 m0, s29
	s_nop 0
	global_load_lds_dwordx4 v0, s[20:21]
	s_add_i32 m0, s29, 0x2000
	s_nop 0
	global_load_lds_dwordx4 v158, s[20:21]
	s_mov_b32 m0, s12
	s_nop 0
	global_load_lds_dwordx4 v221, s[72:73]
	s_mov_b32 m0, s47
	s_nop 0
	global_load_lds_dwordx4 v223, s[72:73]
	s_waitcnt vmcnt(8)
	s_waitcnt lgkmcnt(0)
	s_barrier
	s_setprio 1
	s_waitcnt lgkmcnt(0)
	v_mfma_f32_16x16x32_bf16 v[62:65], v[130:133], v[172:175], v[62:65]
	v_mfma_f32_16x16x32_bf16 v[58:61], v[138:141], v[172:175], v[58:61]
	v_mfma_f32_16x16x32_bf16 v[46:49], v[130:133], v[186:189], v[46:49]
	v_mfma_f32_16x16x32_bf16 v[42:45], v[138:141], v[186:189], v[42:45]
	v_mfma_f32_16x16x32_bf16 v[30:33], v[130:133], v[204:207], v[30:33]
	v_mfma_f32_16x16x32_bf16 v[26:29], v[138:141], v[204:207], v[26:29]
	v_mfma_f32_16x16x32_bf16 v[14:17], v[130:133], v[212:215], v[14:17]
	v_mfma_f32_16x16x32_bf16 v[10:13], v[138:141], v[212:215], v[10:13]
	v_mfma_f32_16x16x32_bf16 v[62:65], v[134:137], v[182:185], v[62:65]
	v_mfma_f32_16x16x32_bf16 v[58:61], v[142:145], v[182:185], v[58:61]
	v_mfma_f32_16x16x32_bf16 v[46:49], v[134:137], v[190:193], v[46:49]
	v_mfma_f32_16x16x32_bf16 v[42:45], v[142:145], v[190:193], v[42:45]
	v_mfma_f32_16x16x32_bf16 v[30:33], v[134:137], v[208:211], v[30:33]
	v_mfma_f32_16x16x32_bf16 v[26:29], v[142:145], v[208:211], v[26:29]
	v_mfma_f32_16x16x32_bf16 v[14:17], v[134:137], v[216:219], v[14:17]
	v_mfma_f32_16x16x32_bf16 v[10:13], v[142:145], v[216:219], v[10:13]
	s_setprio 0
	s_setprio 1
	v_mfma_f32_16x16x32_bf16 v[54:57], v[146:149], v[172:175], v[54:57]
	v_mfma_f32_16x16x32_bf16 v[50:53], v[164:167], v[172:175], v[50:53]
	v_mfma_f32_16x16x32_bf16 v[38:41], v[146:149], v[186:189], v[38:41]
	v_mfma_f32_16x16x32_bf16 v[34:37], v[164:167], v[186:189], v[34:37]
	v_mfma_f32_16x16x32_bf16 v[22:25], v[146:149], v[204:207], v[22:25]
	v_mfma_f32_16x16x32_bf16 v[18:21], v[164:167], v[204:207], v[18:21]
	v_mfma_f32_16x16x32_bf16 v[6:9], v[146:149], v[212:215], v[6:9]
	v_mfma_f32_16x16x32_bf16 v[2:5], v[164:167], v[212:215], v[2:5]
	v_mfma_f32_16x16x32_bf16 v[54:57], v[150:153], v[182:185], v[54:57]
	v_mfma_f32_16x16x32_bf16 v[50:53], v[168:171], v[182:185], v[50:53]
	v_mfma_f32_16x16x32_bf16 v[38:41], v[150:153], v[190:193], v[38:41]
	v_mfma_f32_16x16x32_bf16 v[34:37], v[168:171], v[190:193], v[34:37]
	v_mfma_f32_16x16x32_bf16 v[22:25], v[150:153], v[208:211], v[22:25]
	v_mfma_f32_16x16x32_bf16 v[18:21], v[168:171], v[208:211], v[18:21]
	v_mfma_f32_16x16x32_bf16 v[6:9], v[150:153], v[216:219], v[6:9]
	v_mfma_f32_16x16x32_bf16 v[2:5], v[168:171], v[216:219], v[2:5]
	s_add_i32 s53, s53, 2
	s_add_u32 s51, s51, 0x100
	s_addc_u32 s52, s52, 0
	s_add_u32 s92, s92, 0x100
	s_addc_u32 s93, s93, 0
	s_cmp_gt_u32 s53, 13
	s_cbranch_scc1 .Lrot_exit_397
	s_add_u32 s20, s92, 0xfffc0080
	s_addc_u32 s21, s93, -1
	s_add_i32 s29, 0, 0x10000
	s_cmp_eq_u32 s53, 12
	s_cselect_b32 s73, s1, s21
	s_cselect_b32 s72, s31, s20
	s_cselect_b32 s21, s17, s52
	s_cselect_b32 s20, s50, s51
	s_add_i32 s30, 0, 0x14000
	v_add_u32_e32 v142, s29, v177
	v_add_u32_e32 v168, s30, v177
	s_setprio 0
	s_barrier
	s_branch .Lrot_397
.Lrot_exit_397:
	s_setprio 0
	s_barrier
	s_and_b64 vcc, exec, s[10:11]
	s_cbranch_vccz .LBB0_400
	s_barrier

; #define PG8_STAGE(bufoff, gbase, voff) do { _Pragma("unroll") for (int _i = 0; _i < 2; ++_i) \
;         __builtin_amdgcn_global_load_lds((const gunsigned*)((const gchar*)(gbase) + (voff)[_i]), (LAS unsigned*)(lds + (bufoff) + ldsw + _i * 8192), 16, 0, 0); } while (0)
; #define PG8_LDA(dst, b, h) do { _Pragma("unroll") for (int m = 0; m < 4; ++m) _Pragma("unroll") for (int k = 0; k < 2; ++k) dst[m][k] = *(const LAS bf16x8*)(lds + PG8_SA(b, h) + aoff + m * 2048 + k * 1024); } while (0)
; #define PG8_LDB(dst, b, h) do { _Pragma("unroll") for (int n = 0; n < 2; ++n) _Pragma("unroll") for (int k = 0; k < 2; ++k) dst[n][k] = *(const LAS bf16x8*)(lds + PG8_SB(b, h) + boff + n * 2048 + k * 1024); } while (0)
; #define PG8_WAIT_V(n) asm volatile("s_waitcnt vmcnt(" #n ")" ::: "memory")
; template <class Epi, class Sched>
; __device__ __forceinline__ void gemm_phase(LAS unsigned char* lds, const int tid, const Gemm g, const Sched& S, const Epi& E) {
;     ...
;         for (int t = 0; t < nt; t += 2) {
;             const bool last = (t == nt - 2);
;             const gchar* a1 = cA + (size_t)(t + 1) * kstep;
;             const gchar* a2 = last ? nA : cA + (size_t)(t + 2) * kstep; const gchar* b2 = last ? nB : cB + (size_t)(t + 2) * kstep;
;             const gchar* a3 = a2 + kstep; const gchar* b3 = b2 + kstep;
;             PG8_LDB(B0, 0, 0); PG8_LDB(B1, 0, 1); PG8_SCHED; PG8_LDA(At, 0, 0); PG8_STAGE(PG8_SA(1, 1), a1 + hstep, voffA);
;             PG8_WAIT_V(8); PG8_WAIT_L(0); PG8_BAR; PG8_MMA(0, 0, At, B0); PG8_MMA(0, 1, At, B1); PG8_BAR; PG8_SCHED;
;             PG8_LDA(At, 0, 1); PG8_STAGE(PG8_SB(0, 0), b2, voffB); PG8_STAGE(PG8_SB(0, 1), b2 + hstep, voffB); PG8_STAGE(PG8_SA(0, 0), a2, voffA);
;             PG8_WAIT_V(8); PG8_WAIT_L(0); PG8_BAR; PG8_MMA(1, 0, At, B0); PG8_MMA(1, 1, At, B1); PG8_BAR; PG8_SCHED;
;             PG8_LDB(B0, 1, 0); PG8_LDB(B1, 1, 1); PG8_SCHED; PG8_LDA(At, 1, 0); PG8_STAGE(PG8_SA(0, 1), a2 + hstep, voffA);
;             PG8_WAIT_V(8); PG8_WAIT_L(0); PG8_BAR; PG8_MMA(0, 0, At, B0); PG8_MMA(0, 1, At, B1); PG8_BAR; PG8_SCHED;
;             PG8_LDA(At, 1, 1); PG8_STAGE(PG8_SB(1, 0), b3, voffB); PG8_STAGE(PG8_SB(1, 1), b3 + hstep, voffB); PG8_STAGE(PG8_SA(1, 0), a3, voffA);
;             PG8_WAIT_V(8); PG8_WAIT_L(0); PG8_BAR; PG8_MMA(1, 0, At, B0); PG8_MMA(1, 1, At, B1); PG8_BAR; PG8_SCHED;
;         }
.Lrot_444:
	ds_read_b128 v[132:135], v122
	ds_read_b128 v[136:139], v122 offset:1024
	ds_read_b128 v[140:143], v122 offset:2048
	ds_read_b128 v[144:147], v122 offset:3072
	v_add_u32_e32 v122, s30, v242
	ds_read_b128 v[148:151], v122
	ds_read_b128 v[152:155], v122 offset:1024
	ds_read_b128 v[156:159], v122 offset:2048
	ds_read_b128 v[160:163], v122 offset:3072
	s_add_i32 m0, s93, 0xc000
	ds_read_b128 v[164:167], v244
	ds_read_b128 v[168:171], v244 offset:1024
	ds_read_b128 v[172:175], v244 offset:2048
	ds_read_b128 v[176:179], v244 offset:3072
	ds_read_b128 v[180:183], v244 offset:4096
	ds_read_b128 v[184:187], v244 offset:5120
	ds_read_b128 v[188:191], v244 offset:6144
	ds_read_b128 v[192:195], v244 offset:7168
	global_load_lds_dwordx4 v212, s[16:17]
	s_add_i32 m0, s93, 0xe000
	s_nop 0
	global_load_lds_dwordx4 v210, s[16:17]
	s_waitcnt vmcnt(8)
	s_waitcnt lgkmcnt(0)
	s_barrier
	s_setprio 1
	s_waitcnt lgkmcnt(0)
	v_mfma_f32_16x16x32_bf16 v[128:131], v[132:135], v[164:167], v[128:131]
	v_mfma_f32_16x16x32_bf16 v[122:125], v[140:143], v[164:167], v[124:127]
	v_mfma_f32_16x16x32_bf16 v[110:113], v[132:135], v[172:175], v[110:113]
	v_mfma_f32_16x16x32_bf16 v[106:109], v[140:143], v[172:175], v[106:109]
	v_mfma_f32_16x16x32_bf16 v[94:97], v[132:135], v[180:183], v[94:97]
	v_mfma_f32_16x16x32_bf16 v[90:93], v[140:143], v[180:183], v[90:93]
	v_mfma_f32_16x16x32_bf16 v[78:81], v[132:135], v[188:191], v[78:81]
	v_mfma_f32_16x16x32_bf16 v[74:77], v[140:143], v[188:191], v[74:77]
	v_mfma_f32_16x16x32_bf16 v[128:131], v[136:139], v[168:171], v[128:131]
	v_mfma_f32_16x16x32_bf16 v[122:125], v[144:147], v[168:171], v[122:125]
	v_mfma_f32_16x16x32_bf16 v[110:113], v[136:139], v[176:179], v[110:113]
	v_mfma_f32_16x16x32_bf16 v[106:109], v[144:147], v[176:179], v[106:109]
	v_mfma_f32_16x16x32_bf16 v[94:97], v[136:139], v[184:187], v[94:97]
	v_mfma_f32_16x16x32_bf16 v[90:93], v[144:147], v[184:187], v[90:93]
	v_mfma_f32_16x16x32_bf16 v[78:81], v[136:139], v[192:195], v[78:81]
	v_mfma_f32_16x16x32_bf16 v[74:77], v[144:147], v[192:195], v[74:77]
	s_setprio 0
	s_setprio 1
	v_mfma_f32_16x16x32_bf16 v[118:121], v[148:151], v[164:167], v[118:121]
	v_mfma_f32_16x16x32_bf16 v[114:117], v[156:159], v[164:167], v[114:117]
	v_mfma_f32_16x16x32_bf16 v[102:105], v[148:151], v[172:175], v[102:105]
	v_mfma_f32_16x16x32_bf16 v[98:101], v[156:159], v[172:175], v[98:101]
	v_mfma_f32_16x16x32_bf16 v[86:89], v[148:151], v[180:183], v[86:89]
	v_mfma_f32_16x16x32_bf16 v[82:85], v[156:159], v[180:183], v[82:85]
	v_mfma_f32_16x16x32_bf16 v[70:73], v[148:151], v[188:191], v[70:73]
	v_mfma_f32_16x16x32_bf16 v[66:69], v[156:159], v[188:191], v[66:69]
	v_mfma_f32_16x16x32_bf16 v[118:121], v[152:155], v[168:171], v[118:121]
	v_mfma_f32_16x16x32_bf16 v[114:117], v[160:163], v[168:171], v[114:117]
	v_mfma_f32_16x16x32_bf16 v[102:105], v[152:155], v[176:179], v[102:105]
	v_mfma_f32_16x16x32_bf16 v[98:101], v[160:163], v[176:179], v[98:101]
	v_mfma_f32_16x16x32_bf16 v[86:89], v[152:155], v[184:187], v[86:89]
	v_mfma_f32_16x16x32_bf16 v[82:85], v[160:163], v[184:187], v[82:85]
	v_mfma_f32_16x16x32_bf16 v[70:73], v[152:155], v[192:195], v[70:73]
	v_mfma_f32_16x16x32_bf16 v[66:69], v[160:163], v[192:195], v[66:69]
	s_setprio 0
	s_barrier
	s_add_i32 s29, s29, s42
	s_mov_b32 m0, s29
	ds_read_b128 v[164:167], v244 offset:16384
	ds_read_b128 v[168:171], v244 offset:17408
	ds_read_b128 v[172:175], v244 offset:18432
	ds_read_b128 v[176:179], v244 offset:19456
	ds_read_b128 v[180:183], v244 offset:20480
	ds_read_b128 v[184:187], v244 offset:21504
	ds_read_b128 v[188:191], v244 offset:22528
	ds_read_b128 v[192:195], v244 offset:23552
	global_load_lds_dwordx4 v0, s[20:21]
	s_add_i32 m0, s29, 0x2000
	s_add_u32 s52, s20, 0x20000
	s_addc_u32 s53, s21, 0
	s_add_i32 s29, s30, s42
	global_load_lds_dwordx4 v208, s[20:21]
	s_mov_b32 m0, s29
	s_nop 0
	global_load_lds_dwordx4 v0, s[52:53]
	s_add_i32 m0, s29, 0x2000
	s_nop 0
	global_load_lds_dwordx4 v208, s[52:53]
	s_mov_b32 m0, s93
	s_nop 0
	global_load_lds_dwordx4 v204, s[72:73]
	s_mov_b32 m0, s44
	s_nop 0
	global_load_lds_dwordx4 v206, s[72:73]
	s_waitcnt vmcnt(8)
	s_waitcnt lgkmcnt(0)
	s_barrier
	s_setprio 1
	s_waitcnt lgkmcnt(0)
	v_mfma_f32_16x16x32_bf16 v[62:65], v[132:135], v[164:167], v[62:65]
	v_mfma_f32_16x16x32_bf16 v[58:61], v[140:143], v[164:167], v[58:61]
	v_mfma_f32_16x16x32_bf16 v[46:49], v[132:135], v[172:175], v[46:49]
	v_mfma_f32_16x16x32_bf16 v[42:45], v[140:143], v[172:175], v[42:45]
	v_mfma_f32_16x16x32_bf16 v[30:33], v[132:135], v[180:183], v[30:33]
	v_mfma_f32_16x16x32_bf16 v[26:29], v[140:143], v[180:183], v[26:29]
	v_mfma_f32_16x16x32_bf16 v[14:17], v[132:135], v[188:191], v[14:17]
	v_mfma_f32_16x16x32_bf16 v[10:13], v[140:143], v[188:191], v[10:13]
	v_mfma_f32_16x16x32_bf16 v[62:65], v[136:139], v[168:171], v[62:65]
	v_mfma_f32_16x16x32_bf16 v[58:61], v[144:147], v[168:171], v[58:61]
	v_mfma_f32_16x16x32_bf16 v[46:49], v[136:139], v[176:179], v[46:49]
	v_mfma_f32_16x16x32_bf16 v[42:45], v[144:147], v[176:179], v[42:45]
	v_mfma_f32_16x16x32_bf16 v[30:33], v[136:139], v[184:187], v[30:33]
	v_mfma_f32_16x16x32_bf16 v[26:29], v[144:147], v[184:187], v[26:29]
	v_mfma_f32_16x16x32_bf16 v[14:17], v[136:139], v[192:195], v[14:17]
	v_mfma_f32_16x16x32_bf16 v[10:13], v[144:147], v[192:195], v[10:13]
	s_setprio 0
	s_setprio 1
	v_mfma_f32_16x16x32_bf16 v[54:57], v[148:151], v[164:167], v[54:57]
	v_mfma_f32_16x16x32_bf16 v[50:53], v[156:159], v[164:167], v[50:53]
	v_mfma_f32_16x16x32_bf16 v[38:41], v[148:151], v[172:175], v[38:41]
	v_mfma_f32_16x16x32_bf16 v[34:37], v[156:159], v[172:175], v[34:37]
	v_mfma_f32_16x16x32_bf16 v[22:25], v[148:151], v[180:183], v[22:25]
	v_mfma_f32_16x16x32_bf16 v[18:21], v[156:159], v[180:183], v[18:21]
	v_mfma_f32_16x16x32_bf16 v[6:9], v[148:151], v[188:191], v[6:9]
	v_mfma_f32_16x16x32_bf16 v[2:5], v[156:159], v[188:191], v[2:5]
	v_mfma_f32_16x16x32_bf16 v[54:57], v[152:155], v[168:171], v[54:57]
	v_mfma_f32_16x16x32_bf16 v[50:53], v[160:163], v[168:171], v[50:53]
	v_mfma_f32_16x16x32_bf16 v[38:41], v[152:155], v[176:179], v[38:41]
	v_mfma_f32_16x16x32_bf16 v[34:37], v[160:163], v[176:179], v[34:37]
	v_mfma_f32_16x16x32_bf16 v[22:25], v[152:155], v[184:187], v[22:25]
	v_mfma_f32_16x16x32_bf16 v[18:21], v[160:163], v[184:187], v[18:21]
	v_mfma_f32_16x16x32_bf16 v[6:9], v[152:155], v[192:195], v[6:9]
	v_mfma_f32_16x16x32_bf16 v[2:5], v[160:163], v[192:195], v[2:5]
	s_setprio 0
	s_barrier
; #define PG8_STAGE(bufoff, gbase, voff) do { _Pragma("unroll") for (int _i = 0; _i < 2; ++_i) \
;         __builtin_amdgcn_global_load_lds((const gunsigned*)((const gchar*)(gbase) + (voff)[_i]), (LAS unsigned*)(lds + (bufoff) + ldsw + _i * 8192), 16, 0, 0); } while (0)
; #define PG8_LDA(dst, b, h) do { _Pragma("unroll") for (int m = 0; m < 4; ++m) _Pragma("unroll") for (int k = 0; k < 2; ++k) dst[m][k] = *(const LAS bf16x8*)(lds + PG8_SA(b, h) + aoff + m * 2048 + k * 1024); } while (0)
; #define PG8_LDB(dst, b, h) do { _Pragma("unroll") for (int n = 0; n < 2; ++n) _Pragma("unroll") for (int k = 0; k < 2; ++k) dst[n][k] = *(const LAS bf16x8*)(lds + PG8_SB(b, h) + boff + n * 2048 + k * 1024); } while (0)
; #define PG8_WAIT_V(n) asm volatile("s_waitcnt vmcnt(" #n ")" ::: "memory")
; #define PG8_BAR __builtin_amdgcn_s_barrier()
; template <class Epi, class Sched>
; __device__ __forceinline__ void gemm_phase(LAS unsigned char* lds, const int tid, const Gemm g, const Sched& S, const Epi& E) {
;     ...
;         for (int t = 0; t < nt; t += 2) {
;             const bool last = (t == nt - 2);
;             const gchar* a1 = cA + (size_t)(t + 1) * kstep;
;             const gchar* a2 = last ? nA : cA + (size_t)(t + 2) * kstep; const gchar* b2 = last ? nB : cB + (size_t)(t + 2) * kstep;
;             const gchar* a3 = a2 + kstep; const gchar* b3 = b2 + kstep;
;             PG8_LDB(B0, 0, 0); PG8_LDB(B1, 0, 1); PG8_SCHED; PG8_LDA(At, 0, 0); PG8_STAGE(PG8_SA(1, 1), a1 + hstep, voffA);
;             PG8_WAIT_V(8); PG8_WAIT_L(0); PG8_BAR; PG8_MMA(0, 0, At, B0); PG8_MMA(0, 1, At, B1); PG8_BAR; PG8_SCHED;
;             PG8_LDA(At, 0, 1); PG8_STAGE(PG8_SB(0, 0), b2, voffB); PG8_STAGE(PG8_SB(0, 1), b2 + hstep, voffB); PG8_STAGE(PG8_SA(0, 0), a2, voffA);
;             PG8_WAIT_V(8); PG8_WAIT_L(0); PG8_BAR; PG8_MMA(1, 0, At, B0); PG8_MMA(1, 1, At, B1); PG8_BAR; PG8_SCHED;
;             PG8_LDB(B0, 1, 0); PG8_LDB(B1, 1, 1); PG8_SCHED; PG8_LDA(At, 1, 0); PG8_STAGE(PG8_SA(0, 1), a2 + hstep, voffA);
;             PG8_WAIT_V(8); PG8_WAIT_L(0); PG8_BAR; PG8_MMA(0, 0, At, B0); PG8_MMA(0, 1, At, B1); PG8_BAR; PG8_SCHED;
;             PG8_LDA(At, 1, 1); PG8_STAGE(PG8_SB(1, 0), b3, voffB); PG8_STAGE(PG8_SB(1, 1), b3 + hstep, voffB); PG8_STAGE(PG8_SA(1, 0), a3, voffA);
;             PG8_WAIT_V(8); PG8_WAIT_L(0); PG8_BAR; PG8_MMA(1, 0, At, B0); PG8_MMA(1, 1, At, B1); PG8_BAR; PG8_SCHED;
	s_add_i32 s29, 0, 0x18000
	v_add_u32_e32 v126, s29, v242
	s_add_i32 s30, 0, 0x1c000
	ds_read_b128 v[132:135], v126
	ds_read_b128 v[136:139], v126 offset:1024
	ds_read_b128 v[140:143], v126 offset:2048
	ds_read_b128 v[144:147], v126 offset:3072
	v_add_u32_e32 v126, s30, v242
	ds_read_b128 v[148:151], v126
	ds_read_b128 v[152:155], v126 offset:1024
	ds_read_b128 v[156:159], v126 offset:2048
	ds_read_b128 v[160:163], v126 offset:3072
	s_add_u32 s52, s72, 0x20000
	s_addc_u32 s53, s73, 0
	s_mov_b32 m0, s45
	ds_read_b128 v[164:167], v244 offset:32768
	ds_read_b128 v[168:171], v244 offset:33792
	ds_read_b128 v[172:175], v244 offset:34816
	ds_read_b128 v[176:179], v244 offset:35840
	ds_read_b128 v[180:183], v244 offset:36864
	ds_read_b128 v[184:187], v244 offset:37888
	ds_read_b128 v[188:191], v244 offset:38912
	ds_read_b128 v[192:195], v244 offset:39936
	global_load_lds_dwordx4 v204, s[52:53]
	s_mov_b32 m0, s46
	s_nop 0
	global_load_lds_dwordx4 v206, s[52:53]
	s_waitcnt vmcnt(8)
	s_waitcnt lgkmcnt(0)
	s_barrier
	s_setprio 1
	s_waitcnt lgkmcnt(0)
	v_mfma_f32_16x16x32_bf16 v[126:129], v[132:135], v[164:167], v[128:131]
	v_mfma_f32_16x16x32_bf16 v[122:125], v[140:143], v[164:167], v[122:125]
	v_mfma_f32_16x16x32_bf16 v[110:113], v[132:135], v[172:175], v[110:113]
	v_mfma_f32_16x16x32_bf16 v[106:109], v[140:143], v[172:175], v[106:109]
	v_mfma_f32_16x16x32_bf16 v[94:97], v[132:135], v[180:183], v[94:97]
	v_mfma_f32_16x16x32_bf16 v[90:93], v[140:143], v[180:183], v[90:93]
	v_mfma_f32_16x16x32_bf16 v[78:81], v[132:135], v[188:191], v[78:81]
	v_mfma_f32_16x16x32_bf16 v[74:77], v[140:143], v[188:191], v[74:77]
	v_mfma_f32_16x16x32_bf16 v[128:131], v[136:139], v[168:171], v[126:129]
	v_mfma_f32_16x16x32_bf16 v[124:127], v[144:147], v[168:171], v[122:125]
	v_mfma_f32_16x16x32_bf16 v[110:113], v[136:139], v[176:179], v[110:113]
	v_mfma_f32_16x16x32_bf16 v[106:109], v[144:147], v[176:179], v[106:109]
	v_mfma_f32_16x16x32_bf16 v[94:97], v[136:139], v[184:187], v[94:97]
	v_mfma_f32_16x16x32_bf16 v[90:93], v[144:147], v[184:187], v[90:93]
	v_mfma_f32_16x16x32_bf16 v[78:81], v[136:139], v[192:195], v[78:81]
	v_mfma_f32_16x16x32_bf16 v[74:77], v[144:147], v[192:195], v[74:77]
	s_setprio 0
	s_setprio 1
	v_mfma_f32_16x16x32_bf16 v[118:121], v[148:151], v[164:167], v[118:121]
	v_mfma_f32_16x16x32_bf16 v[114:117], v[156:159], v[164:167], v[114:117]
	v_mfma_f32_16x16x32_bf16 v[102:105], v[148:151], v[172:175], v[102:105]
	v_mfma_f32_16x16x32_bf16 v[98:101], v[156:159], v[172:175], v[98:101]
	v_mfma_f32_16x16x32_bf16 v[86:89], v[148:151], v[180:183], v[86:89]
	v_mfma_f32_16x16x32_bf16 v[82:85], v[156:159], v[180:183], v[82:85]
	v_mfma_f32_16x16x32_bf16 v[70:73], v[148:151], v[188:191], v[70:73]
	v_mfma_f32_16x16x32_bf16 v[66:69], v[156:159], v[188:191], v[66:69]
	v_mfma_f32_16x16x32_bf16 v[118:121], v[152:155], v[168:171], v[118:121]
	v_mfma_f32_16x16x32_bf16 v[114:117], v[160:163], v[168:171], v[114:117]
	v_mfma_f32_16x16x32_bf16 v[102:105], v[152:155], v[176:179], v[102:105]
	v_mfma_f32_16x16x32_bf16 v[98:101], v[160:163], v[176:179], v[98:101]
	v_mfma_f32_16x16x32_bf16 v[86:89], v[152:155], v[184:187], v[86:89]
	v_mfma_f32_16x16x32_bf16 v[82:85], v[160:163], v[184:187], v[82:85]
	v_mfma_f32_16x16x32_bf16 v[70:73], v[152:155], v[192:195], v[70:73]
	v_mfma_f32_16x16x32_bf16 v[66:69], v[160:163], v[192:195], v[66:69]
	s_setprio 0
	s_barrier
	s_add_i32 s29, s29, s42
	s_mov_b32 m0, s29
	ds_read_b128 v[164:167], v244 offset:49152
	ds_read_b128 v[168:171], v244 offset:50176
	ds_read_b128 v[172:175], v244 offset:51200
	ds_read_b128 v[176:179], v244 offset:52224
	ds_read_b128 v[180:183], v244 offset:53248
	ds_read_b128 v[184:187], v244 offset:54272
	ds_read_b128 v[188:191], v244 offset:55296
	ds_read_b128 v[192:195], v244 offset:56320
	global_load_lds_dwordx4 v201, s[20:21]
	s_add_i32 m0, s29, 0x2000
	s_add_i32 s29, s30, s42
	global_load_lds_dwordx4 v215, s[20:21]
	s_add_u32 s20, s20, 0x20080
	s_addc_u32 s21, s21, 0
	s_mov_b32 m0, s29
	s_nop 0
	global_load_lds_dwordx4 v0, s[20:21]
	s_add_i32 m0, s29, 0x2000
	s_nop 0
	global_load_lds_dwordx4 v208, s[20:21]
	s_mov_b32 m0, s47
	s_nop 0
	global_load_lds_dwordx4 v217, s[72:73]
	s_mov_b32 m0, s48
	s_nop 0
	global_load_lds_dwordx4 v219, s[72:73]
	s_waitcnt vmcnt(8)
	s_waitcnt lgkmcnt(0)
	s_barrier
	s_setprio 1
	s_waitcnt lgkmcnt(0)
	v_mfma_f32_16x16x32_bf16 v[62:65], v[132:135], v[164:167], v[62:65]
	v_mfma_f32_16x16x32_bf16 v[58:61], v[140:143], v[164:167], v[58:61]
	v_mfma_f32_16x16x32_bf16 v[46:49], v[132:135], v[172:175], v[46:49]
	v_mfma_f32_16x16x32_bf16 v[42:45], v[140:143], v[172:175], v[42:45]
	v_mfma_f32_16x16x32_bf16 v[30:33], v[132:135], v[180:183], v[30:33]
	v_mfma_f32_16x16x32_bf16 v[26:29], v[140:143], v[180:183], v[26:29]
	v_mfma_f32_16x16x32_bf16 v[14:17], v[132:135], v[188:191], v[14:17]
	v_mfma_f32_16x16x32_bf16 v[10:13], v[140:143], v[188:191], v[10:13]
	v_mfma_f32_16x16x32_bf16 v[62:65], v[136:139], v[168:171], v[62:65]
	v_mfma_f32_16x16x32_bf16 v[58:61], v[144:147], v[168:171], v[58:61]
	v_mfma_f32_16x16x32_bf16 v[46:49], v[136:139], v[176:179], v[46:49]
	v_mfma_f32_16x16x32_bf16 v[42:45], v[144:147], v[176:179], v[42:45]
	v_mfma_f32_16x16x32_bf16 v[30:33], v[136:139], v[184:187], v[30:33]
	v_mfma_f32_16x16x32_bf16 v[26:29], v[144:147], v[184:187], v[26:29]
	v_mfma_f32_16x16x32_bf16 v[14:17], v[136:139], v[192:195], v[14:17]
	v_mfma_f32_16x16x32_bf16 v[10:13], v[144:147], v[192:195], v[10:13]
	s_setprio 0
	s_setprio 1
	v_mfma_f32_16x16x32_bf16 v[54:57], v[148:151], v[164:167], v[54:57]
	v_mfma_f32_16x16x32_bf16 v[50:53], v[156:159], v[164:167], v[50:53]
	v_mfma_f32_16x16x32_bf16 v[38:41], v[148:151], v[172:175], v[38:41]
	v_mfma_f32_16x16x32_bf16 v[34:37], v[156:159], v[172:175], v[34:37]
	v_mfma_f32_16x16x32_bf16 v[22:25], v[148:151], v[180:183], v[22:25]
	v_mfma_f32_16x16x32_bf16 v[18:21], v[156:159], v[180:183], v[18:21]
	v_mfma_f32_16x16x32_bf16 v[6:9], v[148:151], v[188:191], v[6:9]
	v_mfma_f32_16x16x32_bf16 v[2:5], v[156:159], v[188:191], v[2:5]
	v_mfma_f32_16x16x32_bf16 v[54:57], v[152:155], v[168:171], v[54:57]
	v_mfma_f32_16x16x32_bf16 v[50:53], v[160:163], v[168:171], v[50:53]
	v_mfma_f32_16x16x32_bf16 v[38:41], v[152:155], v[176:179], v[38:41]
	v_mfma_f32_16x16x32_bf16 v[34:37], v[160:163], v[176:179], v[34:37]
	v_mfma_f32_16x16x32_bf16 v[22:25], v[152:155], v[184:187], v[22:25]
	v_mfma_f32_16x16x32_bf16 v[18:21], v[160:163], v[184:187], v[18:21]
	v_mfma_f32_16x16x32_bf16 v[6:9], v[152:155], v[192:195], v[6:9]
	v_mfma_f32_16x16x32_bf16 v[2:5], v[160:163], v[192:195], v[2:5]
	s_add_i32 s51, s51, 2
	s_add_u32 s24, s24, 0x100
	s_addc_u32 s31, s31, 0
	s_add_u32 s16, s16, 0x100
	s_addc_u32 s17, s17, 0
	s_cmp_gt_u32 s51, 5
	s_cbranch_scc1 .Lrot_exit_444
	s_add_u32 s20, s16, 0xfffe0080
	s_addc_u32 s21, s17, -1
	s_add_i32 s29, 0, 0x10000
	s_cmp_eq_u32 s51, 4
	s_cselect_b32 s73, s1, s21
	s_cselect_b32 s72, s5, s20
	v_add_u32_e32 v122, s29, v242
	s_cselect_b32 s21, s15, s31
	s_cselect_b32 s20, s23, s24
	s_add_i32 s30, 0, 0x14000
	s_setprio 0
	s_barrier
	s_branch .Lrot_444

; #define PG8_STAGE(bufoff, gbase, voff) do { _Pragma("unroll") for (int _i = 0; _i < 2; ++_i) \
;         __builtin_amdgcn_global_load_lds((const gunsigned*)((const gchar*)(gbase) + (voff)[_i]), (LAS unsigned*)(lds + (bufoff) + ldsw + _i * 8192), 16, 0, 0); } while (0)
; #define PG8_LDA(dst, b, h) do { _Pragma("unroll") for (int m = 0; m < 4; ++m) _Pragma("unroll") for (int k = 0; k < 2; ++k) dst[m][k] = *(const LAS bf16x8*)(lds + PG8_SA(b, h) + aoff + m * 2048 + k * 1024); } while (0)
; #define PG8_LDB(dst, b, h) do { _Pragma("unroll") for (int n = 0; n < 2; ++n) _Pragma("unroll") for (int k = 0; k < 2; ++k) dst[n][k] = *(const LAS bf16x8*)(lds + PG8_SB(b, h) + boff + n * 2048 + k * 1024); } while (0)
; #define PG8_MMA(ai, bj, At, Bt) do { __builtin_amdgcn_s_setprio(1); _Pragma("unroll") for (int m = 0; m < 4; ++m) _Pragma("unroll") for (int n = 0; n < 2; ++n) _Pragma("unroll") for (int k = 0; k < 2; ++k) \
;         acc[ai][bj][m][n] = __builtin_amdgcn_mfma_f32_16x16x32_bf16(Bt[n][k], At[m][k], acc[ai][bj][m][n], 0, 0, 0); __builtin_amdgcn_s_setprio(0); } while (0)
; #define PG8_WAIT_V(n) asm volatile("s_waitcnt vmcnt(" #n ")" ::: "memory")
; #define PG8_WAIT_L(n) asm volatile("s_waitcnt lgkmcnt(" #n ")" ::: "memory")
; #define PG8_BAR __builtin_amdgcn_s_barrier()
; #define PG8_SCHED __builtin_amdgcn_sched_barrier(0)
; template <class Epi, class Sched>
; __device__ __forceinline__ void gemm_phase(LAS unsigned char* lds, const int tid, const Gemm g, const Sched& S, const Epi& E) {
;     ...
;             PG8_LDB(B0, 0, 0); PG8_LDB(B1, 0, 1); PG8_SCHED; PG8_LDA(At, 0, 0); PG8_STAGE(PG8_SA(1, 1), a1 + hstep, voffA);
;             PG8_WAIT_V(8); PG8_WAIT_L(0); PG8_BAR; PG8_MMA(0, 0, At, B0); PG8_MMA(0, 1, At, B1); PG8_BAR; PG8_SCHED;
;             PG8_LDA(At, 0, 1); PG8_STAGE(PG8_SB(0, 0), b2, voffB); PG8_STAGE(PG8_SB(0, 1), b2 + hstep, voffB); PG8_STAGE(PG8_SA(0, 0), a2, voffA);
;             PG8_WAIT_V(8); PG8_WAIT_L(0); PG8_BAR; PG8_MMA(1, 0, At, B0); PG8_MMA(1, 1, At, B1); PG8_BAR; PG8_SCHED;
.Lrot_559:
	ds_read_b128 v[130:133], v152
	ds_read_b128 v[144:147], v152 offset:1024
	ds_read_b128 v[148:151], v152 offset:2048
	ds_read_b128 v[152:155], v152 offset:3072
	ds_read_b128 v[156:159], v160
	ds_read_b128 v[170:173], v160 offset:1024
	ds_read_b128 v[174:177], v160 offset:2048
	ds_read_b128 v[178:181], v160 offset:3072
	s_add_i32 m0, s34, 0xc000
	ds_read_b128 v[182:185], v169
	ds_read_b128 v[186:189], v169 offset:1024
	ds_read_b128 v[190:193], v169 offset:2048
	ds_read_b128 v[204:207], v169 offset:3072
	ds_read_b128 v[210:213], v169 offset:4096
	ds_read_b128 v[214:217], v169 offset:5120
	ds_read_b128 v[218:221], v169 offset:6144
	ds_read_b128 v[222:225], v169 offset:7168
	global_load_lds_dwordx4 v142, s[60:61]
	s_add_i32 m0, s34, 0xe000
	s_nop 0
	global_load_lds_dwordx4 v140, s[60:61]
	s_waitcnt vmcnt(8)
	s_waitcnt lgkmcnt(0)
	s_barrier
	s_setprio 1
	s_waitcnt lgkmcnt(0)
	v_mfma_f32_16x16x32_bf16 v[126:129], v[130:133], v[182:185], v[126:129]
	v_mfma_f32_16x16x32_bf16 v[122:125], v[148:151], v[182:185], v[122:125]
	v_mfma_f32_16x16x32_bf16 v[118:121], v[130:133], v[190:193], v[118:121]
	v_mfma_f32_16x16x32_bf16 v[110:113], v[148:151], v[190:193], v[110:113]
	v_mfma_f32_16x16x32_bf16 v[102:105], v[130:133], v[210:213], v[102:105]
	v_mfma_f32_16x16x32_bf16 v[94:97], v[148:151], v[210:213], v[94:97]
	v_mfma_f32_16x16x32_bf16 v[86:89], v[130:133], v[218:221], v[86:89]
	v_mfma_f32_16x16x32_bf16 v[78:81], v[148:151], v[218:221], v[78:81]
	v_mfma_f32_16x16x32_bf16 v[126:129], v[144:147], v[186:189], v[126:129]
	v_mfma_f32_16x16x32_bf16 v[122:125], v[152:155], v[186:189], v[122:125]
	v_mfma_f32_16x16x32_bf16 v[118:121], v[144:147], v[204:207], v[118:121]
	v_mfma_f32_16x16x32_bf16 v[110:113], v[152:155], v[204:207], v[110:113]
	v_mfma_f32_16x16x32_bf16 v[102:105], v[144:147], v[214:217], v[102:105]
	v_mfma_f32_16x16x32_bf16 v[94:97], v[152:155], v[214:217], v[94:97]
	v_mfma_f32_16x16x32_bf16 v[86:89], v[144:147], v[222:225], v[86:89]
	v_mfma_f32_16x16x32_bf16 v[78:81], v[152:155], v[222:225], v[78:81]
	s_setprio 0
	s_setprio 1
	v_mfma_f32_16x16x32_bf16 v[114:117], v[156:159], v[182:185], v[114:117]
	v_mfma_f32_16x16x32_bf16 v[106:109], v[174:177], v[182:185], v[106:109]
	v_mfma_f32_16x16x32_bf16 v[98:101], v[156:159], v[190:193], v[98:101]
	v_mfma_f32_16x16x32_bf16 v[90:93], v[174:177], v[190:193], v[90:93]
	v_mfma_f32_16x16x32_bf16 v[82:85], v[156:159], v[210:213], v[82:85]
	v_mfma_f32_16x16x32_bf16 v[74:77], v[174:177], v[210:213], v[74:77]
	v_mfma_f32_16x16x32_bf16 v[70:73], v[156:159], v[218:221], v[70:73]
	v_mfma_f32_16x16x32_bf16 v[66:69], v[174:177], v[218:221], v[66:69]
	v_mfma_f32_16x16x32_bf16 v[114:117], v[170:173], v[186:189], v[114:117]
	v_mfma_f32_16x16x32_bf16 v[106:109], v[178:181], v[186:189], v[106:109]
	v_mfma_f32_16x16x32_bf16 v[98:101], v[170:173], v[204:207], v[98:101]
	v_mfma_f32_16x16x32_bf16 v[90:93], v[178:181], v[204:207], v[90:93]
	v_mfma_f32_16x16x32_bf16 v[82:85], v[170:173], v[214:217], v[82:85]
	v_mfma_f32_16x16x32_bf16 v[74:77], v[178:181], v[214:217], v[74:77]
	v_mfma_f32_16x16x32_bf16 v[70:73], v[170:173], v[222:225], v[70:73]
	v_mfma_f32_16x16x32_bf16 v[66:69], v[178:181], v[222:225], v[66:69]
	s_setprio 0
	s_barrier
	s_add_i32 s29, s29, s12
	s_mov_b32 m0, s29
	ds_read_b128 v[182:185], v169 offset:16384
	ds_read_b128 v[186:189], v169 offset:17408
	ds_read_b128 v[190:193], v169 offset:18432
	ds_read_b128 v[204:207], v169 offset:19456
	ds_read_b128 v[210:213], v169 offset:20480
	ds_read_b128 v[214:217], v169 offset:21504
	ds_read_b128 v[218:221], v169 offset:22528
	ds_read_b128 v[222:225], v169 offset:23552
	global_load_lds_dwordx4 v0, s[20:21]
	s_add_i32 m0, s29, 0x2000
	s_add_u32 s48, s20, 0x40000
	s_addc_u32 s49, s21, 0
	s_add_i32 s29, s30, s12
	global_load_lds_dwordx4 v134, s[20:21]
	s_mov_b32 m0, s29
	s_nop 0
	global_load_lds_dwordx4 v0, s[48:49]
	s_add_i32 m0, s29, 0x2000
	s_nop 0
	global_load_lds_dwordx4 v134, s[48:49]
	s_mov_b32 m0, s34
	s_nop 0
	global_load_lds_dwordx4 v138, s[62:63]
	s_mov_b32 m0, s35
	s_nop 0
	global_load_lds_dwordx4 v136, s[62:63]
	s_waitcnt vmcnt(8)
	s_waitcnt lgkmcnt(0)
	s_barrier
	s_setprio 1
	s_waitcnt lgkmcnt(0)
	v_mfma_f32_16x16x32_bf16 v[62:65], v[130:133], v[182:185], v[62:65]
	v_mfma_f32_16x16x32_bf16 v[58:61], v[148:151], v[182:185], v[58:61]
	v_mfma_f32_16x16x32_bf16 v[54:57], v[130:133], v[190:193], v[54:57]
	v_mfma_f32_16x16x32_bf16 v[46:49], v[148:151], v[190:193], v[46:49]
	v_mfma_f32_16x16x32_bf16 v[38:41], v[130:133], v[210:213], v[38:41]
	v_mfma_f32_16x16x32_bf16 v[30:33], v[148:151], v[210:213], v[30:33]
	v_mfma_f32_16x16x32_bf16 v[22:25], v[130:133], v[218:221], v[22:25]
	v_mfma_f32_16x16x32_bf16 v[14:17], v[148:151], v[218:221], v[14:17]
	v_mfma_f32_16x16x32_bf16 v[62:65], v[144:147], v[186:189], v[62:65]
	v_mfma_f32_16x16x32_bf16 v[58:61], v[152:155], v[186:189], v[58:61]
	v_mfma_f32_16x16x32_bf16 v[54:57], v[144:147], v[204:207], v[54:57]
	v_mfma_f32_16x16x32_bf16 v[46:49], v[152:155], v[204:207], v[46:49]
	v_mfma_f32_16x16x32_bf16 v[38:41], v[144:147], v[214:217], v[38:41]
	v_mfma_f32_16x16x32_bf16 v[30:33], v[152:155], v[214:217], v[30:33]
	v_mfma_f32_16x16x32_bf16 v[22:25], v[144:147], v[222:225], v[22:25]
	v_mfma_f32_16x16x32_bf16 v[14:17], v[152:155], v[222:225], v[14:17]
	s_setprio 0
	s_setprio 1
	v_mfma_f32_16x16x32_bf16 v[50:53], v[156:159], v[182:185], v[50:53]
	v_mfma_f32_16x16x32_bf16 v[42:45], v[174:177], v[182:185], v[42:45]
	v_mfma_f32_16x16x32_bf16 v[34:37], v[156:159], v[190:193], v[34:37]
	v_mfma_f32_16x16x32_bf16 v[26:29], v[174:177], v[190:193], v[26:29]
	v_mfma_f32_16x16x32_bf16 v[18:21], v[156:159], v[210:213], v[18:21]
	v_mfma_f32_16x16x32_bf16 v[10:13], v[174:177], v[210:213], v[10:13]
	v_mfma_f32_16x16x32_bf16 v[6:9], v[156:159], v[218:221], v[6:9]
	v_mfma_f32_16x16x32_bf16 v[2:5], v[174:177], v[218:221], v[2:5]
	v_mfma_f32_16x16x32_bf16 v[50:53], v[170:173], v[186:189], v[50:53]
	v_mfma_f32_16x16x32_bf16 v[42:45], v[178:181], v[186:189], v[42:45]
	v_mfma_f32_16x16x32_bf16 v[34:37], v[170:173], v[204:207], v[34:37]
	v_mfma_f32_16x16x32_bf16 v[26:29], v[178:181], v[204:207], v[26:29]
	v_mfma_f32_16x16x32_bf16 v[18:21], v[170:173], v[214:217], v[18:21]
	v_mfma_f32_16x16x32_bf16 v[10:13], v[178:181], v[214:217], v[10:13]
	v_mfma_f32_16x16x32_bf16 v[6:9], v[170:173], v[222:225], v[6:9]
	v_mfma_f32_16x16x32_bf16 v[2:5], v[178:181], v[222:225], v[2:5]
	s_setprio 0
	s_barrier
; #define PG8_STAGE(bufoff, gbase, voff) do { _Pragma("unroll") for (int _i = 0; _i < 2; ++_i) \
;         __builtin_amdgcn_global_load_lds((const gunsigned*)((const gchar*)(gbase) + (voff)[_i]), (LAS unsigned*)(lds + (bufoff) + ldsw + _i * 8192), 16, 0, 0); } while (0)
; #define PG8_LDA(dst, b, h) do { _Pragma("unroll") for (int m = 0; m < 4; ++m) _Pragma("unroll") for (int k = 0; k < 2; ++k) dst[m][k] = *(const LAS bf16x8*)(lds + PG8_SA(b, h) + aoff + m * 2048 + k * 1024); } while (0)
; #define PG8_LDB(dst, b, h) do { _Pragma("unroll") for (int n = 0; n < 2; ++n) _Pragma("unroll") for (int k = 0; k < 2; ++k) dst[n][k] = *(const LAS bf16x8*)(lds + PG8_SB(b, h) + boff + n * 2048 + k * 1024); } while (0)
; #define PG8_MMA(ai, bj, At, Bt) do { __builtin_amdgcn_s_setprio(1); _Pragma("unroll") for (int m = 0; m < 4; ++m) _Pragma("unroll") for (int n = 0; n < 2; ++n) _Pragma("unroll") for (int k = 0; k < 2; ++k) \
;         acc[ai][bj][m][n] = __builtin_amdgcn_mfma_f32_16x16x32_bf16(Bt[n][k], At[m][k], acc[ai][bj][m][n], 0, 0, 0); __builtin_amdgcn_s_setprio(0); } while (0)
; #define PG8_WAIT_V(n) asm volatile("s_waitcnt vmcnt(" #n ")" ::: "memory")
; #define PG8_WAIT_L(n) asm volatile("s_waitcnt lgkmcnt(" #n ")" ::: "memory")
; #define PG8_BAR __builtin_amdgcn_s_barrier()
; #define PG8_SCHED __builtin_amdgcn_sched_barrier(0)
; template <class Epi, class Sched>
; __device__ __forceinline__ void gemm_phase(LAS unsigned char* lds, const int tid, const Gemm g, const Sched& S, const Epi& E) {
;     ...
;             PG8_LDB(B0, 1, 0); PG8_LDB(B1, 1, 1); PG8_SCHED; PG8_LDA(At, 1, 0); PG8_STAGE(PG8_SA(0, 1), a2 + hstep, voffA);
;             PG8_WAIT_V(8); PG8_WAIT_L(0); PG8_BAR; PG8_MMA(0, 0, At, B0); PG8_MMA(0, 1, At, B1); PG8_BAR; PG8_SCHED;
	s_add_i32 s29, 0, 0x18000
	s_add_i32 s30, 0, 0x1c000
	v_add_u32_e32 v152, s29, v165
	v_add_u32_e32 v162, s30, v165
	ds_read_b128 v[130:133], v152
	ds_read_b128 v[144:147], v152 offset:1024
	ds_read_b128 v[148:151], v152 offset:2048
	ds_read_b128 v[152:155], v152 offset:3072
	ds_read_b128 v[156:159], v162
	ds_read_b128 v[170:173], v162 offset:1024
	ds_read_b128 v[174:177], v162 offset:2048
	ds_read_b128 v[178:181], v162 offset:3072
	s_add_u32 s48, s62, 0x40000
	s_addc_u32 s49, s63, 0
	s_mov_b32 m0, s36
	ds_read_b128 v[182:185], v169 offset:32768
	ds_read_b128 v[186:189], v169 offset:33792
	ds_read_b128 v[190:193], v169 offset:34816
	ds_read_b128 v[204:207], v169 offset:35840
	ds_read_b128 v[210:213], v169 offset:36864
	ds_read_b128 v[214:217], v169 offset:37888
	ds_read_b128 v[218:221], v169 offset:38912
	ds_read_b128 v[222:225], v169 offset:39936
	global_load_lds_dwordx4 v138, s[48:49]
	s_mov_b32 m0, s37
	s_nop 0
	global_load_lds_dwordx4 v136, s[48:49]
	s_waitcnt vmcnt(8)
	s_waitcnt lgkmcnt(0)
	s_barrier
	s_setprio 1
	s_waitcnt lgkmcnt(0)
	v_mfma_f32_16x16x32_bf16 v[126:129], v[130:133], v[182:185], v[126:129]
	v_mfma_f32_16x16x32_bf16 v[122:125], v[148:151], v[182:185], v[122:125]
	v_mfma_f32_16x16x32_bf16 v[118:121], v[130:133], v[190:193], v[118:121]
	v_mfma_f32_16x16x32_bf16 v[110:113], v[148:151], v[190:193], v[110:113]
	v_mfma_f32_16x16x32_bf16 v[102:105], v[130:133], v[210:213], v[102:105]
	v_mfma_f32_16x16x32_bf16 v[94:97], v[148:151], v[210:213], v[94:97]
	v_mfma_f32_16x16x32_bf16 v[86:89], v[130:133], v[218:221], v[86:89]
	v_mfma_f32_16x16x32_bf16 v[78:81], v[148:151], v[218:221], v[78:81]
	v_mfma_f32_16x16x32_bf16 v[126:129], v[144:147], v[186:189], v[126:129]
	v_mfma_f32_16x16x32_bf16 v[122:125], v[152:155], v[186:189], v[122:125]
	v_mfma_f32_16x16x32_bf16 v[118:121], v[144:147], v[204:207], v[118:121]
	v_mfma_f32_16x16x32_bf16 v[110:113], v[152:155], v[204:207], v[110:113]
	v_mfma_f32_16x16x32_bf16 v[102:105], v[144:147], v[214:217], v[102:105]
	v_mfma_f32_16x16x32_bf16 v[94:97], v[152:155], v[214:217], v[94:97]
	v_mfma_f32_16x16x32_bf16 v[86:89], v[144:147], v[222:225], v[86:89]
	v_mfma_f32_16x16x32_bf16 v[78:81], v[152:155], v[222:225], v[78:81]
	s_setprio 0
	s_setprio 1
	v_mfma_f32_16x16x32_bf16 v[114:117], v[156:159], v[182:185], v[114:117]
	v_mfma_f32_16x16x32_bf16 v[106:109], v[174:177], v[182:185], v[106:109]
	v_mfma_f32_16x16x32_bf16 v[98:101], v[156:159], v[190:193], v[98:101]
	v_mfma_f32_16x16x32_bf16 v[90:93], v[174:177], v[190:193], v[90:93]
	v_mfma_f32_16x16x32_bf16 v[82:85], v[156:159], v[210:213], v[82:85]
	v_mfma_f32_16x16x32_bf16 v[74:77], v[174:177], v[210:213], v[74:77]
	v_mfma_f32_16x16x32_bf16 v[70:73], v[156:159], v[218:221], v[70:73]
	v_mfma_f32_16x16x32_bf16 v[66:69], v[174:177], v[218:221], v[66:69]
	v_mfma_f32_16x16x32_bf16 v[114:117], v[170:173], v[186:189], v[114:117]
	v_mfma_f32_16x16x32_bf16 v[106:109], v[178:181], v[186:189], v[106:109]
	v_mfma_f32_16x16x32_bf16 v[98:101], v[170:173], v[204:207], v[98:101]
	v_mfma_f32_16x16x32_bf16 v[90:93], v[178:181], v[204:207], v[90:93]
	v_mfma_f32_16x16x32_bf16 v[82:85], v[170:173], v[214:217], v[82:85]
	v_mfma_f32_16x16x32_bf16 v[74:77], v[178:181], v[214:217], v[74:77]
	v_mfma_f32_16x16x32_bf16 v[70:73], v[170:173], v[222:225], v[70:73]
	v_mfma_f32_16x16x32_bf16 v[66:69], v[178:181], v[222:225], v[66:69]
	s_setprio 0
	s_barrier
; #define PG8_STAGE(bufoff, gbase, voff) do { _Pragma("unroll") for (int _i = 0; _i < 2; ++_i) \
;         __builtin_amdgcn_global_load_lds((const gunsigned*)((const gchar*)(gbase) + (voff)[_i]), (LAS unsigned*)(lds + (bufoff) + ldsw + _i * 8192), 16, 0, 0); } while (0)
; #define PG8_LDA(dst, b, h) do { _Pragma("unroll") for (int m = 0; m < 4; ++m) _Pragma("unroll") for (int k = 0; k < 2; ++k) dst[m][k] = *(const LAS bf16x8*)(lds + PG8_SA(b, h) + aoff + m * 2048 + k * 1024); } while (0)
; #define PG8_MMA(ai, bj, At, Bt) do { __builtin_amdgcn_s_setprio(1); _Pragma("unroll") for (int m = 0; m < 4; ++m) _Pragma("unroll") for (int n = 0; n < 2; ++n) _Pragma("unroll") for (int k = 0; k < 2; ++k) \
;         acc[ai][bj][m][n] = __builtin_amdgcn_mfma_f32_16x16x32_bf16(Bt[n][k], At[m][k], acc[ai][bj][m][n], 0, 0, 0); __builtin_amdgcn_s_setprio(0); } while (0)
; #define PG8_WAIT_V(n) asm volatile("s_waitcnt vmcnt(" #n ")" ::: "memory")
; #define PG8_WAIT_L(n) asm volatile("s_waitcnt lgkmcnt(" #n ")" ::: "memory")
; #define PG8_BAR __builtin_amdgcn_s_barrier()
; #define PG8_SCHED __builtin_amdgcn_sched_barrier(0)
; template <class Epi, class Sched>
; __device__ __forceinline__ void gemm_phase(LAS unsigned char* lds, const int tid, const Gemm g, const Sched& S, const Epi& E) {
;     ...
;         for (int t = 0; t < nt; t += 2) {
;             const bool last = (t == nt - 2);
;             const gchar* a1 = cA + (size_t)(t + 1) * kstep;
;             const gchar* a2 = last ? nA : cA + (size_t)(t + 2) * kstep; const gchar* b2 = last ? nB : cB + (size_t)(t + 2) * kstep;
;     ...
;             PG8_LDA(At, 1, 1); PG8_STAGE(PG8_SB(1, 0), b3, voffB); PG8_STAGE(PG8_SB(1, 1), b3 + hstep, voffB); PG8_STAGE(PG8_SA(1, 0), a3, voffA);
;             PG8_WAIT_V(8); PG8_WAIT_L(0); PG8_BAR; PG8_MMA(1, 0, At, B0); PG8_MMA(1, 1, At, B1); PG8_BAR; PG8_SCHED;
	s_add_i32 s29, s29, s12
	s_mov_b32 m0, s29
	ds_read_b128 v[182:185], v169 offset:49152
	ds_read_b128 v[186:189], v169 offset:50176
	ds_read_b128 v[190:193], v169 offset:51200
	ds_read_b128 v[204:207], v169 offset:52224
	ds_read_b128 v[210:213], v169 offset:53248
	ds_read_b128 v[214:217], v169 offset:54272
	ds_read_b128 v[218:221], v169 offset:55296
	ds_read_b128 v[222:225], v169 offset:56320
	global_load_lds_dwordx4 v161, s[20:21]
	s_add_i32 m0, s29, 0x2000
	s_add_i32 s29, s30, s12
	global_load_lds_dwordx4 v195, s[20:21]
	s_add_u32 s20, s20, 0x40080
	s_addc_u32 s21, s21, 0
	s_mov_b32 m0, s29
	s_nop 0
	global_load_lds_dwordx4 v0, s[20:21]
	s_add_i32 m0, s29, 0x2000
	s_nop 0
	global_load_lds_dwordx4 v134, s[20:21]
	s_mov_b32 m0, s38
	s_nop 0
	global_load_lds_dwordx4 v201, s[62:63]
	s_mov_b32 m0, s39
	s_nop 0
	global_load_lds_dwordx4 v227, s[62:63]
	s_waitcnt vmcnt(8)
	s_waitcnt lgkmcnt(0)
	s_barrier
	s_setprio 1
	s_waitcnt lgkmcnt(0)
	v_mfma_f32_16x16x32_bf16 v[62:65], v[130:133], v[182:185], v[62:65]
	v_mfma_f32_16x16x32_bf16 v[58:61], v[148:151], v[182:185], v[58:61]
	v_mfma_f32_16x16x32_bf16 v[54:57], v[130:133], v[190:193], v[54:57]
	v_mfma_f32_16x16x32_bf16 v[46:49], v[148:151], v[190:193], v[46:49]
	v_mfma_f32_16x16x32_bf16 v[38:41], v[130:133], v[210:213], v[38:41]
	v_mfma_f32_16x16x32_bf16 v[30:33], v[148:151], v[210:213], v[30:33]
	v_mfma_f32_16x16x32_bf16 v[22:25], v[130:133], v[218:221], v[22:25]
	v_mfma_f32_16x16x32_bf16 v[14:17], v[148:151], v[218:221], v[14:17]
	v_mfma_f32_16x16x32_bf16 v[62:65], v[144:147], v[186:189], v[62:65]
	v_mfma_f32_16x16x32_bf16 v[58:61], v[152:155], v[186:189], v[58:61]
	v_mfma_f32_16x16x32_bf16 v[54:57], v[144:147], v[204:207], v[54:57]
	v_mfma_f32_16x16x32_bf16 v[46:49], v[152:155], v[204:207], v[46:49]
	v_mfma_f32_16x16x32_bf16 v[38:41], v[144:147], v[214:217], v[38:41]
	v_mfma_f32_16x16x32_bf16 v[30:33], v[152:155], v[214:217], v[30:33]
	v_mfma_f32_16x16x32_bf16 v[22:25], v[144:147], v[222:225], v[22:25]
	v_mfma_f32_16x16x32_bf16 v[14:17], v[152:155], v[222:225], v[14:17]
	s_setprio 0
	s_setprio 1
	v_mfma_f32_16x16x32_bf16 v[50:53], v[156:159], v[182:185], v[50:53]
	v_mfma_f32_16x16x32_bf16 v[42:45], v[174:177], v[182:185], v[42:45]
	v_mfma_f32_16x16x32_bf16 v[34:37], v[156:159], v[190:193], v[34:37]
	v_mfma_f32_16x16x32_bf16 v[26:29], v[174:177], v[190:193], v[26:29]
	v_mfma_f32_16x16x32_bf16 v[18:21], v[156:159], v[210:213], v[18:21]
	v_mfma_f32_16x16x32_bf16 v[10:13], v[174:177], v[210:213], v[10:13]
	v_mfma_f32_16x16x32_bf16 v[6:9], v[156:159], v[218:221], v[6:9]
	v_mfma_f32_16x16x32_bf16 v[2:5], v[174:177], v[218:221], v[2:5]
	v_mfma_f32_16x16x32_bf16 v[50:53], v[170:173], v[186:189], v[50:53]
	v_mfma_f32_16x16x32_bf16 v[42:45], v[178:181], v[186:189], v[42:45]
	v_mfma_f32_16x16x32_bf16 v[34:37], v[170:173], v[204:207], v[34:37]
	v_mfma_f32_16x16x32_bf16 v[26:29], v[178:181], v[204:207], v[26:29]
	v_mfma_f32_16x16x32_bf16 v[18:21], v[170:173], v[214:217], v[18:21]
	v_mfma_f32_16x16x32_bf16 v[10:13], v[178:181], v[214:217], v[10:13]
	v_mfma_f32_16x16x32_bf16 v[6:9], v[170:173], v[222:225], v[6:9]
	v_mfma_f32_16x16x32_bf16 v[2:5], v[178:181], v[222:225], v[2:5]
	s_add_i32 s46, s46, 2
	s_add_u32 s44, s44, 0x100
	s_addc_u32 s45, s45, 0
	s_add_u32 s60, s60, 0x100
	s_addc_u32 s61, s61, 0
	s_cmp_gt_u32 s46, 13
	s_cbranch_scc1 .Lrot_exit_559
	s_add_u32 s20, s60, 0xfffc0080
	s_addc_u32 s21, s61, -1
	s_add_i32 s29, 0, 0x10000
	s_cmp_eq_u32 s46, 12
	s_cselect_b32 s63, s9, s21
	s_cselect_b32 s62, s42, s20
	s_cselect_b32 s21, s7, s45
	s_cselect_b32 s20, s43, s44
	s_add_i32 s30, 0, 0x14000
	v_add_u32_e32 v152, s29, v165
	v_add_u32_e32 v160, s30, v165
	s_setprio 0
	s_barrier
	s_branch .Lrot_559
.Lrot_exit_559:
	s_setprio 0
	s_barrier
	s_and_b64 vcc, exec, s[4:5]
	s_cbranch_vccz .LBB0_562
	s_barrier

; #define PG8_STAGE(bufoff, gbase, voff) do { _Pragma("unroll") for (int _i = 0; _i < 2; ++_i) \
;         __builtin_amdgcn_global_load_lds((const gunsigned*)((const gchar*)(gbase) + (voff)[_i]), (LAS unsigned*)(lds + (bufoff) + ldsw + _i * 8192), 16, 0, 0); } while (0)
; #define PG8_LDA(dst, b, h) do { _Pragma("unroll") for (int m = 0; m < 4; ++m) _Pragma("unroll") for (int k = 0; k < 2; ++k) dst[m][k] = *(const LAS bf16x8*)(lds + PG8_SA(b, h) + aoff + m * 2048 + k * 1024); } while (0)
; #define PG8_LDB(dst, b, h) do { _Pragma("unroll") for (int n = 0; n < 2; ++n) _Pragma("unroll") for (int k = 0; k < 2; ++k) dst[n][k] = *(const LAS bf16x8*)(lds + PG8_SB(b, h) + boff + n * 2048 + k * 1024); } while (0)
; #define PG8_MMA(ai, bj, At, Bt) do { __builtin_amdgcn_s_setprio(1); _Pragma("unroll") for (int m = 0; m < 4; ++m) _Pragma("unroll") for (int n = 0; n < 2; ++n) _Pragma("unroll") for (int k = 0; k < 2; ++k) \
;         acc[ai][bj][m][n] = __builtin_amdgcn_mfma_f32_16x16x32_bf16(Bt[n][k], At[m][k], acc[ai][bj][m][n], 0, 0, 0); __builtin_amdgcn_s_setprio(0); } while (0)
; #define PG8_WAIT_V(n) asm volatile("s_waitcnt vmcnt(" #n ")" ::: "memory")
; #define PG8_WAIT_L(n) asm volatile("s_waitcnt lgkmcnt(" #n ")" ::: "memory")
; #define PG8_BAR __builtin_amdgcn_s_barrier()
; #define PG8_SCHED __builtin_amdgcn_sched_barrier(0)
; template <class Epi, class Sched>
; __device__ __forceinline__ void gemm_phase(LAS unsigned char* lds, const int tid, const Gemm g, const Sched& S, const Epi& E) {
;     ...
;             PG8_LDB(B0, 0, 0); PG8_LDB(B1, 0, 1); PG8_SCHED; PG8_LDA(At, 0, 0); PG8_STAGE(PG8_SA(1, 1), a1 + hstep, voffA);
;             PG8_WAIT_V(8); PG8_WAIT_L(0); PG8_BAR; PG8_MMA(0, 0, At, B0); PG8_MMA(0, 1, At, B1); PG8_BAR; PG8_SCHED;
;             PG8_LDA(At, 0, 1); PG8_STAGE(PG8_SB(0, 0), b2, voffB); PG8_STAGE(PG8_SB(0, 1), b2 + hstep, voffB); PG8_STAGE(PG8_SA(0, 0), a2, voffA);
;             PG8_WAIT_V(8); PG8_WAIT_L(0); PG8_BAR; PG8_MMA(1, 0, At, B0); PG8_MMA(1, 1, At, B1); PG8_BAR; PG8_SCHED;
.Lrot_598:
	ds_read_b128 v[130:133], v142
	ds_read_b128 v[134:137], v142 offset:1024
	ds_read_b128 v[138:141], v142 offset:2048
	ds_read_b128 v[142:145], v142 offset:3072
	ds_read_b128 v[146:149], v158
	ds_read_b128 v[150:153], v158 offset:1024
	ds_read_b128 v[154:157], v158 offset:2048
	ds_read_b128 v[158:161], v158 offset:3072
	s_add_i32 m0, s34, 0xc000
	ds_read_b128 v[162:165], v214
	ds_read_b128 v[166:169], v214 offset:1024
	ds_read_b128 v[170:173], v214 offset:2048
	ds_read_b128 v[174:177], v214 offset:3072
	ds_read_b128 v[188:191], v214 offset:4096
	ds_read_b128 v[192:195], v214 offset:5120
	ds_read_b128 v[204:207], v214 offset:6144
	ds_read_b128 v[216:219], v214 offset:7168
	global_load_lds_dwordx4 v186, s[62:63]
	s_add_i32 m0, s34, 0xe000
	s_nop 0
	global_load_lds_dwordx4 v184, s[62:63]
	s_waitcnt vmcnt(8)
	s_waitcnt lgkmcnt(0)
	s_barrier
	s_setprio 1
	s_waitcnt lgkmcnt(0)
	v_mfma_f32_16x16x32_bf16 v[126:129], v[130:133], v[162:165], v[126:129]
	v_mfma_f32_16x16x32_bf16 v[122:125], v[138:141], v[162:165], v[122:125]
	v_mfma_f32_16x16x32_bf16 v[110:113], v[130:133], v[170:173], v[110:113]
	v_mfma_f32_16x16x32_bf16 v[106:109], v[138:141], v[170:173], v[106:109]
	v_mfma_f32_16x16x32_bf16 v[94:97], v[130:133], v[188:191], v[94:97]
	v_mfma_f32_16x16x32_bf16 v[90:93], v[138:141], v[188:191], v[90:93]
	v_mfma_f32_16x16x32_bf16 v[78:81], v[130:133], v[204:207], v[78:81]
	v_mfma_f32_16x16x32_bf16 v[74:77], v[138:141], v[204:207], v[74:77]
	v_mfma_f32_16x16x32_bf16 v[126:129], v[134:137], v[166:169], v[126:129]
	v_mfma_f32_16x16x32_bf16 v[122:125], v[142:145], v[166:169], v[122:125]
	v_mfma_f32_16x16x32_bf16 v[110:113], v[134:137], v[174:177], v[110:113]
	v_mfma_f32_16x16x32_bf16 v[106:109], v[142:145], v[174:177], v[106:109]
	v_mfma_f32_16x16x32_bf16 v[94:97], v[134:137], v[192:195], v[94:97]
	v_mfma_f32_16x16x32_bf16 v[90:93], v[142:145], v[192:195], v[90:93]
	v_mfma_f32_16x16x32_bf16 v[78:81], v[134:137], v[216:219], v[78:81]
	v_mfma_f32_16x16x32_bf16 v[74:77], v[142:145], v[216:219], v[74:77]
	s_setprio 0
	s_setprio 1
	v_mfma_f32_16x16x32_bf16 v[118:121], v[146:149], v[162:165], v[118:121]
	v_mfma_f32_16x16x32_bf16 v[114:117], v[154:157], v[162:165], v[114:117]
	v_mfma_f32_16x16x32_bf16 v[102:105], v[146:149], v[170:173], v[102:105]
	v_mfma_f32_16x16x32_bf16 v[98:101], v[154:157], v[170:173], v[98:101]
	v_mfma_f32_16x16x32_bf16 v[86:89], v[146:149], v[188:191], v[86:89]
	v_mfma_f32_16x16x32_bf16 v[82:85], v[154:157], v[188:191], v[82:85]
	v_mfma_f32_16x16x32_bf16 v[70:73], v[146:149], v[204:207], v[70:73]
	v_mfma_f32_16x16x32_bf16 v[66:69], v[154:157], v[204:207], v[66:69]
	v_mfma_f32_16x16x32_bf16 v[118:121], v[150:153], v[166:169], v[118:121]
	v_mfma_f32_16x16x32_bf16 v[114:117], v[158:161], v[166:169], v[114:117]
	v_mfma_f32_16x16x32_bf16 v[102:105], v[150:153], v[174:177], v[102:105]
	v_mfma_f32_16x16x32_bf16 v[98:101], v[158:161], v[174:177], v[98:101]
	v_mfma_f32_16x16x32_bf16 v[86:89], v[150:153], v[192:195], v[86:89]
	v_mfma_f32_16x16x32_bf16 v[82:85], v[158:161], v[192:195], v[82:85]
	v_mfma_f32_16x16x32_bf16 v[70:73], v[150:153], v[216:219], v[70:73]
	v_mfma_f32_16x16x32_bf16 v[66:69], v[158:161], v[216:219], v[66:69]
	s_setprio 0
	s_barrier
	s_add_i32 s29, s29, s15
	s_mov_b32 m0, s29
	ds_read_b128 v[162:165], v214 offset:16384
	ds_read_b128 v[166:169], v214 offset:17408
	ds_read_b128 v[170:173], v214 offset:18432
	ds_read_b128 v[174:177], v214 offset:19456
	ds_read_b128 v[188:191], v214 offset:20480
	ds_read_b128 v[192:195], v214 offset:21504
	ds_read_b128 v[204:207], v214 offset:22528
	ds_read_b128 v[216:219], v214 offset:23552
	global_load_lds_dwordx4 v0, s[66:67]
	s_add_i32 m0, s29, 0x2000
	s_add_u32 s46, s66, 0xb0000
	s_addc_u32 s47, s67, 0
	s_add_i32 s29, s48, s15
	global_load_lds_dwordx4 v182, s[66:67]
	s_mov_b32 m0, s29
	s_nop 0
	global_load_lds_dwordx4 v0, s[46:47]
	s_add_i32 m0, s29, 0x2000
	s_nop 0
	global_load_lds_dwordx4 v182, s[46:47]
	s_mov_b32 m0, s34
	s_nop 0
	global_load_lds_dwordx4 v178, s[72:73]
	s_mov_b32 m0, s12
	s_nop 0
	global_load_lds_dwordx4 v180, s[72:73]
	s_waitcnt vmcnt(8)
	s_waitcnt lgkmcnt(0)
	s_barrier
	s_setprio 1
	s_waitcnt lgkmcnt(0)
	v_mfma_f32_16x16x32_bf16 v[62:65], v[130:133], v[162:165], v[62:65]
	v_mfma_f32_16x16x32_bf16 v[58:61], v[138:141], v[162:165], v[58:61]
	v_mfma_f32_16x16x32_bf16 v[46:49], v[130:133], v[170:173], v[46:49]
	v_mfma_f32_16x16x32_bf16 v[42:45], v[138:141], v[170:173], v[42:45]
	v_mfma_f32_16x16x32_bf16 v[30:33], v[130:133], v[188:191], v[30:33]
	v_mfma_f32_16x16x32_bf16 v[26:29], v[138:141], v[188:191], v[26:29]
	v_mfma_f32_16x16x32_bf16 v[14:17], v[130:133], v[204:207], v[14:17]
	v_mfma_f32_16x16x32_bf16 v[10:13], v[138:141], v[204:207], v[10:13]
	v_mfma_f32_16x16x32_bf16 v[62:65], v[134:137], v[166:169], v[62:65]
	v_mfma_f32_16x16x32_bf16 v[58:61], v[142:145], v[166:169], v[58:61]
	v_mfma_f32_16x16x32_bf16 v[46:49], v[134:137], v[174:177], v[46:49]
	v_mfma_f32_16x16x32_bf16 v[42:45], v[142:145], v[174:177], v[42:45]
	v_mfma_f32_16x16x32_bf16 v[30:33], v[134:137], v[192:195], v[30:33]
	v_mfma_f32_16x16x32_bf16 v[26:29], v[142:145], v[192:195], v[26:29]
	v_mfma_f32_16x16x32_bf16 v[14:17], v[134:137], v[216:219], v[14:17]
	v_mfma_f32_16x16x32_bf16 v[10:13], v[142:145], v[216:219], v[10:13]
	s_setprio 0
	s_setprio 1
	v_mfma_f32_16x16x32_bf16 v[54:57], v[146:149], v[162:165], v[54:57]
	v_mfma_f32_16x16x32_bf16 v[50:53], v[154:157], v[162:165], v[50:53]
	v_mfma_f32_16x16x32_bf16 v[38:41], v[146:149], v[170:173], v[38:41]
	v_mfma_f32_16x16x32_bf16 v[34:37], v[154:157], v[170:173], v[34:37]
	v_mfma_f32_16x16x32_bf16 v[22:25], v[146:149], v[188:191], v[22:25]
	v_mfma_f32_16x16x32_bf16 v[18:21], v[154:157], v[188:191], v[18:21]
	v_mfma_f32_16x16x32_bf16 v[6:9], v[146:149], v[204:207], v[6:9]
	v_mfma_f32_16x16x32_bf16 v[2:5], v[154:157], v[204:207], v[2:5]
	v_mfma_f32_16x16x32_bf16 v[54:57], v[150:153], v[166:169], v[54:57]
	v_mfma_f32_16x16x32_bf16 v[50:53], v[158:161], v[166:169], v[50:53]
	v_mfma_f32_16x16x32_bf16 v[38:41], v[150:153], v[174:177], v[38:41]
	v_mfma_f32_16x16x32_bf16 v[34:37], v[158:161], v[174:177], v[34:37]
	v_mfma_f32_16x16x32_bf16 v[22:25], v[150:153], v[192:195], v[22:25]
	v_mfma_f32_16x16x32_bf16 v[18:21], v[158:161], v[192:195], v[18:21]
	v_mfma_f32_16x16x32_bf16 v[6:9], v[150:153], v[216:219], v[6:9]
	v_mfma_f32_16x16x32_bf16 v[2:5], v[158:161], v[216:219], v[2:5]
	s_setprio 0
	s_barrier
; #define PG8_STAGE(bufoff, gbase, voff) do { _Pragma("unroll") for (int _i = 0; _i < 2; ++_i) \
;         __builtin_amdgcn_global_load_lds((const gunsigned*)((const gchar*)(gbase) + (voff)[_i]), (LAS unsigned*)(lds + (bufoff) + ldsw + _i * 8192), 16, 0, 0); } while (0)
; #define PG8_LDA(dst, b, h) do { _Pragma("unroll") for (int m = 0; m < 4; ++m) _Pragma("unroll") for (int k = 0; k < 2; ++k) dst[m][k] = *(const LAS bf16x8*)(lds + PG8_SA(b, h) + aoff + m * 2048 + k * 1024); } while (0)
; #define PG8_LDB(dst, b, h) do { _Pragma("unroll") for (int n = 0; n < 2; ++n) _Pragma("unroll") for (int k = 0; k < 2; ++k) dst[n][k] = *(const LAS bf16x8*)(lds + PG8_SB(b, h) + boff + n * 2048 + k * 1024); } while (0)
; #define PG8_MMA(ai, bj, At, Bt) do { __builtin_amdgcn_s_setprio(1); _Pragma("unroll") for (int m = 0; m < 4; ++m) _Pragma("unroll") for (int n = 0; n < 2; ++n) _Pragma("unroll") for (int k = 0; k < 2; ++k) \
;         acc[ai][bj][m][n] = __builtin_amdgcn_mfma_f32_16x16x32_bf16(Bt[n][k], At[m][k], acc[ai][bj][m][n], 0, 0, 0); __builtin_amdgcn_s_setprio(0); } while (0)
; #define PG8_WAIT_V(n) asm volatile("s_waitcnt vmcnt(" #n ")" ::: "memory")
; #define PG8_WAIT_L(n) asm volatile("s_waitcnt lgkmcnt(" #n ")" ::: "memory")
; #define PG8_BAR __builtin_amdgcn_s_barrier()
; #define PG8_SCHED __builtin_amdgcn_sched_barrier(0)
; template <class Epi, class Sched>
; __device__ __forceinline__ void gemm_phase(LAS unsigned char* lds, const int tid, const Gemm g, const Sched& S, const Epi& E) {
;     ...
;         for (int t = 0; t < nt; t += 2) {
;             const bool last = (t == nt - 2);
;             const gchar* a1 = cA + (size_t)(t + 1) * kstep;
;             const gchar* a2 = last ? nA : cA + (size_t)(t + 2) * kstep; const gchar* b2 = last ? nB : cB + (size_t)(t + 2) * kstep;
;     ...
;             PG8_LDB(B0, 1, 0); PG8_LDB(B1, 1, 1); PG8_SCHED; PG8_LDA(At, 1, 0); PG8_STAGE(PG8_SA(0, 1), a2 + hstep, voffA);
;             PG8_WAIT_V(8); PG8_WAIT_L(0); PG8_BAR; PG8_MMA(0, 0, At, B0); PG8_MMA(0, 1, At, B1); PG8_BAR; PG8_SCHED;
;             PG8_LDA(At, 1, 1); PG8_STAGE(PG8_SB(1, 0), b3, voffB); PG8_STAGE(PG8_SB(1, 1), b3 + hstep, voffB); PG8_STAGE(PG8_SA(1, 0), a3, voffA);
;             PG8_WAIT_V(8); PG8_WAIT_L(0); PG8_BAR; PG8_MMA(1, 0, At, B0); PG8_MMA(1, 1, At, B1); PG8_BAR; PG8_SCHED;
	s_add_i32 s29, 0, 0x18000
	s_add_i32 s48, 0, 0x1c000
	v_add_u32_e32 v142, s29, v210
	v_add_u32_e32 v158, s48, v210
	ds_read_b128 v[130:133], v142
	ds_read_b128 v[134:137], v142 offset:1024
	ds_read_b128 v[138:141], v142 offset:2048
	ds_read_b128 v[142:145], v142 offset:3072
	ds_read_b128 v[146:149], v158
	ds_read_b128 v[150:153], v158 offset:1024
	ds_read_b128 v[154:157], v158 offset:2048
	ds_read_b128 v[158:161], v158 offset:3072
	s_add_u32 s46, s72, 0xb0000
	s_addc_u32 s47, s73, 0
	s_mov_b32 m0, s35
	ds_read_b128 v[162:165], v214 offset:32768
	ds_read_b128 v[166:169], v214 offset:33792
	ds_read_b128 v[170:173], v214 offset:34816
	ds_read_b128 v[174:177], v214 offset:35840
	ds_read_b128 v[188:191], v214 offset:36864
	ds_read_b128 v[192:195], v214 offset:37888
	ds_read_b128 v[204:207], v214 offset:38912
	ds_read_b128 v[216:219], v214 offset:39936
	global_load_lds_dwordx4 v178, s[46:47]
	s_mov_b32 m0, s36
	s_nop 0
	global_load_lds_dwordx4 v180, s[46:47]
	s_waitcnt vmcnt(8)
	s_waitcnt lgkmcnt(0)
	s_barrier
	s_setprio 1
	s_waitcnt lgkmcnt(0)
	v_mfma_f32_16x16x32_bf16 v[126:129], v[130:133], v[162:165], v[126:129]
	v_mfma_f32_16x16x32_bf16 v[122:125], v[138:141], v[162:165], v[122:125]
	v_mfma_f32_16x16x32_bf16 v[110:113], v[130:133], v[170:173], v[110:113]
	v_mfma_f32_16x16x32_bf16 v[106:109], v[138:141], v[170:173], v[106:109]
	v_mfma_f32_16x16x32_bf16 v[94:97], v[130:133], v[188:191], v[94:97]
	v_mfma_f32_16x16x32_bf16 v[90:93], v[138:141], v[188:191], v[90:93]
	v_mfma_f32_16x16x32_bf16 v[78:81], v[130:133], v[204:207], v[78:81]
	v_mfma_f32_16x16x32_bf16 v[74:77], v[138:141], v[204:207], v[74:77]
	v_mfma_f32_16x16x32_bf16 v[126:129], v[134:137], v[166:169], v[126:129]
	v_mfma_f32_16x16x32_bf16 v[122:125], v[142:145], v[166:169], v[122:125]
	v_mfma_f32_16x16x32_bf16 v[110:113], v[134:137], v[174:177], v[110:113]
	v_mfma_f32_16x16x32_bf16 v[106:109], v[142:145], v[174:177], v[106:109]
	v_mfma_f32_16x16x32_bf16 v[94:97], v[134:137], v[192:195], v[94:97]
	v_mfma_f32_16x16x32_bf16 v[90:93], v[142:145], v[192:195], v[90:93]
	v_mfma_f32_16x16x32_bf16 v[78:81], v[134:137], v[216:219], v[78:81]
	v_mfma_f32_16x16x32_bf16 v[74:77], v[142:145], v[216:219], v[74:77]
	s_setprio 0
	s_setprio 1
	v_mfma_f32_16x16x32_bf16 v[118:121], v[146:149], v[162:165], v[118:121]
	v_mfma_f32_16x16x32_bf16 v[114:117], v[154:157], v[162:165], v[114:117]
	v_mfma_f32_16x16x32_bf16 v[102:105], v[146:149], v[170:173], v[102:105]
	v_mfma_f32_16x16x32_bf16 v[98:101], v[154:157], v[170:173], v[98:101]
	v_mfma_f32_16x16x32_bf16 v[86:89], v[146:149], v[188:191], v[86:89]
	v_mfma_f32_16x16x32_bf16 v[82:85], v[154:157], v[188:191], v[82:85]
	v_mfma_f32_16x16x32_bf16 v[70:73], v[146:149], v[204:207], v[70:73]
	v_mfma_f32_16x16x32_bf16 v[66:69], v[154:157], v[204:207], v[66:69]
	v_mfma_f32_16x16x32_bf16 v[118:121], v[150:153], v[166:169], v[118:121]
	v_mfma_f32_16x16x32_bf16 v[114:117], v[158:161], v[166:169], v[114:117]
	v_mfma_f32_16x16x32_bf16 v[102:105], v[150:153], v[174:177], v[102:105]
	v_mfma_f32_16x16x32_bf16 v[98:101], v[158:161], v[174:177], v[98:101]
	v_mfma_f32_16x16x32_bf16 v[86:89], v[150:153], v[192:195], v[86:89]
	v_mfma_f32_16x16x32_bf16 v[82:85], v[158:161], v[192:195], v[82:85]
	v_mfma_f32_16x16x32_bf16 v[70:73], v[150:153], v[216:219], v[70:73]
	v_mfma_f32_16x16x32_bf16 v[66:69], v[158:161], v[216:219], v[66:69]
	s_setprio 0
	s_barrier
	s_add_i32 s29, s29, s15
	s_mov_b32 m0, s29
	ds_read_b128 v[162:165], v214 offset:49152
	ds_read_b128 v[166:169], v214 offset:50176
	ds_read_b128 v[170:173], v214 offset:51200
	ds_read_b128 v[174:177], v214 offset:52224
	ds_read_b128 v[188:191], v214 offset:53248
	ds_read_b128 v[192:195], v214 offset:54272
	ds_read_b128 v[204:207], v214 offset:55296
	ds_read_b128 v[216:219], v214 offset:56320
	global_load_lds_dwordx4 v221, s[66:67]
	s_add_i32 m0, s29, 0x2000
	s_add_u32 s46, s66, 0xb0080
	s_addc_u32 s47, s67, 0
	s_add_i32 s29, s48, s15
	global_load_lds_dwordx4 v223, s[66:67]
	s_mov_b32 m0, s29
	s_nop 0
	global_load_lds_dwordx4 v0, s[46:47]
	s_add_i32 m0, s29, 0x2000
	s_nop 0
	global_load_lds_dwordx4 v182, s[46:47]
	s_mov_b32 m0, s37
	s_nop 0
	global_load_lds_dwordx4 v225, s[72:73]
	s_mov_b32 m0, s38
	s_nop 0
	global_load_lds_dwordx4 v227, s[72:73]
	s_waitcnt vmcnt(8)
	s_waitcnt lgkmcnt(0)
	s_barrier
	s_setprio 1
	s_waitcnt lgkmcnt(0)
	v_mfma_f32_16x16x32_bf16 v[62:65], v[130:133], v[162:165], v[62:65]
	v_mfma_f32_16x16x32_bf16 v[58:61], v[138:141], v[162:165], v[58:61]
	v_mfma_f32_16x16x32_bf16 v[46:49], v[130:133], v[170:173], v[46:49]
	v_mfma_f32_16x16x32_bf16 v[42:45], v[138:141], v[170:173], v[42:45]
	v_mfma_f32_16x16x32_bf16 v[30:33], v[130:133], v[188:191], v[30:33]
	v_mfma_f32_16x16x32_bf16 v[26:29], v[138:141], v[188:191], v[26:29]
	v_mfma_f32_16x16x32_bf16 v[14:17], v[130:133], v[204:207], v[14:17]
	v_mfma_f32_16x16x32_bf16 v[10:13], v[138:141], v[204:207], v[10:13]
	v_mfma_f32_16x16x32_bf16 v[62:65], v[134:137], v[166:169], v[62:65]
	v_mfma_f32_16x16x32_bf16 v[58:61], v[142:145], v[166:169], v[58:61]
	v_mfma_f32_16x16x32_bf16 v[46:49], v[134:137], v[174:177], v[46:49]
	v_mfma_f32_16x16x32_bf16 v[42:45], v[142:145], v[174:177], v[42:45]
	v_mfma_f32_16x16x32_bf16 v[30:33], v[134:137], v[192:195], v[30:33]
	v_mfma_f32_16x16x32_bf16 v[26:29], v[142:145], v[192:195], v[26:29]
	v_mfma_f32_16x16x32_bf16 v[14:17], v[134:137], v[216:219], v[14:17]
	v_mfma_f32_16x16x32_bf16 v[10:13], v[142:145], v[216:219], v[10:13]
	s_setprio 0
	s_setprio 1
	v_mfma_f32_16x16x32_bf16 v[54:57], v[146:149], v[162:165], v[54:57]
	v_mfma_f32_16x16x32_bf16 v[50:53], v[154:157], v[162:165], v[50:53]
	v_mfma_f32_16x16x32_bf16 v[38:41], v[146:149], v[170:173], v[38:41]
	v_mfma_f32_16x16x32_bf16 v[34:37], v[154:157], v[170:173], v[34:37]
	v_mfma_f32_16x16x32_bf16 v[22:25], v[146:149], v[188:191], v[22:25]
	v_mfma_f32_16x16x32_bf16 v[18:21], v[154:157], v[188:191], v[18:21]
	v_mfma_f32_16x16x32_bf16 v[6:9], v[146:149], v[204:207], v[6:9]
	v_mfma_f32_16x16x32_bf16 v[2:5], v[154:157], v[204:207], v[2:5]
	v_mfma_f32_16x16x32_bf16 v[54:57], v[150:153], v[166:169], v[54:57]
	v_mfma_f32_16x16x32_bf16 v[50:53], v[158:161], v[166:169], v[50:53]
	v_mfma_f32_16x16x32_bf16 v[38:41], v[150:153], v[174:177], v[38:41]
	v_mfma_f32_16x16x32_bf16 v[34:37], v[158:161], v[174:177], v[34:37]
	v_mfma_f32_16x16x32_bf16 v[22:25], v[150:153], v[192:195], v[22:25]
	v_mfma_f32_16x16x32_bf16 v[18:21], v[158:161], v[192:195], v[18:21]
	v_mfma_f32_16x16x32_bf16 v[6:9], v[150:153], v[216:219], v[6:9]
	v_mfma_f32_16x16x32_bf16 v[2:5], v[158:161], v[216:219], v[2:5]
	s_add_i32 s45, s45, 2
	s_add_u32 s31, s31, 0x100
	s_addc_u32 s44, s44, 0
	s_cmp_gt_u32 s45, 41
	s_mov_b64 s[62:63], s[20:21]
	s_cbranch_scc1 .Lrot_exit_598
	s_add_u32 s20, s62, 0x100
	s_addc_u32 s21, s63, 0
	s_add_i32 s29, 0, 0x10000
	s_cmp_eq_u32 s45, 40
	s_cselect_b32 s73, s9, s21
	s_cselect_b32 s72, s8, s20
	s_cselect_b32 s67, s61, s44
	s_cselect_b32 s66, s60, s31
	s_add_i32 s48, 0, 0x14000
	v_add_u32_e32 v142, s29, v210
	v_add_u32_e32 v158, s48, v210
	s_setprio 0
	s_barrier
	s_branch .Lrot_598
; #define PG8_BAR __builtin_amdgcn_s_barrier()
; template <class Epi, class Sched>
; __device__ __forceinline__ void gemm_phase(LAS unsigned char* lds, const int tid, const Gemm g, const Sched& S, const Epi& E) {
;     ...
;         if (wr == 0) PG8_BAR;
.Lrot_exit_598:
	s_setprio 0
	s_barrier
	s_and_b64 vcc, exec, s[58:59]
	s_cbranch_vccz .LBB0_601
	s_barrier

; #define PG8_STAGE(bufoff, gbase, voff) do { _Pragma("unroll") for (int _i = 0; _i < 2; ++_i) \
;         __builtin_amdgcn_global_load_lds((const gunsigned*)((const gchar*)(gbase) + (voff)[_i]), (LAS unsigned*)(lds + (bufoff) + ldsw + _i * 8192), 16, 0, 0); } while (0)
; #define PG8_LDA(dst, b, h) do { _Pragma("unroll") for (int m = 0; m < 4; ++m) _Pragma("unroll") for (int k = 0; k < 2; ++k) dst[m][k] = *(const LAS bf16x8*)(lds + PG8_SA(b, h) + aoff + m * 2048 + k * 1024); } while (0)
; #define PG8_LDB(dst, b, h) do { _Pragma("unroll") for (int n = 0; n < 2; ++n) _Pragma("unroll") for (int k = 0; k < 2; ++k) dst[n][k] = *(const LAS bf16x8*)(lds + PG8_SB(b, h) + boff + n * 2048 + k * 1024); } while (0)
; #define PG8_MMA(ai, bj, At, Bt) do { __builtin_amdgcn_s_setprio(1); _Pragma("unroll") for (int m = 0; m < 4; ++m) _Pragma("unroll") for (int n = 0; n < 2; ++n) _Pragma("unroll") for (int k = 0; k < 2; ++k) \
;         acc[ai][bj][m][n] = __builtin_amdgcn_mfma_f32_16x16x32_bf16(Bt[n][k], At[m][k], acc[ai][bj][m][n], 0, 0, 0); __builtin_amdgcn_s_setprio(0); } while (0)
; #define PG8_WAIT_V(n) asm volatile("s_waitcnt vmcnt(" #n ")" ::: "memory")
; #define PG8_WAIT_L(n) asm volatile("s_waitcnt lgkmcnt(" #n ")" ::: "memory")
; #define PG8_BAR __builtin_amdgcn_s_barrier()
; #define PG8_SCHED __builtin_amdgcn_sched_barrier(0)
; template <class Epi, class Sched>
; __device__ __forceinline__ void gemm_phase(LAS unsigned char* lds, const int tid, const Gemm g, const Sched& S, const Epi& E) {
;     ...
;             PG8_LDB(B0, 0, 0); PG8_LDB(B1, 0, 1); PG8_SCHED; PG8_LDA(At, 0, 0); PG8_STAGE(PG8_SA(1, 1), a1 + hstep, voffA);
;             PG8_WAIT_V(8); PG8_WAIT_L(0); PG8_BAR; PG8_MMA(0, 0, At, B0); PG8_MMA(0, 1, At, B1); PG8_BAR; PG8_SCHED;
;             PG8_LDA(At, 0, 1); PG8_STAGE(PG8_SB(0, 0), b2, voffB); PG8_STAGE(PG8_SB(0, 1), b2 + hstep, voffB); PG8_STAGE(PG8_SA(0, 0), a2, voffA);
;             PG8_WAIT_V(8); PG8_WAIT_L(0); PG8_BAR; PG8_MMA(1, 0, At, B0); PG8_MMA(1, 1, At, B1); PG8_BAR; PG8_SCHED;
.Lrot_647:
	ds_read_b128 v[146:149], v140
	ds_read_b128 v[150:153], v140 offset:1024
	ds_read_b128 v[154:157], v140 offset:2048
	ds_read_b128 v[158:161], v140 offset:3072
	v_add_u32_e32 v140, s44, v143
	ds_read_b128 v[162:165], v140
	ds_read_b128 v[166:169], v140 offset:1024
	ds_read_b128 v[170:173], v140 offset:2048
	ds_read_b128 v[174:177], v140 offset:3072
	s_add_i32 m0, s23, 0xc000
	ds_read_b128 v[178:181], v145
	ds_read_b128 v[182:185], v145 offset:1024
	ds_read_b128 v[186:189], v145 offset:2048
	ds_read_b128 v[190:193], v145 offset:3072
	ds_read_b128 v[204:207], v145 offset:4096
	ds_read_b128 v[208:211], v145 offset:5120
	ds_read_b128 v[212:215], v145 offset:6144
	ds_read_b128 v[216:219], v145 offset:7168
	global_load_lds_dwordx4 v138, s[58:59]
	s_add_i32 m0, s23, 0xe000
	s_nop 0
	global_load_lds_dwordx4 v136, s[58:59]
	s_waitcnt vmcnt(8)
	s_waitcnt lgkmcnt(0)
	s_barrier
	s_setprio 1
	s_waitcnt lgkmcnt(0)
	v_mfma_f32_16x16x32_bf16 v[126:129], v[146:149], v[178:181], v[126:129]
	v_mfma_f32_16x16x32_bf16 v[122:125], v[154:157], v[178:181], v[122:125]
	v_mfma_f32_16x16x32_bf16 v[110:113], v[146:149], v[186:189], v[110:113]
	v_mfma_f32_16x16x32_bf16 v[106:109], v[154:157], v[186:189], v[106:109]
	v_mfma_f32_16x16x32_bf16 v[94:97], v[146:149], v[204:207], v[94:97]
	v_mfma_f32_16x16x32_bf16 v[90:93], v[154:157], v[204:207], v[90:93]
	v_mfma_f32_16x16x32_bf16 v[78:81], v[146:149], v[212:215], v[78:81]
	v_mfma_f32_16x16x32_bf16 v[74:77], v[154:157], v[212:215], v[74:77]
	v_mfma_f32_16x16x32_bf16 v[126:129], v[150:153], v[182:185], v[126:129]
	v_mfma_f32_16x16x32_bf16 v[122:125], v[158:161], v[182:185], v[122:125]
	v_mfma_f32_16x16x32_bf16 v[110:113], v[150:153], v[190:193], v[110:113]
	v_mfma_f32_16x16x32_bf16 v[106:109], v[158:161], v[190:193], v[106:109]
	v_mfma_f32_16x16x32_bf16 v[94:97], v[150:153], v[208:211], v[94:97]
	v_mfma_f32_16x16x32_bf16 v[90:93], v[158:161], v[208:211], v[90:93]
	v_mfma_f32_16x16x32_bf16 v[78:81], v[150:153], v[216:219], v[78:81]
	v_mfma_f32_16x16x32_bf16 v[74:77], v[158:161], v[216:219], v[74:77]
	s_setprio 0
	s_setprio 1
	v_mfma_f32_16x16x32_bf16 v[118:121], v[162:165], v[178:181], v[118:121]
	v_mfma_f32_16x16x32_bf16 v[114:117], v[170:173], v[178:181], v[114:117]
	v_mfma_f32_16x16x32_bf16 v[102:105], v[162:165], v[186:189], v[102:105]
	v_mfma_f32_16x16x32_bf16 v[98:101], v[170:173], v[186:189], v[98:101]
	v_mfma_f32_16x16x32_bf16 v[86:89], v[162:165], v[204:207], v[86:89]
	v_mfma_f32_16x16x32_bf16 v[82:85], v[170:173], v[204:207], v[82:85]
	v_mfma_f32_16x16x32_bf16 v[70:73], v[162:165], v[212:215], v[70:73]
	v_mfma_f32_16x16x32_bf16 v[66:69], v[170:173], v[212:215], v[66:69]
	v_mfma_f32_16x16x32_bf16 v[118:121], v[166:169], v[182:185], v[118:121]
	v_mfma_f32_16x16x32_bf16 v[114:117], v[174:177], v[182:185], v[114:117]
	v_mfma_f32_16x16x32_bf16 v[102:105], v[166:169], v[190:193], v[102:105]
	v_mfma_f32_16x16x32_bf16 v[98:101], v[174:177], v[190:193], v[98:101]
	v_mfma_f32_16x16x32_bf16 v[86:89], v[166:169], v[208:211], v[86:89]
	v_mfma_f32_16x16x32_bf16 v[82:85], v[174:177], v[208:211], v[82:85]
	v_mfma_f32_16x16x32_bf16 v[70:73], v[166:169], v[216:219], v[70:73]
	v_mfma_f32_16x16x32_bf16 v[66:69], v[174:177], v[216:219], v[66:69]
	s_setprio 0
	s_barrier
	s_add_i32 s42, s42, s12
	s_mov_b32 m0, s42
	ds_read_b128 v[178:181], v145 offset:16384
	ds_read_b128 v[182:185], v145 offset:17408
	ds_read_b128 v[186:189], v145 offset:18432
	ds_read_b128 v[190:193], v145 offset:19456
	ds_read_b128 v[204:207], v145 offset:20480
	ds_read_b128 v[208:211], v145 offset:21504
	ds_read_b128 v[212:215], v145 offset:22528
	ds_read_b128 v[216:219], v145 offset:23552
	global_load_lds_dwordx4 v0, s[20:21]
	s_add_i32 m0, s42, 0x2000
	s_add_u32 s42, s20, 0x40000
	s_addc_u32 s43, s21, 0
	s_add_i32 s44, s44, s12
	global_load_lds_dwordx4 v130, s[20:21]
	s_mov_b32 m0, s44
	s_nop 0
	global_load_lds_dwordx4 v0, s[42:43]
	s_add_i32 m0, s44, 0x2000
	s_nop 0
	global_load_lds_dwordx4 v130, s[42:43]
	s_mov_b32 m0, s23
	s_nop 0
	global_load_lds_dwordx4 v134, s[60:61]
	s_mov_b32 m0, s24
	s_nop 0
	global_load_lds_dwordx4 v132, s[60:61]
	s_waitcnt vmcnt(8)
	s_waitcnt lgkmcnt(0)
	s_barrier
	s_setprio 1
	s_waitcnt lgkmcnt(0)
	v_mfma_f32_16x16x32_bf16 v[62:65], v[146:149], v[178:181], v[62:65]
	v_mfma_f32_16x16x32_bf16 v[58:61], v[154:157], v[178:181], v[58:61]
	v_mfma_f32_16x16x32_bf16 v[46:49], v[146:149], v[186:189], v[46:49]
	v_mfma_f32_16x16x32_bf16 v[42:45], v[154:157], v[186:189], v[42:45]
	v_mfma_f32_16x16x32_bf16 v[30:33], v[146:149], v[204:207], v[30:33]
	v_mfma_f32_16x16x32_bf16 v[26:29], v[154:157], v[204:207], v[26:29]
	v_mfma_f32_16x16x32_bf16 v[14:17], v[146:149], v[212:215], v[14:17]
	v_mfma_f32_16x16x32_bf16 v[10:13], v[154:157], v[212:215], v[10:13]
	v_mfma_f32_16x16x32_bf16 v[62:65], v[150:153], v[182:185], v[62:65]
	v_mfma_f32_16x16x32_bf16 v[58:61], v[158:161], v[182:185], v[58:61]
	v_mfma_f32_16x16x32_bf16 v[46:49], v[150:153], v[190:193], v[46:49]
	v_mfma_f32_16x16x32_bf16 v[42:45], v[158:161], v[190:193], v[42:45]
	v_mfma_f32_16x16x32_bf16 v[30:33], v[150:153], v[208:211], v[30:33]
	v_mfma_f32_16x16x32_bf16 v[26:29], v[158:161], v[208:211], v[26:29]
	v_mfma_f32_16x16x32_bf16 v[14:17], v[150:153], v[216:219], v[14:17]
	v_mfma_f32_16x16x32_bf16 v[10:13], v[158:161], v[216:219], v[10:13]
	s_setprio 0
	s_setprio 1
	v_mfma_f32_16x16x32_bf16 v[54:57], v[162:165], v[178:181], v[54:57]
	v_mfma_f32_16x16x32_bf16 v[50:53], v[170:173], v[178:181], v[50:53]
	v_mfma_f32_16x16x32_bf16 v[38:41], v[162:165], v[186:189], v[38:41]
	v_mfma_f32_16x16x32_bf16 v[34:37], v[170:173], v[186:189], v[34:37]
	v_mfma_f32_16x16x32_bf16 v[22:25], v[162:165], v[204:207], v[22:25]
	v_mfma_f32_16x16x32_bf16 v[18:21], v[170:173], v[204:207], v[18:21]
	v_mfma_f32_16x16x32_bf16 v[6:9], v[162:165], v[212:215], v[6:9]
	v_mfma_f32_16x16x32_bf16 v[2:5], v[170:173], v[212:215], v[2:5]
	v_mfma_f32_16x16x32_bf16 v[54:57], v[166:169], v[182:185], v[54:57]
	v_mfma_f32_16x16x32_bf16 v[50:53], v[174:177], v[182:185], v[50:53]
	v_mfma_f32_16x16x32_bf16 v[38:41], v[166:169], v[190:193], v[38:41]
	v_mfma_f32_16x16x32_bf16 v[34:37], v[174:177], v[190:193], v[34:37]
	v_mfma_f32_16x16x32_bf16 v[22:25], v[166:169], v[208:211], v[22:25]
	v_mfma_f32_16x16x32_bf16 v[18:21], v[174:177], v[208:211], v[18:21]
	v_mfma_f32_16x16x32_bf16 v[6:9], v[166:169], v[216:219], v[6:9]
	v_mfma_f32_16x16x32_bf16 v[2:5], v[174:177], v[216:219], v[2:5]
	s_setprio 0
	s_barrier
; #define PG8_STAGE(bufoff, gbase, voff) do { _Pragma("unroll") for (int _i = 0; _i < 2; ++_i) \
;         __builtin_amdgcn_global_load_lds((const gunsigned*)((const gchar*)(gbase) + (voff)[_i]), (LAS unsigned*)(lds + (bufoff) + ldsw + _i * 8192), 16, 0, 0); } while (0)
; #define PG8_LDA(dst, b, h) do { _Pragma("unroll") for (int m = 0; m < 4; ++m) _Pragma("unroll") for (int k = 0; k < 2; ++k) dst[m][k] = *(const LAS bf16x8*)(lds + PG8_SA(b, h) + aoff + m * 2048 + k * 1024); } while (0)
; #define PG8_LDB(dst, b, h) do { _Pragma("unroll") for (int n = 0; n < 2; ++n) _Pragma("unroll") for (int k = 0; k < 2; ++k) dst[n][k] = *(const LAS bf16x8*)(lds + PG8_SB(b, h) + boff + n * 2048 + k * 1024); } while (0)
; #define PG8_MMA(ai, bj, At, Bt) do { __builtin_amdgcn_s_setprio(1); _Pragma("unroll") for (int m = 0; m < 4; ++m) _Pragma("unroll") for (int n = 0; n < 2; ++n) _Pragma("unroll") for (int k = 0; k < 2; ++k) \
;         acc[ai][bj][m][n] = __builtin_amdgcn_mfma_f32_16x16x32_bf16(Bt[n][k], At[m][k], acc[ai][bj][m][n], 0, 0, 0); __builtin_amdgcn_s_setprio(0); } while (0)
; #define PG8_WAIT_V(n) asm volatile("s_waitcnt vmcnt(" #n ")" ::: "memory")
; #define PG8_WAIT_L(n) asm volatile("s_waitcnt lgkmcnt(" #n ")" ::: "memory")
; #define PG8_BAR __builtin_amdgcn_s_barrier()
; #define PG8_SCHED __builtin_amdgcn_sched_barrier(0)
; template <class Epi, class Sched>
; __device__ __forceinline__ void gemm_phase(LAS unsigned char* lds, const int tid, const Gemm g, const Sched& S, const Epi& E) {
;     ...
;         for (int t = 0; t < nt; t += 2) {
;             const bool last = (t == nt - 2);
;             const gchar* a1 = cA + (size_t)(t + 1) * kstep;
;             const gchar* a2 = last ? nA : cA + (size_t)(t + 2) * kstep; const gchar* b2 = last ? nB : cB + (size_t)(t + 2) * kstep;
;     ...
;             PG8_LDB(B0, 1, 0); PG8_LDB(B1, 1, 1); PG8_SCHED; PG8_LDA(At, 1, 0); PG8_STAGE(PG8_SA(0, 1), a2 + hstep, voffA);
;             PG8_WAIT_V(8); PG8_WAIT_L(0); PG8_BAR; PG8_MMA(0, 0, At, B0); PG8_MMA(0, 1, At, B1); PG8_BAR; PG8_SCHED;
;             PG8_LDA(At, 1, 1); PG8_STAGE(PG8_SB(1, 0), b3, voffB); PG8_STAGE(PG8_SB(1, 1), b3 + hstep, voffB); PG8_STAGE(PG8_SA(1, 0), a3, voffA);
;             PG8_WAIT_V(8); PG8_WAIT_L(0); PG8_BAR; PG8_MMA(1, 0, At, B0); PG8_MMA(1, 1, At, B1); PG8_BAR; PG8_SCHED;
	s_add_i32 s44, 0, 0x18000
	s_add_i32 s45, 0, 0x1c000
	v_add_u32_e32 v158, s44, v143
	v_add_u32_e32 v174, s45, v143
	ds_read_b128 v[146:149], v158
	ds_read_b128 v[150:153], v158 offset:1024
	ds_read_b128 v[154:157], v158 offset:2048
	ds_read_b128 v[158:161], v158 offset:3072
	ds_read_b128 v[162:165], v174
	ds_read_b128 v[166:169], v174 offset:1024
	ds_read_b128 v[170:173], v174 offset:2048
	ds_read_b128 v[174:177], v174 offset:3072
	s_add_u32 s42, s60, 0x40000
	s_addc_u32 s43, s61, 0
	s_mov_b32 m0, s29
	ds_read_b128 v[178:181], v145 offset:32768
	ds_read_b128 v[182:185], v145 offset:33792
	ds_read_b128 v[186:189], v145 offset:34816
	ds_read_b128 v[190:193], v145 offset:35840
	ds_read_b128 v[204:207], v145 offset:36864
	ds_read_b128 v[208:211], v145 offset:37888
	ds_read_b128 v[212:215], v145 offset:38912
	ds_read_b128 v[216:219], v145 offset:39936
	global_load_lds_dwordx4 v134, s[42:43]
	s_mov_b32 m0, s30
	s_nop 0
	global_load_lds_dwordx4 v132, s[42:43]
	s_waitcnt vmcnt(8)
	s_waitcnt lgkmcnt(0)
	s_barrier
	s_setprio 1
	s_waitcnt lgkmcnt(0)
	v_mfma_f32_16x16x32_bf16 v[126:129], v[146:149], v[178:181], v[126:129]
	v_mfma_f32_16x16x32_bf16 v[122:125], v[154:157], v[178:181], v[122:125]
	v_mfma_f32_16x16x32_bf16 v[110:113], v[146:149], v[186:189], v[110:113]
	v_mfma_f32_16x16x32_bf16 v[106:109], v[154:157], v[186:189], v[106:109]
	v_mfma_f32_16x16x32_bf16 v[94:97], v[146:149], v[204:207], v[94:97]
	v_mfma_f32_16x16x32_bf16 v[90:93], v[154:157], v[204:207], v[90:93]
	v_mfma_f32_16x16x32_bf16 v[78:81], v[146:149], v[212:215], v[78:81]
	v_mfma_f32_16x16x32_bf16 v[74:77], v[154:157], v[212:215], v[74:77]
	v_mfma_f32_16x16x32_bf16 v[126:129], v[150:153], v[182:185], v[126:129]
	v_mfma_f32_16x16x32_bf16 v[122:125], v[158:161], v[182:185], v[122:125]
	v_mfma_f32_16x16x32_bf16 v[110:113], v[150:153], v[190:193], v[110:113]
	v_mfma_f32_16x16x32_bf16 v[106:109], v[158:161], v[190:193], v[106:109]
	v_mfma_f32_16x16x32_bf16 v[94:97], v[150:153], v[208:211], v[94:97]
	v_mfma_f32_16x16x32_bf16 v[90:93], v[158:161], v[208:211], v[90:93]
	v_mfma_f32_16x16x32_bf16 v[78:81], v[150:153], v[216:219], v[78:81]
	v_mfma_f32_16x16x32_bf16 v[74:77], v[158:161], v[216:219], v[74:77]
	s_setprio 0
	s_setprio 1
	v_mfma_f32_16x16x32_bf16 v[118:121], v[162:165], v[178:181], v[118:121]
	v_mfma_f32_16x16x32_bf16 v[114:117], v[170:173], v[178:181], v[114:117]
	v_mfma_f32_16x16x32_bf16 v[102:105], v[162:165], v[186:189], v[102:105]
	v_mfma_f32_16x16x32_bf16 v[98:101], v[170:173], v[186:189], v[98:101]
	v_mfma_f32_16x16x32_bf16 v[86:89], v[162:165], v[204:207], v[86:89]
	v_mfma_f32_16x16x32_bf16 v[82:85], v[170:173], v[204:207], v[82:85]
	v_mfma_f32_16x16x32_bf16 v[70:73], v[162:165], v[212:215], v[70:73]
	v_mfma_f32_16x16x32_bf16 v[66:69], v[170:173], v[212:215], v[66:69]
	v_mfma_f32_16x16x32_bf16 v[118:121], v[166:169], v[182:185], v[118:121]
	v_mfma_f32_16x16x32_bf16 v[114:117], v[174:177], v[182:185], v[114:117]
	v_mfma_f32_16x16x32_bf16 v[102:105], v[166:169], v[190:193], v[102:105]
	v_mfma_f32_16x16x32_bf16 v[98:101], v[174:177], v[190:193], v[98:101]
	v_mfma_f32_16x16x32_bf16 v[86:89], v[166:169], v[208:211], v[86:89]
	v_mfma_f32_16x16x32_bf16 v[82:85], v[174:177], v[208:211], v[82:85]
	v_mfma_f32_16x16x32_bf16 v[70:73], v[166:169], v[216:219], v[70:73]
	v_mfma_f32_16x16x32_bf16 v[66:69], v[174:177], v[216:219], v[66:69]
	s_setprio 0
	s_barrier
	s_add_i32 s42, s44, s12
	s_mov_b32 m0, s42
	ds_read_b128 v[178:181], v145 offset:49152
	ds_read_b128 v[182:185], v145 offset:50176
	ds_read_b128 v[186:189], v145 offset:51200
	ds_read_b128 v[190:193], v145 offset:52224
	ds_read_b128 v[204:207], v145 offset:53248
	ds_read_b128 v[208:211], v145 offset:54272
	ds_read_b128 v[212:215], v145 offset:55296
	ds_read_b128 v[216:219], v145 offset:56320
	global_load_lds_dwordx4 v141, s[20:21]
	s_add_i32 m0, s42, 0x2000
	s_add_i32 s42, s45, s12
	global_load_lds_dwordx4 v195, s[20:21]
	s_add_u32 s20, s20, 0x40080
	s_addc_u32 s21, s21, 0
	s_mov_b32 m0, s42
	s_nop 0
	global_load_lds_dwordx4 v0, s[20:21]
	s_add_i32 m0, s42, 0x2000
	s_nop 0
	global_load_lds_dwordx4 v130, s[20:21]
	s_mov_b32 m0, s31
	s_nop 0
	global_load_lds_dwordx4 v221, s[60:61]
	s_mov_b32 m0, s34
	s_nop 0
	global_load_lds_dwordx4 v223, s[60:61]
	s_waitcnt vmcnt(8)
	s_waitcnt lgkmcnt(0)
	s_barrier
	s_setprio 1
	s_waitcnt lgkmcnt(0)
	v_mfma_f32_16x16x32_bf16 v[62:65], v[146:149], v[178:181], v[62:65]
	v_mfma_f32_16x16x32_bf16 v[58:61], v[154:157], v[178:181], v[58:61]
	v_mfma_f32_16x16x32_bf16 v[46:49], v[146:149], v[186:189], v[46:49]
	v_mfma_f32_16x16x32_bf16 v[42:45], v[154:157], v[186:189], v[42:45]
	v_mfma_f32_16x16x32_bf16 v[30:33], v[146:149], v[204:207], v[30:33]
	v_mfma_f32_16x16x32_bf16 v[26:29], v[154:157], v[204:207], v[26:29]
	v_mfma_f32_16x16x32_bf16 v[14:17], v[146:149], v[212:215], v[14:17]
	v_mfma_f32_16x16x32_bf16 v[10:13], v[154:157], v[212:215], v[10:13]
	v_mfma_f32_16x16x32_bf16 v[62:65], v[150:153], v[182:185], v[62:65]
	v_mfma_f32_16x16x32_bf16 v[58:61], v[158:161], v[182:185], v[58:61]
	v_mfma_f32_16x16x32_bf16 v[46:49], v[150:153], v[190:193], v[46:49]
	v_mfma_f32_16x16x32_bf16 v[42:45], v[158:161], v[190:193], v[42:45]
	v_mfma_f32_16x16x32_bf16 v[30:33], v[150:153], v[208:211], v[30:33]
	v_mfma_f32_16x16x32_bf16 v[26:29], v[158:161], v[208:211], v[26:29]
	v_mfma_f32_16x16x32_bf16 v[14:17], v[150:153], v[216:219], v[14:17]
	v_mfma_f32_16x16x32_bf16 v[10:13], v[158:161], v[216:219], v[10:13]
	s_setprio 0
	s_setprio 1
	v_mfma_f32_16x16x32_bf16 v[54:57], v[162:165], v[178:181], v[54:57]
	v_mfma_f32_16x16x32_bf16 v[50:53], v[170:173], v[178:181], v[50:53]
	v_mfma_f32_16x16x32_bf16 v[38:41], v[162:165], v[186:189], v[38:41]
	v_mfma_f32_16x16x32_bf16 v[34:37], v[170:173], v[186:189], v[34:37]
	v_mfma_f32_16x16x32_bf16 v[22:25], v[162:165], v[204:207], v[22:25]
	v_mfma_f32_16x16x32_bf16 v[18:21], v[170:173], v[204:207], v[18:21]
	v_mfma_f32_16x16x32_bf16 v[6:9], v[162:165], v[212:215], v[6:9]
	v_mfma_f32_16x16x32_bf16 v[2:5], v[170:173], v[212:215], v[2:5]
	v_mfma_f32_16x16x32_bf16 v[54:57], v[166:169], v[182:185], v[54:57]
	v_mfma_f32_16x16x32_bf16 v[50:53], v[174:177], v[182:185], v[50:53]
	v_mfma_f32_16x16x32_bf16 v[38:41], v[166:169], v[190:193], v[38:41]
	v_mfma_f32_16x16x32_bf16 v[34:37], v[174:177], v[190:193], v[34:37]
	v_mfma_f32_16x16x32_bf16 v[22:25], v[166:169], v[208:211], v[22:25]
	v_mfma_f32_16x16x32_bf16 v[18:21], v[174:177], v[208:211], v[18:21]
	v_mfma_f32_16x16x32_bf16 v[6:9], v[166:169], v[216:219], v[6:9]
	v_mfma_f32_16x16x32_bf16 v[2:5], v[174:177], v[216:219], v[2:5]
	s_add_i32 s41, s41, 2
	s_add_u32 s39, s39, 0x100
	s_addc_u32 s40, s40, 0
	s_add_u32 s58, s58, 0x100
	s_addc_u32 s59, s59, 0
	s_cmp_gt_u32 s41, 13
	s_cbranch_scc1 .Lrot_exit_647
	s_add_u32 s20, s58, 0xfffc0080
	s_addc_u32 s21, s59, -1
	s_add_i32 s42, 0, 0x10000
	s_cmp_eq_u32 s41, 12
	s_cselect_b32 s61, s9, s21
	s_cselect_b32 s60, s37, s20
	v_add_u32_e32 v140, s42, v143
	s_cselect_b32 s21, s7, s40
	s_cselect_b32 s20, s38, s39
	s_add_i32 s44, 0, 0x14000
	s_setprio 0
	s_barrier
	s_branch .Lrot_647
